# extra priority flips every 8 MFMAs inside GEMM MFMA blocks (on top of previous)
# baseline (speedup 1.0000x reference)
.LBB0_757:
	s_ashr_i32 s17, s16, 31
	s_lshl_b64 s[18:19], s[16:17], 20
	s_add_u32 s18, s35, s18
	s_addc_u32 s19, s40, s19
	s_and_b64 s[20:21], s[4:5], exec
	s_cselect_b32 s17, s19, s29
	s_cselect_b32 s23, s18, s28
	s_ashr_i32 s15, s14, 31
	s_lshl_b64 s[20:21], s[14:15], 19
	s_add_u32 s20, s38, s20
	s_addc_u32 s21, s39, s21
	s_and_b64 s[30:31], s[4:5], exec
	s_cselect_b32 s15, s21, s27
	s_cselect_b32 s25, s20, s26
	s_add_u32 s52, s26, 0x100
	s_addc_u32 s53, s27, 0
	s_add_u32 s26, s28, 0x80080
	s_addc_u32 s27, s29, 0
	s_mov_b32 s54, -2
	s_waitcnt lgkmcnt(0)
	s_add_u32 s28, s26, 0xfff80080
	s_addc_u32 s29, s27, -1
	s_add_i32 s55, 0, 0x10000
	s_cmp_eq_u32 s54, 12
	s_cselect_b32 s31, s17, s29
	s_cselect_b32 s30, s23, s28
	s_cselect_b32 s29, s15, s53
	s_cselect_b32 s28, s25, s52
	s_add_i32 s58, 0, 0x14000
	v_add_u32_e32 v156, s55, v145
	v_add_u32_e32 v172, s58, v145
	ds_read_b128 v[140:143], v156
	ds_read_b128 v[148:151], v156 offset:1024
	ds_read_b128 v[152:155], v156 offset:2048
	ds_read_b128 v[156:159], v156 offset:3072
	ds_read_b128 v[160:163], v172
	ds_read_b128 v[164:167], v172 offset:1024
	ds_read_b128 v[168:171], v172 offset:2048
	ds_read_b128 v[172:175], v172 offset:3072
	s_add_i32 m0, s42, 0xc000
	ds_read_b128 v[176:179], v147
	ds_read_b128 v[180:183], v147 offset:1024
	ds_read_b128 v[184:187], v147 offset:2048
	ds_read_b128 v[208:211], v147 offset:3072
	ds_read_b128 v[230:233], v147 offset:4096
	ds_read_b128 v[234:237], v147 offset:5120
	ds_read_b128 v[238:241], v147 offset:6144
	ds_read_b128 v[242:245], v147 offset:7168
	global_load_lds_dwordx4 v138, s[26:27]
	s_add_i32 m0, s42, 0xe000
	s_nop 0
	global_load_lds_dwordx4 v136, s[26:27]
	s_waitcnt vmcnt(8)
	s_waitcnt lgkmcnt(0)
	s_barrier
	s_setprio 1
	s_waitcnt lgkmcnt(0)
	v_mfma_f32_16x16x32_bf16 v[126:129], v[140:143], v[176:179], 0
	v_mfma_f32_16x16x32_bf16 v[122:125], v[152:155], v[176:179], 0
	v_mfma_f32_16x16x32_bf16 v[108:111], v[140:143], v[184:187], 0
	v_mfma_f32_16x16x32_bf16 v[104:107], v[152:155], v[184:187], 0
	v_mfma_f32_16x16x32_bf16 v[92:95], v[140:143], v[230:233], 0
	v_mfma_f32_16x16x32_bf16 v[88:91], v[152:155], v[230:233], 0
	v_mfma_f32_16x16x32_bf16 v[76:79], v[140:143], v[238:241], 0
	v_mfma_f32_16x16x32_bf16 v[72:75], v[152:155], v[238:241], 0
	s_setprio 0
	s_setprio 1
	v_mfma_f32_16x16x32_bf16 v[126:129], v[148:151], v[180:183], v[126:129]
	v_mfma_f32_16x16x32_bf16 v[122:125], v[156:159], v[180:183], v[122:125]
	v_mfma_f32_16x16x32_bf16 v[108:111], v[148:151], v[208:211], v[108:111]
	v_mfma_f32_16x16x32_bf16 v[104:107], v[156:159], v[208:211], v[104:107]
	v_mfma_f32_16x16x32_bf16 v[92:95], v[148:151], v[234:237], v[92:95]
	v_mfma_f32_16x16x32_bf16 v[88:91], v[156:159], v[234:237], v[88:91]
	v_mfma_f32_16x16x32_bf16 v[76:79], v[148:151], v[242:245], v[76:79]
	v_mfma_f32_16x16x32_bf16 v[72:75], v[156:159], v[242:245], v[72:75]
	s_setprio 0
	s_setprio 1
	v_mfma_f32_16x16x32_bf16 v[118:121], v[160:163], v[176:179], 0
	v_mfma_f32_16x16x32_bf16 v[114:117], v[168:171], v[176:179], 0
	v_mfma_f32_16x16x32_bf16 v[100:103], v[160:163], v[184:187], 0
	v_mfma_f32_16x16x32_bf16 v[96:99], v[168:171], v[184:187], 0
	v_mfma_f32_16x16x32_bf16 v[84:87], v[160:163], v[230:233], 0
	v_mfma_f32_16x16x32_bf16 v[80:83], v[168:171], v[230:233], 0
	v_mfma_f32_16x16x32_bf16 v[68:71], v[160:163], v[238:241], 0
	v_mfma_f32_16x16x32_bf16 v[64:67], v[168:171], v[238:241], 0
	s_setprio 0
	s_setprio 1
	v_mfma_f32_16x16x32_bf16 v[118:121], v[164:167], v[180:183], v[118:121]
	v_mfma_f32_16x16x32_bf16 v[114:117], v[172:175], v[180:183], v[114:117]
	v_mfma_f32_16x16x32_bf16 v[100:103], v[164:167], v[208:211], v[100:103]
	v_mfma_f32_16x16x32_bf16 v[96:99], v[172:175], v[208:211], v[96:99]
	v_mfma_f32_16x16x32_bf16 v[84:87], v[164:167], v[234:237], v[84:87]
	v_mfma_f32_16x16x32_bf16 v[80:83], v[172:175], v[234:237], v[80:83]
	v_mfma_f32_16x16x32_bf16 v[68:71], v[164:167], v[242:245], v[68:71]
	v_mfma_f32_16x16x32_bf16 v[64:67], v[172:175], v[242:245], v[64:67]
	s_setprio 0
	s_barrier
	s_add_i32 s55, s55, s41
	s_mov_b32 m0, s55
	ds_read_b128 v[176:179], v147 offset:16384
	ds_read_b128 v[180:183], v147 offset:17408
	ds_read_b128 v[184:187], v147 offset:18432
	ds_read_b128 v[208:211], v147 offset:19456
	ds_read_b128 v[230:233], v147 offset:20480
	ds_read_b128 v[234:237], v147 offset:21504
	ds_read_b128 v[238:241], v147 offset:22528
	ds_read_b128 v[242:245], v147 offset:23552
	global_load_lds_dwordx4 v112, s[28:29]
	s_add_i32 m0, s55, 0x2000
	s_add_u32 s56, s28, 0x40000
	v_lshl_add_u64 v[212:213], s[28:29], 0, v[134:135]
	s_addc_u32 s57, s29, 0
	s_add_i32 s55, s58, s41
	global_load_lds_dwordx4 v134, s[28:29]
	s_mov_b32 m0, s55
	v_lshl_add_u64 v[246:247], s[30:31], 0, v[132:133]
	global_load_lds_dwordx4 v112, s[56:57]
	s_add_i32 m0, s55, 0x2000
	s_nop 0
	global_load_lds_dwordx4 v134, s[56:57]
	v_lshl_add_u64 v[228:229], s[30:31], 0, v[130:131]
	s_mov_b32 m0, s42
	s_nop 0
	global_load_lds_dwordx4 v130, s[30:31]
	s_mov_b32 m0, s43
	s_nop 0
	global_load_lds_dwordx4 v132, s[30:31]
	s_waitcnt vmcnt(8)
	s_waitcnt lgkmcnt(0)
	s_barrier
	s_setprio 1
	s_waitcnt lgkmcnt(0)
	v_mfma_f32_16x16x32_bf16 v[60:63], v[140:143], v[176:179], 0
	v_mfma_f32_16x16x32_bf16 v[56:59], v[152:155], v[176:179], 0
	v_mfma_f32_16x16x32_bf16 v[44:47], v[140:143], v[184:187], 0
	v_mfma_f32_16x16x32_bf16 v[40:43], v[152:155], v[184:187], 0
	v_mfma_f32_16x16x32_bf16 v[28:31], v[140:143], v[230:233], 0
	v_mfma_f32_16x16x32_bf16 v[24:27], v[152:155], v[230:233], 0
	v_mfma_f32_16x16x32_bf16 v[12:15], v[140:143], v[238:241], 0
	v_mfma_f32_16x16x32_bf16 v[8:11], v[152:155], v[238:241], 0
	s_setprio 0
	s_setprio 1
	v_mfma_f32_16x16x32_bf16 v[60:63], v[148:151], v[180:183], v[60:63]
	v_mfma_f32_16x16x32_bf16 v[56:59], v[156:159], v[180:183], v[56:59]
	v_mfma_f32_16x16x32_bf16 v[44:47], v[148:151], v[208:211], v[44:47]
	v_mfma_f32_16x16x32_bf16 v[40:43], v[156:159], v[208:211], v[40:43]
	v_mfma_f32_16x16x32_bf16 v[28:31], v[148:151], v[234:237], v[28:31]
	v_mfma_f32_16x16x32_bf16 v[24:27], v[156:159], v[234:237], v[24:27]
	v_mfma_f32_16x16x32_bf16 v[12:15], v[148:151], v[242:245], v[12:15]
	v_mfma_f32_16x16x32_bf16 v[8:11], v[156:159], v[242:245], v[8:11]
	s_setprio 0
	s_setprio 1
	v_mfma_f32_16x16x32_bf16 v[52:55], v[160:163], v[176:179], 0
	v_mfma_f32_16x16x32_bf16 v[48:51], v[168:171], v[176:179], 0
	v_mfma_f32_16x16x32_bf16 v[36:39], v[160:163], v[184:187], 0
	v_mfma_f32_16x16x32_bf16 v[32:35], v[168:171], v[184:187], 0
	v_mfma_f32_16x16x32_bf16 v[20:23], v[160:163], v[230:233], 0
	v_mfma_f32_16x16x32_bf16 v[16:19], v[168:171], v[230:233], 0
	v_mfma_f32_16x16x32_bf16 v[4:7], v[160:163], v[238:241], 0
	v_mfma_f32_16x16x32_bf16 v[0:3], v[168:171], v[238:241], 0
	s_setprio 0
	s_setprio 1
	v_mfma_f32_16x16x32_bf16 v[52:55], v[164:167], v[180:183], v[52:55]
	v_mfma_f32_16x16x32_bf16 v[48:51], v[172:175], v[180:183], v[48:51]
	v_mfma_f32_16x16x32_bf16 v[36:39], v[164:167], v[208:211], v[36:39]
	v_mfma_f32_16x16x32_bf16 v[32:35], v[172:175], v[208:211], v[32:35]
	v_mfma_f32_16x16x32_bf16 v[20:23], v[164:167], v[234:237], v[20:23]
	v_mfma_f32_16x16x32_bf16 v[16:19], v[172:175], v[234:237], v[16:19]
	v_mfma_f32_16x16x32_bf16 v[4:7], v[164:167], v[242:245], v[4:7]
	v_mfma_f32_16x16x32_bf16 v[0:3], v[172:175], v[242:245], v[0:3]
	s_setprio 0
	s_barrier
	s_add_i32 s55, 0, 0x18000
	s_add_i32 s56, 0, 0x1c000
	v_add_u32_e32 v156, s55, v145
	v_add_u32_e32 v172, s56, v145
	ds_read_b128 v[140:143], v156
	ds_read_b128 v[148:151], v156 offset:1024
	ds_read_b128 v[152:155], v156 offset:2048
	ds_read_b128 v[156:159], v156 offset:3072
	ds_read_b128 v[160:163], v172
	ds_read_b128 v[164:167], v172 offset:1024
	ds_read_b128 v[168:171], v172 offset:2048
	ds_read_b128 v[172:175], v172 offset:3072
	s_add_u32 s30, s30, 0x80000
	s_addc_u32 s31, s31, 0
	s_mov_b32 m0, s44
	ds_read_b128 v[176:179], v147 offset:32768
	ds_read_b128 v[180:183], v147 offset:33792
	ds_read_b128 v[184:187], v147 offset:34816
	ds_read_b128 v[208:211], v147 offset:35840
	ds_read_b128 v[230:233], v147 offset:36864
	ds_read_b128 v[234:237], v147 offset:37888
	ds_read_b128 v[238:241], v147 offset:38912
	ds_read_b128 v[242:245], v147 offset:39936
	global_load_lds_dwordx4 v130, s[30:31]
	s_mov_b32 m0, s45
	s_nop 0
	global_load_lds_dwordx4 v132, s[30:31]
	s_waitcnt vmcnt(8)
	s_waitcnt lgkmcnt(0)
	s_barrier
	s_setprio 1
	s_waitcnt lgkmcnt(0)
	v_mfma_f32_16x16x32_bf16 v[126:129], v[140:143], v[176:179], v[126:129]
	v_mfma_f32_16x16x32_bf16 v[122:125], v[152:155], v[176:179], v[122:125]
	v_mfma_f32_16x16x32_bf16 v[108:111], v[140:143], v[184:187], v[108:111]
	v_mfma_f32_16x16x32_bf16 v[104:107], v[152:155], v[184:187], v[104:107]
	v_mfma_f32_16x16x32_bf16 v[92:95], v[140:143], v[230:233], v[92:95]
	v_mfma_f32_16x16x32_bf16 v[88:91], v[152:155], v[230:233], v[88:91]
	v_mfma_f32_16x16x32_bf16 v[76:79], v[140:143], v[238:241], v[76:79]
	v_mfma_f32_16x16x32_bf16 v[72:75], v[152:155], v[238:241], v[72:75]
	s_setprio 0
	s_setprio 1
	v_mfma_f32_16x16x32_bf16 v[126:129], v[148:151], v[180:183], v[126:129]
	v_mfma_f32_16x16x32_bf16 v[122:125], v[156:159], v[180:183], v[122:125]
	v_mfma_f32_16x16x32_bf16 v[108:111], v[148:151], v[208:211], v[108:111]
	v_mfma_f32_16x16x32_bf16 v[104:107], v[156:159], v[208:211], v[104:107]
	v_mfma_f32_16x16x32_bf16 v[92:95], v[148:151], v[234:237], v[92:95]
	v_mfma_f32_16x16x32_bf16 v[88:91], v[156:159], v[234:237], v[88:91]
	v_mfma_f32_16x16x32_bf16 v[76:79], v[148:151], v[242:245], v[76:79]
	v_mfma_f32_16x16x32_bf16 v[72:75], v[156:159], v[242:245], v[72:75]
	s_setprio 0
	s_setprio 1
	v_mfma_f32_16x16x32_bf16 v[118:121], v[160:163], v[176:179], v[118:121]
	v_mfma_f32_16x16x32_bf16 v[114:117], v[168:171], v[176:179], v[114:117]
	v_mfma_f32_16x16x32_bf16 v[100:103], v[160:163], v[184:187], v[100:103]
	v_mfma_f32_16x16x32_bf16 v[96:99], v[168:171], v[184:187], v[96:99]
	v_mfma_f32_16x16x32_bf16 v[84:87], v[160:163], v[230:233], v[84:87]
	v_mfma_f32_16x16x32_bf16 v[80:83], v[168:171], v[230:233], v[80:83]
	v_mfma_f32_16x16x32_bf16 v[68:71], v[160:163], v[238:241], v[68:71]
	v_mfma_f32_16x16x32_bf16 v[64:67], v[168:171], v[238:241], v[64:67]
	s_setprio 0
	s_setprio 1
	v_mfma_f32_16x16x32_bf16 v[118:121], v[164:167], v[180:183], v[118:121]
	v_mfma_f32_16x16x32_bf16 v[114:117], v[172:175], v[180:183], v[114:117]
	v_mfma_f32_16x16x32_bf16 v[100:103], v[164:167], v[208:211], v[100:103]
	v_mfma_f32_16x16x32_bf16 v[96:99], v[172:175], v[208:211], v[96:99]
	v_mfma_f32_16x16x32_bf16 v[84:87], v[164:167], v[234:237], v[84:87]
	v_mfma_f32_16x16x32_bf16 v[80:83], v[172:175], v[234:237], v[80:83]
	v_mfma_f32_16x16x32_bf16 v[68:71], v[164:167], v[242:245], v[68:71]
	v_mfma_f32_16x16x32_bf16 v[64:67], v[172:175], v[242:245], v[64:67]
	s_setprio 0
	s_barrier
	s_add_i32 s30, s55, s41
	s_mov_b32 m0, s30
	ds_read_b128 v[176:179], v147 offset:49152
	ds_read_b128 v[180:183], v147 offset:50176
	ds_read_b128 v[184:187], v147 offset:51200
	ds_read_b128 v[208:211], v147 offset:52224
	ds_read_b128 v[230:233], v147 offset:53248
	ds_read_b128 v[234:237], v147 offset:54272
	ds_read_b128 v[238:241], v147 offset:55296
	ds_read_b128 v[242:245], v147 offset:56320
	s_add_u32 s98, s28, 0x80
	s_addc_u32 s99, s29, 0
	global_load_lds_dwordx4 v112, s[98:99]
	s_add_i32 m0, s30, 0x2000
	s_add_u32 s28, s28, 0x40080
	v_lshl_add_u64 v[188:189], v[212:213], 0, s[96:97]
	s_addc_u32 s29, s29, 0
	s_add_i32 s30, s56, s41
	global_load_lds_dwordx4 v[188:189], off
	s_mov_b32 m0, s30
	s_nop 0
	global_load_lds_dwordx4 v112, s[28:29]
	s_add_i32 m0, s30, 0x2000
	s_nop 0
	global_load_lds_dwordx4 v134, s[28:29]
	v_lshl_add_u64 v[188:189], v[228:229], 0, s[96:97]
	s_mov_b32 m0, s47
	s_nop 0
	global_load_lds_dwordx4 v[188:189], off
	v_lshl_add_u64 v[188:189], v[246:247], 0, s[96:97]
	s_mov_b32 m0, s48
	s_nop 0
	global_load_lds_dwordx4 v[188:189], off
	s_waitcnt vmcnt(8)
	s_waitcnt lgkmcnt(0)
	s_barrier
	s_setprio 1
	s_waitcnt lgkmcnt(0)
	v_mfma_f32_16x16x32_bf16 v[60:63], v[140:143], v[176:179], v[60:63]
	v_mfma_f32_16x16x32_bf16 v[56:59], v[152:155], v[176:179], v[56:59]
	v_mfma_f32_16x16x32_bf16 v[44:47], v[140:143], v[184:187], v[44:47]
	v_mfma_f32_16x16x32_bf16 v[40:43], v[152:155], v[184:187], v[40:43]
	v_mfma_f32_16x16x32_bf16 v[28:31], v[140:143], v[230:233], v[28:31]
	v_mfma_f32_16x16x32_bf16 v[24:27], v[152:155], v[230:233], v[24:27]
	v_mfma_f32_16x16x32_bf16 v[12:15], v[140:143], v[238:241], v[12:15]
	v_mfma_f32_16x16x32_bf16 v[8:11], v[152:155], v[238:241], v[8:11]
	s_setprio 0
	s_setprio 1
	v_mfma_f32_16x16x32_bf16 v[60:63], v[148:151], v[180:183], v[60:63]
	v_mfma_f32_16x16x32_bf16 v[56:59], v[156:159], v[180:183], v[56:59]
	v_mfma_f32_16x16x32_bf16 v[44:47], v[148:151], v[208:211], v[44:47]
	v_mfma_f32_16x16x32_bf16 v[40:43], v[156:159], v[208:211], v[40:43]
	v_mfma_f32_16x16x32_bf16 v[28:31], v[148:151], v[234:237], v[28:31]
	v_mfma_f32_16x16x32_bf16 v[24:27], v[156:159], v[234:237], v[24:27]
	v_mfma_f32_16x16x32_bf16 v[12:15], v[148:151], v[242:245], v[12:15]
	v_mfma_f32_16x16x32_bf16 v[8:11], v[156:159], v[242:245], v[8:11]
	s_setprio 0
	s_setprio 1
	v_mfma_f32_16x16x32_bf16 v[52:55], v[160:163], v[176:179], v[52:55]
	v_mfma_f32_16x16x32_bf16 v[48:51], v[168:171], v[176:179], v[48:51]
	v_mfma_f32_16x16x32_bf16 v[36:39], v[160:163], v[184:187], v[36:39]
	v_mfma_f32_16x16x32_bf16 v[32:35], v[168:171], v[184:187], v[32:35]
	v_mfma_f32_16x16x32_bf16 v[20:23], v[160:163], v[230:233], v[20:23]
	v_mfma_f32_16x16x32_bf16 v[16:19], v[168:171], v[230:233], v[16:19]
	v_mfma_f32_16x16x32_bf16 v[4:7], v[160:163], v[238:241], v[4:7]
	v_mfma_f32_16x16x32_bf16 v[0:3], v[168:171], v[238:241], v[0:3]
	s_setprio 0
	s_setprio 1
	v_mfma_f32_16x16x32_bf16 v[52:55], v[164:167], v[180:183], v[52:55]
	v_mfma_f32_16x16x32_bf16 v[48:51], v[172:175], v[180:183], v[48:51]
	v_mfma_f32_16x16x32_bf16 v[36:39], v[164:167], v[208:211], v[36:39]
	v_mfma_f32_16x16x32_bf16 v[32:35], v[172:175], v[208:211], v[32:35]
	v_mfma_f32_16x16x32_bf16 v[20:23], v[164:167], v[234:237], v[20:23]
	v_mfma_f32_16x16x32_bf16 v[16:19], v[172:175], v[234:237], v[16:19]
	v_mfma_f32_16x16x32_bf16 v[4:7], v[164:167], v[242:245], v[4:7]
	v_mfma_f32_16x16x32_bf16 v[0:3], v[172:175], v[242:245], v[0:3]
	s_setprio 0
	s_barrier
	s_add_i32 s54, s54, 2
	s_add_u32 s52, s52, 0x100
	s_addc_u32 s53, s53, 0
	s_add_u32 s26, s26, 0x100
	s_addc_u32 s27, s27, 0
	s_cmp_gt_u32 s54, 13
	s_cbranch_scc0 .LBB0_758
	s_branch .Lpeel_exit_758
.LBB0_758:
	s_add_u32 s28, s26, 0xfff80080
	s_addc_u32 s29, s27, -1
	s_add_i32 s55, 0, 0x10000
	s_cmp_eq_u32 s54, 12
	s_cselect_b32 s31, s17, s29
	s_cselect_b32 s30, s23, s28
	s_cselect_b32 s29, s15, s53
	s_cselect_b32 s28, s25, s52
	s_add_i32 s58, 0, 0x14000
	v_add_u32_e32 v156, s55, v145
	v_add_u32_e32 v172, s58, v145
	ds_read_b128 v[140:143], v156
	ds_read_b128 v[148:151], v156 offset:1024
	ds_read_b128 v[152:155], v156 offset:2048
	ds_read_b128 v[156:159], v156 offset:3072
	ds_read_b128 v[160:163], v172
	ds_read_b128 v[164:167], v172 offset:1024
	ds_read_b128 v[168:171], v172 offset:2048
	ds_read_b128 v[172:175], v172 offset:3072
	s_add_i32 m0, s42, 0xc000
	ds_read_b128 v[176:179], v147
	ds_read_b128 v[180:183], v147 offset:1024
	ds_read_b128 v[184:187], v147 offset:2048
	ds_read_b128 v[208:211], v147 offset:3072
	ds_read_b128 v[230:233], v147 offset:4096
	ds_read_b128 v[234:237], v147 offset:5120
	ds_read_b128 v[238:241], v147 offset:6144
	ds_read_b128 v[242:245], v147 offset:7168
	global_load_lds_dwordx4 v138, s[26:27]
	s_add_i32 m0, s42, 0xe000
	s_nop 0
	global_load_lds_dwordx4 v136, s[26:27]
	s_waitcnt vmcnt(8)
	s_waitcnt lgkmcnt(0)
	s_barrier
	s_setprio 1
	s_waitcnt lgkmcnt(0)
	v_mfma_f32_16x16x32_bf16 v[126:129], v[140:143], v[176:179], v[126:129]
	v_mfma_f32_16x16x32_bf16 v[122:125], v[152:155], v[176:179], v[122:125]
	v_mfma_f32_16x16x32_bf16 v[108:111], v[140:143], v[184:187], v[108:111]
	v_mfma_f32_16x16x32_bf16 v[104:107], v[152:155], v[184:187], v[104:107]
	v_mfma_f32_16x16x32_bf16 v[92:95], v[140:143], v[230:233], v[92:95]
	v_mfma_f32_16x16x32_bf16 v[88:91], v[152:155], v[230:233], v[88:91]
	v_mfma_f32_16x16x32_bf16 v[76:79], v[140:143], v[238:241], v[76:79]
	v_mfma_f32_16x16x32_bf16 v[72:75], v[152:155], v[238:241], v[72:75]
	s_setprio 0
	s_setprio 1
	v_mfma_f32_16x16x32_bf16 v[126:129], v[148:151], v[180:183], v[126:129]
	v_mfma_f32_16x16x32_bf16 v[122:125], v[156:159], v[180:183], v[122:125]
	v_mfma_f32_16x16x32_bf16 v[108:111], v[148:151], v[208:211], v[108:111]
	v_mfma_f32_16x16x32_bf16 v[104:107], v[156:159], v[208:211], v[104:107]
	v_mfma_f32_16x16x32_bf16 v[92:95], v[148:151], v[234:237], v[92:95]
	v_mfma_f32_16x16x32_bf16 v[88:91], v[156:159], v[234:237], v[88:91]
	v_mfma_f32_16x16x32_bf16 v[76:79], v[148:151], v[242:245], v[76:79]
	v_mfma_f32_16x16x32_bf16 v[72:75], v[156:159], v[242:245], v[72:75]
	s_setprio 0
	s_setprio 1
	v_mfma_f32_16x16x32_bf16 v[118:121], v[160:163], v[176:179], v[118:121]
	v_mfma_f32_16x16x32_bf16 v[114:117], v[168:171], v[176:179], v[114:117]
	v_mfma_f32_16x16x32_bf16 v[100:103], v[160:163], v[184:187], v[100:103]
	v_mfma_f32_16x16x32_bf16 v[96:99], v[168:171], v[184:187], v[96:99]
	v_mfma_f32_16x16x32_bf16 v[84:87], v[160:163], v[230:233], v[84:87]
	v_mfma_f32_16x16x32_bf16 v[80:83], v[168:171], v[230:233], v[80:83]
	v_mfma_f32_16x16x32_bf16 v[68:71], v[160:163], v[238:241], v[68:71]
	v_mfma_f32_16x16x32_bf16 v[64:67], v[168:171], v[238:241], v[64:67]
	s_setprio 0
	s_setprio 1
	v_mfma_f32_16x16x32_bf16 v[118:121], v[164:167], v[180:183], v[118:121]
	v_mfma_f32_16x16x32_bf16 v[114:117], v[172:175], v[180:183], v[114:117]
	v_mfma_f32_16x16x32_bf16 v[100:103], v[164:167], v[208:211], v[100:103]
	v_mfma_f32_16x16x32_bf16 v[96:99], v[172:175], v[208:211], v[96:99]
	v_mfma_f32_16x16x32_bf16 v[84:87], v[164:167], v[234:237], v[84:87]
	v_mfma_f32_16x16x32_bf16 v[80:83], v[172:175], v[234:237], v[80:83]
	v_mfma_f32_16x16x32_bf16 v[68:71], v[164:167], v[242:245], v[68:71]
	v_mfma_f32_16x16x32_bf16 v[64:67], v[172:175], v[242:245], v[64:67]
	s_setprio 0
	s_barrier
	s_add_i32 s55, s55, s41
	s_mov_b32 m0, s55
	ds_read_b128 v[176:179], v147 offset:16384
	ds_read_b128 v[180:183], v147 offset:17408
	ds_read_b128 v[184:187], v147 offset:18432
	ds_read_b128 v[208:211], v147 offset:19456
	ds_read_b128 v[230:233], v147 offset:20480
	ds_read_b128 v[234:237], v147 offset:21504
	ds_read_b128 v[238:241], v147 offset:22528
	ds_read_b128 v[242:245], v147 offset:23552
	global_load_lds_dwordx4 v112, s[28:29]
	s_add_i32 m0, s55, 0x2000
	s_add_u32 s56, s28, 0x40000
	v_lshl_add_u64 v[212:213], s[28:29], 0, v[134:135]
	s_addc_u32 s57, s29, 0
	s_add_i32 s55, s58, s41
	global_load_lds_dwordx4 v134, s[28:29]
	s_mov_b32 m0, s55
	v_lshl_add_u64 v[246:247], s[30:31], 0, v[132:133]
	global_load_lds_dwordx4 v112, s[56:57]
	s_add_i32 m0, s55, 0x2000
	s_nop 0
	global_load_lds_dwordx4 v134, s[56:57]
	v_lshl_add_u64 v[228:229], s[30:31], 0, v[130:131]
	s_mov_b32 m0, s42
	s_nop 0
	global_load_lds_dwordx4 v130, s[30:31]
	s_mov_b32 m0, s43
	s_nop 0
	global_load_lds_dwordx4 v132, s[30:31]
	s_waitcnt vmcnt(8)
	s_waitcnt lgkmcnt(0)
	s_barrier
	s_setprio 1
	s_waitcnt lgkmcnt(0)
	v_mfma_f32_16x16x32_bf16 v[60:63], v[140:143], v[176:179], v[60:63]
	v_mfma_f32_16x16x32_bf16 v[56:59], v[152:155], v[176:179], v[56:59]
	v_mfma_f32_16x16x32_bf16 v[44:47], v[140:143], v[184:187], v[44:47]
	v_mfma_f32_16x16x32_bf16 v[40:43], v[152:155], v[184:187], v[40:43]
	v_mfma_f32_16x16x32_bf16 v[28:31], v[140:143], v[230:233], v[28:31]
	v_mfma_f32_16x16x32_bf16 v[24:27], v[152:155], v[230:233], v[24:27]
	v_mfma_f32_16x16x32_bf16 v[12:15], v[140:143], v[238:241], v[12:15]
	v_mfma_f32_16x16x32_bf16 v[8:11], v[152:155], v[238:241], v[8:11]
	s_setprio 0
	s_setprio 1
	v_mfma_f32_16x16x32_bf16 v[60:63], v[148:151], v[180:183], v[60:63]
	v_mfma_f32_16x16x32_bf16 v[56:59], v[156:159], v[180:183], v[56:59]
	v_mfma_f32_16x16x32_bf16 v[44:47], v[148:151], v[208:211], v[44:47]
	v_mfma_f32_16x16x32_bf16 v[40:43], v[156:159], v[208:211], v[40:43]
	v_mfma_f32_16x16x32_bf16 v[28:31], v[148:151], v[234:237], v[28:31]
	v_mfma_f32_16x16x32_bf16 v[24:27], v[156:159], v[234:237], v[24:27]
	v_mfma_f32_16x16x32_bf16 v[12:15], v[148:151], v[242:245], v[12:15]
	v_mfma_f32_16x16x32_bf16 v[8:11], v[156:159], v[242:245], v[8:11]
	s_setprio 0
	s_setprio 1
	v_mfma_f32_16x16x32_bf16 v[52:55], v[160:163], v[176:179], v[52:55]
	v_mfma_f32_16x16x32_bf16 v[48:51], v[168:171], v[176:179], v[48:51]
	v_mfma_f32_16x16x32_bf16 v[36:39], v[160:163], v[184:187], v[36:39]
	v_mfma_f32_16x16x32_bf16 v[32:35], v[168:171], v[184:187], v[32:35]
	v_mfma_f32_16x16x32_bf16 v[20:23], v[160:163], v[230:233], v[20:23]
	v_mfma_f32_16x16x32_bf16 v[16:19], v[168:171], v[230:233], v[16:19]
	v_mfma_f32_16x16x32_bf16 v[4:7], v[160:163], v[238:241], v[4:7]
	v_mfma_f32_16x16x32_bf16 v[0:3], v[168:171], v[238:241], v[0:3]
	s_setprio 0
	s_setprio 1
	v_mfma_f32_16x16x32_bf16 v[52:55], v[164:167], v[180:183], v[52:55]
	v_mfma_f32_16x16x32_bf16 v[48:51], v[172:175], v[180:183], v[48:51]
	v_mfma_f32_16x16x32_bf16 v[36:39], v[164:167], v[208:211], v[36:39]
	v_mfma_f32_16x16x32_bf16 v[32:35], v[172:175], v[208:211], v[32:35]
	v_mfma_f32_16x16x32_bf16 v[20:23], v[164:167], v[234:237], v[20:23]
	v_mfma_f32_16x16x32_bf16 v[16:19], v[172:175], v[234:237], v[16:19]
	v_mfma_f32_16x16x32_bf16 v[4:7], v[164:167], v[242:245], v[4:7]
	v_mfma_f32_16x16x32_bf16 v[0:3], v[172:175], v[242:245], v[0:3]
	s_setprio 0
	s_barrier
	s_add_i32 s55, 0, 0x18000
	s_add_i32 s56, 0, 0x1c000
	v_add_u32_e32 v156, s55, v145
	v_add_u32_e32 v172, s56, v145
	ds_read_b128 v[140:143], v156
	ds_read_b128 v[148:151], v156 offset:1024
	ds_read_b128 v[152:155], v156 offset:2048
	ds_read_b128 v[156:159], v156 offset:3072
	ds_read_b128 v[160:163], v172
	ds_read_b128 v[164:167], v172 offset:1024
	ds_read_b128 v[168:171], v172 offset:2048
	ds_read_b128 v[172:175], v172 offset:3072
	s_add_u32 s30, s30, 0x80000
	s_addc_u32 s31, s31, 0
	s_mov_b32 m0, s44
	ds_read_b128 v[176:179], v147 offset:32768
	ds_read_b128 v[180:183], v147 offset:33792
	ds_read_b128 v[184:187], v147 offset:34816
	ds_read_b128 v[208:211], v147 offset:35840
	ds_read_b128 v[230:233], v147 offset:36864
	ds_read_b128 v[234:237], v147 offset:37888
	ds_read_b128 v[238:241], v147 offset:38912
	ds_read_b128 v[242:245], v147 offset:39936
	global_load_lds_dwordx4 v130, s[30:31]
	s_mov_b32 m0, s45
	s_nop 0
	global_load_lds_dwordx4 v132, s[30:31]
	s_waitcnt vmcnt(8)
	s_waitcnt lgkmcnt(0)
	s_barrier
	s_setprio 1
	s_waitcnt lgkmcnt(0)
	v_mfma_f32_16x16x32_bf16 v[126:129], v[140:143], v[176:179], v[126:129]
	v_mfma_f32_16x16x32_bf16 v[122:125], v[152:155], v[176:179], v[122:125]
	v_mfma_f32_16x16x32_bf16 v[108:111], v[140:143], v[184:187], v[108:111]
	v_mfma_f32_16x16x32_bf16 v[104:107], v[152:155], v[184:187], v[104:107]
	v_mfma_f32_16x16x32_bf16 v[92:95], v[140:143], v[230:233], v[92:95]
	v_mfma_f32_16x16x32_bf16 v[88:91], v[152:155], v[230:233], v[88:91]
	v_mfma_f32_16x16x32_bf16 v[76:79], v[140:143], v[238:241], v[76:79]
	v_mfma_f32_16x16x32_bf16 v[72:75], v[152:155], v[238:241], v[72:75]
	s_setprio 0
	s_setprio 1
	v_mfma_f32_16x16x32_bf16 v[126:129], v[148:151], v[180:183], v[126:129]
	v_mfma_f32_16x16x32_bf16 v[122:125], v[156:159], v[180:183], v[122:125]
	v_mfma_f32_16x16x32_bf16 v[108:111], v[148:151], v[208:211], v[108:111]
	v_mfma_f32_16x16x32_bf16 v[104:107], v[156:159], v[208:211], v[104:107]
	v_mfma_f32_16x16x32_bf16 v[92:95], v[148:151], v[234:237], v[92:95]
	v_mfma_f32_16x16x32_bf16 v[88:91], v[156:159], v[234:237], v[88:91]
	v_mfma_f32_16x16x32_bf16 v[76:79], v[148:151], v[242:245], v[76:79]
	v_mfma_f32_16x16x32_bf16 v[72:75], v[156:159], v[242:245], v[72:75]
	s_setprio 0
	s_setprio 1
	v_mfma_f32_16x16x32_bf16 v[118:121], v[160:163], v[176:179], v[118:121]
	v_mfma_f32_16x16x32_bf16 v[114:117], v[168:171], v[176:179], v[114:117]
	v_mfma_f32_16x16x32_bf16 v[100:103], v[160:163], v[184:187], v[100:103]
	v_mfma_f32_16x16x32_bf16 v[96:99], v[168:171], v[184:187], v[96:99]
	v_mfma_f32_16x16x32_bf16 v[84:87], v[160:163], v[230:233], v[84:87]
	v_mfma_f32_16x16x32_bf16 v[80:83], v[168:171], v[230:233], v[80:83]
	v_mfma_f32_16x16x32_bf16 v[68:71], v[160:163], v[238:241], v[68:71]
	v_mfma_f32_16x16x32_bf16 v[64:67], v[168:171], v[238:241], v[64:67]
	s_setprio 0
	s_setprio 1
	v_mfma_f32_16x16x32_bf16 v[118:121], v[164:167], v[180:183], v[118:121]
	v_mfma_f32_16x16x32_bf16 v[114:117], v[172:175], v[180:183], v[114:117]
	v_mfma_f32_16x16x32_bf16 v[100:103], v[164:167], v[208:211], v[100:103]
	v_mfma_f32_16x16x32_bf16 v[96:99], v[172:175], v[208:211], v[96:99]
	v_mfma_f32_16x16x32_bf16 v[84:87], v[164:167], v[234:237], v[84:87]
	v_mfma_f32_16x16x32_bf16 v[80:83], v[172:175], v[234:237], v[80:83]
	v_mfma_f32_16x16x32_bf16 v[68:71], v[164:167], v[242:245], v[68:71]
	v_mfma_f32_16x16x32_bf16 v[64:67], v[172:175], v[242:245], v[64:67]
	s_setprio 0
	s_barrier
	s_add_i32 s30, s55, s41
	s_mov_b32 m0, s30
	ds_read_b128 v[176:179], v147 offset:49152
	ds_read_b128 v[180:183], v147 offset:50176
	ds_read_b128 v[184:187], v147 offset:51200
	ds_read_b128 v[208:211], v147 offset:52224
	ds_read_b128 v[230:233], v147 offset:53248
	ds_read_b128 v[234:237], v147 offset:54272
	ds_read_b128 v[238:241], v147 offset:55296
	ds_read_b128 v[242:245], v147 offset:56320
	s_add_u32 s98, s28, 0x80
	s_addc_u32 s99, s29, 0
	global_load_lds_dwordx4 v112, s[98:99]
	s_add_i32 m0, s30, 0x2000
	s_add_u32 s28, s28, 0x40080
	v_lshl_add_u64 v[188:189], v[212:213], 0, s[96:97]
	s_addc_u32 s29, s29, 0
	s_add_i32 s30, s56, s41
	global_load_lds_dwordx4 v[188:189], off
	s_mov_b32 m0, s30
	s_nop 0
	global_load_lds_dwordx4 v112, s[28:29]
	s_add_i32 m0, s30, 0x2000
	s_nop 0
	global_load_lds_dwordx4 v134, s[28:29]
	v_lshl_add_u64 v[188:189], v[228:229], 0, s[96:97]
	s_mov_b32 m0, s47
	s_nop 0
	global_load_lds_dwordx4 v[188:189], off
	v_lshl_add_u64 v[188:189], v[246:247], 0, s[96:97]
	s_mov_b32 m0, s48
	s_nop 0
	global_load_lds_dwordx4 v[188:189], off
	s_waitcnt vmcnt(8)
	s_waitcnt lgkmcnt(0)
	s_barrier
	s_setprio 1
	s_waitcnt lgkmcnt(0)
	v_mfma_f32_16x16x32_bf16 v[60:63], v[140:143], v[176:179], v[60:63]
	v_mfma_f32_16x16x32_bf16 v[56:59], v[152:155], v[176:179], v[56:59]
	v_mfma_f32_16x16x32_bf16 v[44:47], v[140:143], v[184:187], v[44:47]
	v_mfma_f32_16x16x32_bf16 v[40:43], v[152:155], v[184:187], v[40:43]
	v_mfma_f32_16x16x32_bf16 v[28:31], v[140:143], v[230:233], v[28:31]
	v_mfma_f32_16x16x32_bf16 v[24:27], v[152:155], v[230:233], v[24:27]
	v_mfma_f32_16x16x32_bf16 v[12:15], v[140:143], v[238:241], v[12:15]
	v_mfma_f32_16x16x32_bf16 v[8:11], v[152:155], v[238:241], v[8:11]
	s_setprio 0
	s_setprio 1
	v_mfma_f32_16x16x32_bf16 v[60:63], v[148:151], v[180:183], v[60:63]
	v_mfma_f32_16x16x32_bf16 v[56:59], v[156:159], v[180:183], v[56:59]
	v_mfma_f32_16x16x32_bf16 v[44:47], v[148:151], v[208:211], v[44:47]
	v_mfma_f32_16x16x32_bf16 v[40:43], v[156:159], v[208:211], v[40:43]
	v_mfma_f32_16x16x32_bf16 v[28:31], v[148:151], v[234:237], v[28:31]
	v_mfma_f32_16x16x32_bf16 v[24:27], v[156:159], v[234:237], v[24:27]
	v_mfma_f32_16x16x32_bf16 v[12:15], v[148:151], v[242:245], v[12:15]
	v_mfma_f32_16x16x32_bf16 v[8:11], v[156:159], v[242:245], v[8:11]
	s_setprio 0
	s_setprio 1
	v_mfma_f32_16x16x32_bf16 v[52:55], v[160:163], v[176:179], v[52:55]
	v_mfma_f32_16x16x32_bf16 v[48:51], v[168:171], v[176:179], v[48:51]
	v_mfma_f32_16x16x32_bf16 v[36:39], v[160:163], v[184:187], v[36:39]
	v_mfma_f32_16x16x32_bf16 v[32:35], v[168:171], v[184:187], v[32:35]
	v_mfma_f32_16x16x32_bf16 v[20:23], v[160:163], v[230:233], v[20:23]
	v_mfma_f32_16x16x32_bf16 v[16:19], v[168:171], v[230:233], v[16:19]
	v_mfma_f32_16x16x32_bf16 v[4:7], v[160:163], v[238:241], v[4:7]
	v_mfma_f32_16x16x32_bf16 v[0:3], v[168:171], v[238:241], v[0:3]
	s_setprio 0
	s_setprio 1
	v_mfma_f32_16x16x32_bf16 v[52:55], v[164:167], v[180:183], v[52:55]
	v_mfma_f32_16x16x32_bf16 v[48:51], v[172:175], v[180:183], v[48:51]
	v_mfma_f32_16x16x32_bf16 v[36:39], v[164:167], v[208:211], v[36:39]
	v_mfma_f32_16x16x32_bf16 v[32:35], v[172:175], v[208:211], v[32:35]
	v_mfma_f32_16x16x32_bf16 v[20:23], v[164:167], v[234:237], v[20:23]
	v_mfma_f32_16x16x32_bf16 v[16:19], v[172:175], v[234:237], v[16:19]
	v_mfma_f32_16x16x32_bf16 v[4:7], v[164:167], v[242:245], v[4:7]
	v_mfma_f32_16x16x32_bf16 v[0:3], v[172:175], v[242:245], v[0:3]
	s_setprio 0
	s_barrier
	s_add_i32 s54, s54, 2
	s_add_u32 s52, s52, 0x100
	s_addc_u32 s53, s53, 0
	s_add_u32 s26, s26, 0x100
	s_addc_u32 s27, s27, 0
	s_cmp_gt_u32 s54, 13
	s_cbranch_scc0 .LBB0_758

.LBB0_803:
	s_ashr_i32 s15, s14, 31
	s_lshl_b64 s[18:19], s[14:15], 20
	s_add_u32 s18, s38, s18
	s_addc_u32 s19, s39, s19
	s_and_b64 s[0:1], s[0:1], exec
	s_cselect_b32 s15, s19, s25
	s_cselect_b32 s21, s18, s24
	s_add_u32 s50, s24, 0x100
	s_addc_u32 s51, s25, 0
	s_mov_b32 s52, -2
	s_waitcnt lgkmcnt(0)
	s_add_u32 s0, s22, 0x100
	s_addc_u32 s1, s23, 0
	s_add_i32 s53, 0, 0x10000
	s_cmp_eq_u32 s52, 28
	s_cselect_b32 s27, s17, s1
	s_cselect_b32 s26, s16, s0
	s_cselect_b32 s25, s15, s51
	s_cselect_b32 s24, s21, s50
	s_add_i32 s54, 0, 0x14000
	v_add_u32_e32 v156, s53, v145
	v_add_u32_e32 v172, s54, v145
	ds_read_b128 v[140:143], v156
	ds_read_b128 v[148:151], v156 offset:1024
	ds_read_b128 v[152:155], v156 offset:2048
	ds_read_b128 v[156:159], v156 offset:3072
	ds_read_b128 v[160:163], v172
	ds_read_b128 v[164:167], v172 offset:1024
	ds_read_b128 v[168:171], v172 offset:2048
	ds_read_b128 v[172:175], v172 offset:3072
	s_add_i32 m0, s31, 0xc000
	ds_read_b128 v[176:179], v147
	ds_read_b128 v[180:183], v147 offset:1024
	ds_read_b128 v[184:187], v147 offset:2048
	ds_read_b128 v[208:211], v147 offset:3072
	ds_read_b128 v[230:233], v147 offset:4096
	ds_read_b128 v[234:237], v147 offset:5120
	ds_read_b128 v[238:241], v147 offset:6144
	ds_read_b128 v[242:245], v147 offset:7168
	global_load_lds_dwordx4 v138, s[22:23]
	s_add_i32 m0, s31, 0xe000
	s_nop 0
	global_load_lds_dwordx4 v136, s[22:23]
	s_waitcnt vmcnt(8)
	s_waitcnt lgkmcnt(0)
	s_barrier
	s_setprio 1
	s_waitcnt lgkmcnt(0)
	v_mfma_f32_16x16x32_bf16 v[126:129], v[140:143], v[176:179], 0
	v_mfma_f32_16x16x32_bf16 v[122:125], v[152:155], v[176:179], 0
	v_mfma_f32_16x16x32_bf16 v[108:111], v[140:143], v[184:187], 0
	v_mfma_f32_16x16x32_bf16 v[104:107], v[152:155], v[184:187], 0
	v_mfma_f32_16x16x32_bf16 v[92:95], v[140:143], v[230:233], 0
	v_mfma_f32_16x16x32_bf16 v[88:91], v[152:155], v[230:233], 0
	v_mfma_f32_16x16x32_bf16 v[76:79], v[140:143], v[238:241], 0
	v_mfma_f32_16x16x32_bf16 v[72:75], v[152:155], v[238:241], 0
	s_setprio 0
	s_setprio 1
	v_mfma_f32_16x16x32_bf16 v[126:129], v[148:151], v[180:183], v[126:129]
	v_mfma_f32_16x16x32_bf16 v[122:125], v[156:159], v[180:183], v[122:125]
	v_mfma_f32_16x16x32_bf16 v[108:111], v[148:151], v[208:211], v[108:111]
	v_mfma_f32_16x16x32_bf16 v[104:107], v[156:159], v[208:211], v[104:107]
	v_mfma_f32_16x16x32_bf16 v[92:95], v[148:151], v[234:237], v[92:95]
	v_mfma_f32_16x16x32_bf16 v[88:91], v[156:159], v[234:237], v[88:91]
	v_mfma_f32_16x16x32_bf16 v[76:79], v[148:151], v[242:245], v[76:79]
	v_mfma_f32_16x16x32_bf16 v[72:75], v[156:159], v[242:245], v[72:75]
	s_setprio 0
	s_setprio 1
	v_mfma_f32_16x16x32_bf16 v[118:121], v[160:163], v[176:179], 0
	v_mfma_f32_16x16x32_bf16 v[114:117], v[168:171], v[176:179], 0
	v_mfma_f32_16x16x32_bf16 v[100:103], v[160:163], v[184:187], 0
	v_mfma_f32_16x16x32_bf16 v[96:99], v[168:171], v[184:187], 0
	v_mfma_f32_16x16x32_bf16 v[84:87], v[160:163], v[230:233], 0
	v_mfma_f32_16x16x32_bf16 v[80:83], v[168:171], v[230:233], 0
	v_mfma_f32_16x16x32_bf16 v[68:71], v[160:163], v[238:241], 0
	v_mfma_f32_16x16x32_bf16 v[64:67], v[168:171], v[238:241], 0
	s_setprio 0
	s_setprio 1
	v_mfma_f32_16x16x32_bf16 v[118:121], v[164:167], v[180:183], v[118:121]
	v_mfma_f32_16x16x32_bf16 v[114:117], v[172:175], v[180:183], v[114:117]
	v_mfma_f32_16x16x32_bf16 v[100:103], v[164:167], v[208:211], v[100:103]
	v_mfma_f32_16x16x32_bf16 v[96:99], v[172:175], v[208:211], v[96:99]
	v_mfma_f32_16x16x32_bf16 v[84:87], v[164:167], v[234:237], v[84:87]
	v_mfma_f32_16x16x32_bf16 v[80:83], v[172:175], v[234:237], v[80:83]
	v_mfma_f32_16x16x32_bf16 v[68:71], v[164:167], v[242:245], v[68:71]
	v_mfma_f32_16x16x32_bf16 v[64:67], v[172:175], v[242:245], v[64:67]
	s_setprio 0
	s_barrier
	s_add_i32 s22, s53, s30
	s_mov_b32 m0, s22
	ds_read_b128 v[176:179], v147 offset:16384
	ds_read_b128 v[180:183], v147 offset:17408
	ds_read_b128 v[184:187], v147 offset:18432
	ds_read_b128 v[208:211], v147 offset:19456
	ds_read_b128 v[230:233], v147 offset:20480
	ds_read_b128 v[234:237], v147 offset:21504
	ds_read_b128 v[238:241], v147 offset:22528
	ds_read_b128 v[242:245], v147 offset:23552
	global_load_lds_dwordx4 v112, s[24:25]
	s_add_i32 m0, s22, 0x2000
	s_add_u32 s22, s24, 0x80000
	v_lshl_add_u64 v[212:213], s[24:25], 0, v[134:135]
	s_addc_u32 s23, s25, 0
	s_add_i32 s53, s54, s30
	global_load_lds_dwordx4 v134, s[24:25]
	s_mov_b32 m0, s53
	s_nop 0
	global_load_lds_dwordx4 v112, s[22:23]
	s_add_i32 m0, s53, 0x2000
	s_nop 0
	global_load_lds_dwordx4 v134, s[22:23]
	s_mov_b32 m0, s31
	s_nop 0
	global_load_lds_dwordx4 v130, s[26:27]
	s_mov_b32 m0, s35
	s_nop 0
	global_load_lds_dwordx4 v132, s[26:27]
	s_waitcnt vmcnt(8)
	s_waitcnt lgkmcnt(0)
	s_barrier
	s_setprio 1
	s_waitcnt lgkmcnt(0)
	v_mfma_f32_16x16x32_bf16 v[60:63], v[140:143], v[176:179], 0
	v_mfma_f32_16x16x32_bf16 v[56:59], v[152:155], v[176:179], 0
	v_mfma_f32_16x16x32_bf16 v[44:47], v[140:143], v[184:187], 0
	v_mfma_f32_16x16x32_bf16 v[40:43], v[152:155], v[184:187], 0
	v_mfma_f32_16x16x32_bf16 v[28:31], v[140:143], v[230:233], 0
	v_mfma_f32_16x16x32_bf16 v[24:27], v[152:155], v[230:233], 0
	v_mfma_f32_16x16x32_bf16 v[12:15], v[140:143], v[238:241], 0
	v_mfma_f32_16x16x32_bf16 v[8:11], v[152:155], v[238:241], 0
	s_setprio 0
	s_setprio 1
	v_mfma_f32_16x16x32_bf16 v[60:63], v[148:151], v[180:183], v[60:63]
	v_mfma_f32_16x16x32_bf16 v[56:59], v[156:159], v[180:183], v[56:59]
	v_mfma_f32_16x16x32_bf16 v[44:47], v[148:151], v[208:211], v[44:47]
	v_mfma_f32_16x16x32_bf16 v[40:43], v[156:159], v[208:211], v[40:43]
	v_mfma_f32_16x16x32_bf16 v[28:31], v[148:151], v[234:237], v[28:31]
	v_mfma_f32_16x16x32_bf16 v[24:27], v[156:159], v[234:237], v[24:27]
	v_mfma_f32_16x16x32_bf16 v[12:15], v[148:151], v[242:245], v[12:15]
	v_mfma_f32_16x16x32_bf16 v[8:11], v[156:159], v[242:245], v[8:11]
	s_setprio 0
	s_setprio 1
	v_mfma_f32_16x16x32_bf16 v[52:55], v[160:163], v[176:179], 0
	v_mfma_f32_16x16x32_bf16 v[48:51], v[168:171], v[176:179], 0
	v_mfma_f32_16x16x32_bf16 v[36:39], v[160:163], v[184:187], 0
	v_mfma_f32_16x16x32_bf16 v[32:35], v[168:171], v[184:187], 0
	v_mfma_f32_16x16x32_bf16 v[20:23], v[160:163], v[230:233], 0
	v_mfma_f32_16x16x32_bf16 v[16:19], v[168:171], v[230:233], 0
	v_mfma_f32_16x16x32_bf16 v[4:7], v[160:163], v[238:241], 0
	v_mfma_f32_16x16x32_bf16 v[0:3], v[168:171], v[238:241], 0
	s_setprio 0
	s_setprio 1
	v_mfma_f32_16x16x32_bf16 v[52:55], v[164:167], v[180:183], v[52:55]
	v_mfma_f32_16x16x32_bf16 v[48:51], v[172:175], v[180:183], v[48:51]
	v_mfma_f32_16x16x32_bf16 v[36:39], v[164:167], v[208:211], v[36:39]
	v_mfma_f32_16x16x32_bf16 v[32:35], v[172:175], v[208:211], v[32:35]
	v_mfma_f32_16x16x32_bf16 v[20:23], v[164:167], v[234:237], v[20:23]
	v_mfma_f32_16x16x32_bf16 v[16:19], v[172:175], v[234:237], v[16:19]
	v_mfma_f32_16x16x32_bf16 v[4:7], v[164:167], v[242:245], v[4:7]
	v_mfma_f32_16x16x32_bf16 v[0:3], v[172:175], v[242:245], v[0:3]
	s_setprio 0
	s_barrier
	s_add_i32 s53, 0, 0x18000
	s_add_i32 s54, 0, 0x1c000
	v_add_u32_e32 v156, s53, v145
	v_add_u32_e32 v172, s54, v145
	ds_read_b128 v[140:143], v156
	ds_read_b128 v[148:151], v156 offset:1024
	ds_read_b128 v[152:155], v156 offset:2048
	ds_read_b128 v[156:159], v156 offset:3072
	ds_read_b128 v[160:163], v172
	ds_read_b128 v[164:167], v172 offset:1024
	ds_read_b128 v[168:171], v172 offset:2048
	ds_read_b128 v[172:175], v172 offset:3072
	s_add_u32 s22, s26, 0x120000
	s_addc_u32 s23, s27, 0
	s_mov_b32 m0, s40
	ds_read_b128 v[176:179], v147 offset:32768
	ds_read_b128 v[180:183], v147 offset:33792
	ds_read_b128 v[184:187], v147 offset:34816
	ds_read_b128 v[208:211], v147 offset:35840
	ds_read_b128 v[230:233], v147 offset:36864
	ds_read_b128 v[234:237], v147 offset:37888
	ds_read_b128 v[238:241], v147 offset:38912
	ds_read_b128 v[242:245], v147 offset:39936
	global_load_lds_dwordx4 v130, s[22:23]
	s_mov_b32 m0, s41
	s_nop 0
	global_load_lds_dwordx4 v132, s[22:23]
	s_waitcnt vmcnt(8)
	s_waitcnt lgkmcnt(0)
	s_barrier
	s_setprio 1
	s_waitcnt lgkmcnt(0)
	v_mfma_f32_16x16x32_bf16 v[126:129], v[140:143], v[176:179], v[126:129]
	v_mfma_f32_16x16x32_bf16 v[122:125], v[152:155], v[176:179], v[122:125]
	v_mfma_f32_16x16x32_bf16 v[108:111], v[140:143], v[184:187], v[108:111]
	v_mfma_f32_16x16x32_bf16 v[104:107], v[152:155], v[184:187], v[104:107]
	v_mfma_f32_16x16x32_bf16 v[92:95], v[140:143], v[230:233], v[92:95]
	v_mfma_f32_16x16x32_bf16 v[88:91], v[152:155], v[230:233], v[88:91]
	v_mfma_f32_16x16x32_bf16 v[76:79], v[140:143], v[238:241], v[76:79]
	v_mfma_f32_16x16x32_bf16 v[72:75], v[152:155], v[238:241], v[72:75]
	s_setprio 0
	s_setprio 1
	v_mfma_f32_16x16x32_bf16 v[126:129], v[148:151], v[180:183], v[126:129]
	v_mfma_f32_16x16x32_bf16 v[122:125], v[156:159], v[180:183], v[122:125]
	v_mfma_f32_16x16x32_bf16 v[108:111], v[148:151], v[208:211], v[108:111]
	v_mfma_f32_16x16x32_bf16 v[104:107], v[156:159], v[208:211], v[104:107]
	v_mfma_f32_16x16x32_bf16 v[92:95], v[148:151], v[234:237], v[92:95]
	v_mfma_f32_16x16x32_bf16 v[88:91], v[156:159], v[234:237], v[88:91]
	v_mfma_f32_16x16x32_bf16 v[76:79], v[148:151], v[242:245], v[76:79]
	v_mfma_f32_16x16x32_bf16 v[72:75], v[156:159], v[242:245], v[72:75]
	s_setprio 0
	s_setprio 1
	v_mfma_f32_16x16x32_bf16 v[118:121], v[160:163], v[176:179], v[118:121]
	v_mfma_f32_16x16x32_bf16 v[114:117], v[168:171], v[176:179], v[114:117]
	v_mfma_f32_16x16x32_bf16 v[100:103], v[160:163], v[184:187], v[100:103]
	v_mfma_f32_16x16x32_bf16 v[96:99], v[168:171], v[184:187], v[96:99]
	v_mfma_f32_16x16x32_bf16 v[84:87], v[160:163], v[230:233], v[84:87]
	v_mfma_f32_16x16x32_bf16 v[80:83], v[168:171], v[230:233], v[80:83]
	v_mfma_f32_16x16x32_bf16 v[68:71], v[160:163], v[238:241], v[68:71]
	v_mfma_f32_16x16x32_bf16 v[64:67], v[168:171], v[238:241], v[64:67]
	s_setprio 0
	s_setprio 1
	v_mfma_f32_16x16x32_bf16 v[118:121], v[164:167], v[180:183], v[118:121]
	v_mfma_f32_16x16x32_bf16 v[114:117], v[172:175], v[180:183], v[114:117]
	v_mfma_f32_16x16x32_bf16 v[100:103], v[164:167], v[208:211], v[100:103]
	v_mfma_f32_16x16x32_bf16 v[96:99], v[172:175], v[208:211], v[96:99]
	v_mfma_f32_16x16x32_bf16 v[84:87], v[164:167], v[234:237], v[84:87]
	v_mfma_f32_16x16x32_bf16 v[80:83], v[172:175], v[234:237], v[80:83]
	v_mfma_f32_16x16x32_bf16 v[68:71], v[164:167], v[242:245], v[68:71]
	v_mfma_f32_16x16x32_bf16 v[64:67], v[172:175], v[242:245], v[64:67]
	s_setprio 0
	s_barrier
	s_add_i32 s22, s53, s30
	s_mov_b32 m0, s22
	ds_read_b128 v[176:179], v147 offset:49152
	ds_read_b128 v[180:183], v147 offset:50176
	ds_read_b128 v[184:187], v147 offset:51200
	ds_read_b128 v[208:211], v147 offset:52224
	ds_read_b128 v[230:233], v147 offset:53248
	ds_read_b128 v[234:237], v147 offset:54272
	ds_read_b128 v[238:241], v147 offset:55296
	ds_read_b128 v[242:245], v147 offset:56320
	s_add_u32 s98, s24, 0x80
	s_addc_u32 s99, s25, 0
	global_load_lds_dwordx4 v112, s[98:99]
	s_add_i32 m0, s22, 0x2000
	s_add_u32 s22, s24, 0x80080
	v_lshl_add_u64 v[188:189], v[212:213], 0, s[96:97]
	s_addc_u32 s23, s25, 0
	s_add_i32 s24, s54, s30
	global_load_lds_dwordx4 v[188:189], off
	s_mov_b32 m0, s24
	s_nop 0
	global_load_lds_dwordx4 v112, s[22:23]
	s_add_i32 m0, s24, 0x2000
	s_nop 0
	global_load_lds_dwordx4 v134, s[22:23]
	s_mov_b32 m0, s43
	s_nop 0
	s_add_u32 s98, s26, 0x80
	s_addc_u32 s99, s27, 0
	global_load_lds_dwordx4 v130, s[98:99]
	s_mov_b32 m0, s44
	s_nop 0
	s_add_u32 s98, s26, 0x80
	s_addc_u32 s99, s27, 0
	global_load_lds_dwordx4 v132, s[98:99]
	s_waitcnt vmcnt(8)
	s_waitcnt lgkmcnt(0)
	s_barrier
	s_setprio 1
	s_waitcnt lgkmcnt(0)
	v_mfma_f32_16x16x32_bf16 v[60:63], v[140:143], v[176:179], v[60:63]
	v_mfma_f32_16x16x32_bf16 v[56:59], v[152:155], v[176:179], v[56:59]
	v_mfma_f32_16x16x32_bf16 v[44:47], v[140:143], v[184:187], v[44:47]
	v_mfma_f32_16x16x32_bf16 v[40:43], v[152:155], v[184:187], v[40:43]
	v_mfma_f32_16x16x32_bf16 v[28:31], v[140:143], v[230:233], v[28:31]
	v_mfma_f32_16x16x32_bf16 v[24:27], v[152:155], v[230:233], v[24:27]
	v_mfma_f32_16x16x32_bf16 v[12:15], v[140:143], v[238:241], v[12:15]
	v_mfma_f32_16x16x32_bf16 v[8:11], v[152:155], v[238:241], v[8:11]
	s_setprio 0
	s_setprio 1
	v_mfma_f32_16x16x32_bf16 v[60:63], v[148:151], v[180:183], v[60:63]
	v_mfma_f32_16x16x32_bf16 v[56:59], v[156:159], v[180:183], v[56:59]
	v_mfma_f32_16x16x32_bf16 v[44:47], v[148:151], v[208:211], v[44:47]
	v_mfma_f32_16x16x32_bf16 v[40:43], v[156:159], v[208:211], v[40:43]
	v_mfma_f32_16x16x32_bf16 v[28:31], v[148:151], v[234:237], v[28:31]
	v_mfma_f32_16x16x32_bf16 v[24:27], v[156:159], v[234:237], v[24:27]
	v_mfma_f32_16x16x32_bf16 v[12:15], v[148:151], v[242:245], v[12:15]
	v_mfma_f32_16x16x32_bf16 v[8:11], v[156:159], v[242:245], v[8:11]
	s_setprio 0
	s_setprio 1
	v_mfma_f32_16x16x32_bf16 v[52:55], v[160:163], v[176:179], v[52:55]
	v_mfma_f32_16x16x32_bf16 v[48:51], v[168:171], v[176:179], v[48:51]
	v_mfma_f32_16x16x32_bf16 v[36:39], v[160:163], v[184:187], v[36:39]
	v_mfma_f32_16x16x32_bf16 v[32:35], v[168:171], v[184:187], v[32:35]
	v_mfma_f32_16x16x32_bf16 v[20:23], v[160:163], v[230:233], v[20:23]
	v_mfma_f32_16x16x32_bf16 v[16:19], v[168:171], v[230:233], v[16:19]
	v_mfma_f32_16x16x32_bf16 v[4:7], v[160:163], v[238:241], v[4:7]
	v_mfma_f32_16x16x32_bf16 v[0:3], v[168:171], v[238:241], v[0:3]
	s_setprio 0
	s_setprio 1
	v_mfma_f32_16x16x32_bf16 v[52:55], v[164:167], v[180:183], v[52:55]
	v_mfma_f32_16x16x32_bf16 v[48:51], v[172:175], v[180:183], v[48:51]
	v_mfma_f32_16x16x32_bf16 v[36:39], v[164:167], v[208:211], v[36:39]
	v_mfma_f32_16x16x32_bf16 v[32:35], v[172:175], v[208:211], v[32:35]
	v_mfma_f32_16x16x32_bf16 v[20:23], v[164:167], v[234:237], v[20:23]
	v_mfma_f32_16x16x32_bf16 v[16:19], v[172:175], v[234:237], v[16:19]
	v_mfma_f32_16x16x32_bf16 v[4:7], v[164:167], v[242:245], v[4:7]
	v_mfma_f32_16x16x32_bf16 v[0:3], v[172:175], v[242:245], v[0:3]
	s_setprio 0
	s_barrier
	s_add_i32 s52, s52, 2
	s_add_u32 s50, s50, 0x100
	s_addc_u32 s51, s51, 0
	s_cmp_gt_u32 s52, 29
	s_mov_b64 s[22:23], s[0:1]
	s_cbranch_scc0 .LBB0_804
	s_branch .Lpeel_exit_804
.LBB0_804:
	s_add_u32 s0, s22, 0x100
	s_addc_u32 s1, s23, 0
	s_add_i32 s53, 0, 0x10000
	s_cmp_eq_u32 s52, 28
	s_cselect_b32 s27, s17, s1
	s_cselect_b32 s26, s16, s0
	s_cselect_b32 s25, s15, s51
	s_cselect_b32 s24, s21, s50
	s_add_i32 s54, 0, 0x14000
	v_add_u32_e32 v156, s53, v145
	v_add_u32_e32 v172, s54, v145
	ds_read_b128 v[140:143], v156
	ds_read_b128 v[148:151], v156 offset:1024
	ds_read_b128 v[152:155], v156 offset:2048
	ds_read_b128 v[156:159], v156 offset:3072
	ds_read_b128 v[160:163], v172
	ds_read_b128 v[164:167], v172 offset:1024
	ds_read_b128 v[168:171], v172 offset:2048
	ds_read_b128 v[172:175], v172 offset:3072
	s_add_i32 m0, s31, 0xc000
	ds_read_b128 v[176:179], v147
	ds_read_b128 v[180:183], v147 offset:1024
	ds_read_b128 v[184:187], v147 offset:2048
	ds_read_b128 v[208:211], v147 offset:3072
	ds_read_b128 v[230:233], v147 offset:4096
	ds_read_b128 v[234:237], v147 offset:5120
	ds_read_b128 v[238:241], v147 offset:6144
	ds_read_b128 v[242:245], v147 offset:7168
	global_load_lds_dwordx4 v138, s[22:23]
	s_add_i32 m0, s31, 0xe000
	s_nop 0
	global_load_lds_dwordx4 v136, s[22:23]
	s_waitcnt vmcnt(8)
	s_waitcnt lgkmcnt(0)
	s_barrier
	s_setprio 1
	s_waitcnt lgkmcnt(0)
	v_mfma_f32_16x16x32_bf16 v[126:129], v[140:143], v[176:179], v[126:129]
	v_mfma_f32_16x16x32_bf16 v[122:125], v[152:155], v[176:179], v[122:125]
	v_mfma_f32_16x16x32_bf16 v[108:111], v[140:143], v[184:187], v[108:111]
	v_mfma_f32_16x16x32_bf16 v[104:107], v[152:155], v[184:187], v[104:107]
	v_mfma_f32_16x16x32_bf16 v[92:95], v[140:143], v[230:233], v[92:95]
	v_mfma_f32_16x16x32_bf16 v[88:91], v[152:155], v[230:233], v[88:91]
	v_mfma_f32_16x16x32_bf16 v[76:79], v[140:143], v[238:241], v[76:79]
	v_mfma_f32_16x16x32_bf16 v[72:75], v[152:155], v[238:241], v[72:75]
	s_setprio 0
	s_setprio 1
	v_mfma_f32_16x16x32_bf16 v[126:129], v[148:151], v[180:183], v[126:129]
	v_mfma_f32_16x16x32_bf16 v[122:125], v[156:159], v[180:183], v[122:125]
	v_mfma_f32_16x16x32_bf16 v[108:111], v[148:151], v[208:211], v[108:111]
	v_mfma_f32_16x16x32_bf16 v[104:107], v[156:159], v[208:211], v[104:107]
	v_mfma_f32_16x16x32_bf16 v[92:95], v[148:151], v[234:237], v[92:95]
	v_mfma_f32_16x16x32_bf16 v[88:91], v[156:159], v[234:237], v[88:91]
	v_mfma_f32_16x16x32_bf16 v[76:79], v[148:151], v[242:245], v[76:79]
	v_mfma_f32_16x16x32_bf16 v[72:75], v[156:159], v[242:245], v[72:75]
	s_setprio 0
	s_setprio 1
	v_mfma_f32_16x16x32_bf16 v[118:121], v[160:163], v[176:179], v[118:121]
	v_mfma_f32_16x16x32_bf16 v[114:117], v[168:171], v[176:179], v[114:117]
	v_mfma_f32_16x16x32_bf16 v[100:103], v[160:163], v[184:187], v[100:103]
	v_mfma_f32_16x16x32_bf16 v[96:99], v[168:171], v[184:187], v[96:99]
	v_mfma_f32_16x16x32_bf16 v[84:87], v[160:163], v[230:233], v[84:87]
	v_mfma_f32_16x16x32_bf16 v[80:83], v[168:171], v[230:233], v[80:83]
	v_mfma_f32_16x16x32_bf16 v[68:71], v[160:163], v[238:241], v[68:71]
	v_mfma_f32_16x16x32_bf16 v[64:67], v[168:171], v[238:241], v[64:67]
	s_setprio 0
	s_setprio 1
	v_mfma_f32_16x16x32_bf16 v[118:121], v[164:167], v[180:183], v[118:121]
	v_mfma_f32_16x16x32_bf16 v[114:117], v[172:175], v[180:183], v[114:117]
	v_mfma_f32_16x16x32_bf16 v[100:103], v[164:167], v[208:211], v[100:103]
	v_mfma_f32_16x16x32_bf16 v[96:99], v[172:175], v[208:211], v[96:99]
	v_mfma_f32_16x16x32_bf16 v[84:87], v[164:167], v[234:237], v[84:87]
	v_mfma_f32_16x16x32_bf16 v[80:83], v[172:175], v[234:237], v[80:83]
	v_mfma_f32_16x16x32_bf16 v[68:71], v[164:167], v[242:245], v[68:71]
	v_mfma_f32_16x16x32_bf16 v[64:67], v[172:175], v[242:245], v[64:67]
	s_setprio 0
	s_barrier
	s_add_i32 s22, s53, s30
	s_mov_b32 m0, s22
	ds_read_b128 v[176:179], v147 offset:16384
	ds_read_b128 v[180:183], v147 offset:17408
	ds_read_b128 v[184:187], v147 offset:18432
	ds_read_b128 v[208:211], v147 offset:19456
	ds_read_b128 v[230:233], v147 offset:20480
	ds_read_b128 v[234:237], v147 offset:21504
	ds_read_b128 v[238:241], v147 offset:22528
	ds_read_b128 v[242:245], v147 offset:23552
	global_load_lds_dwordx4 v112, s[24:25]
	s_add_i32 m0, s22, 0x2000
	s_add_u32 s22, s24, 0x80000
	v_lshl_add_u64 v[212:213], s[24:25], 0, v[134:135]
	s_addc_u32 s23, s25, 0
	s_add_i32 s53, s54, s30
	global_load_lds_dwordx4 v134, s[24:25]
	s_mov_b32 m0, s53
	s_nop 0
	global_load_lds_dwordx4 v112, s[22:23]
	s_add_i32 m0, s53, 0x2000
	s_nop 0
	global_load_lds_dwordx4 v134, s[22:23]
	s_mov_b32 m0, s31
	s_nop 0
	global_load_lds_dwordx4 v130, s[26:27]
	s_mov_b32 m0, s35
	s_nop 0
	global_load_lds_dwordx4 v132, s[26:27]
	s_waitcnt vmcnt(8)
	s_waitcnt lgkmcnt(0)
	s_barrier
	s_setprio 1
	s_waitcnt lgkmcnt(0)
	v_mfma_f32_16x16x32_bf16 v[60:63], v[140:143], v[176:179], v[60:63]
	v_mfma_f32_16x16x32_bf16 v[56:59], v[152:155], v[176:179], v[56:59]
	v_mfma_f32_16x16x32_bf16 v[44:47], v[140:143], v[184:187], v[44:47]
	v_mfma_f32_16x16x32_bf16 v[40:43], v[152:155], v[184:187], v[40:43]
	v_mfma_f32_16x16x32_bf16 v[28:31], v[140:143], v[230:233], v[28:31]
	v_mfma_f32_16x16x32_bf16 v[24:27], v[152:155], v[230:233], v[24:27]
	v_mfma_f32_16x16x32_bf16 v[12:15], v[140:143], v[238:241], v[12:15]
	v_mfma_f32_16x16x32_bf16 v[8:11], v[152:155], v[238:241], v[8:11]
	s_setprio 0
	s_setprio 1
	v_mfma_f32_16x16x32_bf16 v[60:63], v[148:151], v[180:183], v[60:63]
	v_mfma_f32_16x16x32_bf16 v[56:59], v[156:159], v[180:183], v[56:59]
	v_mfma_f32_16x16x32_bf16 v[44:47], v[148:151], v[208:211], v[44:47]
	v_mfma_f32_16x16x32_bf16 v[40:43], v[156:159], v[208:211], v[40:43]
	v_mfma_f32_16x16x32_bf16 v[28:31], v[148:151], v[234:237], v[28:31]
	v_mfma_f32_16x16x32_bf16 v[24:27], v[156:159], v[234:237], v[24:27]
	v_mfma_f32_16x16x32_bf16 v[12:15], v[148:151], v[242:245], v[12:15]
	v_mfma_f32_16x16x32_bf16 v[8:11], v[156:159], v[242:245], v[8:11]
	s_setprio 0
	s_setprio 1
	v_mfma_f32_16x16x32_bf16 v[52:55], v[160:163], v[176:179], v[52:55]
	v_mfma_f32_16x16x32_bf16 v[48:51], v[168:171], v[176:179], v[48:51]
	v_mfma_f32_16x16x32_bf16 v[36:39], v[160:163], v[184:187], v[36:39]
	v_mfma_f32_16x16x32_bf16 v[32:35], v[168:171], v[184:187], v[32:35]
	v_mfma_f32_16x16x32_bf16 v[20:23], v[160:163], v[230:233], v[20:23]
	v_mfma_f32_16x16x32_bf16 v[16:19], v[168:171], v[230:233], v[16:19]
	v_mfma_f32_16x16x32_bf16 v[4:7], v[160:163], v[238:241], v[4:7]
	v_mfma_f32_16x16x32_bf16 v[0:3], v[168:171], v[238:241], v[0:3]
	s_setprio 0
	s_setprio 1
	v_mfma_f32_16x16x32_bf16 v[52:55], v[164:167], v[180:183], v[52:55]
	v_mfma_f32_16x16x32_bf16 v[48:51], v[172:175], v[180:183], v[48:51]
	v_mfma_f32_16x16x32_bf16 v[36:39], v[164:167], v[208:211], v[36:39]
	v_mfma_f32_16x16x32_bf16 v[32:35], v[172:175], v[208:211], v[32:35]
	v_mfma_f32_16x16x32_bf16 v[20:23], v[164:167], v[234:237], v[20:23]
	v_mfma_f32_16x16x32_bf16 v[16:19], v[172:175], v[234:237], v[16:19]
	v_mfma_f32_16x16x32_bf16 v[4:7], v[164:167], v[242:245], v[4:7]
	v_mfma_f32_16x16x32_bf16 v[0:3], v[172:175], v[242:245], v[0:3]
	s_setprio 0
	s_barrier
	s_add_i32 s53, 0, 0x18000
	s_add_i32 s54, 0, 0x1c000
	v_add_u32_e32 v156, s53, v145
	v_add_u32_e32 v172, s54, v145
	ds_read_b128 v[140:143], v156
	ds_read_b128 v[148:151], v156 offset:1024
	ds_read_b128 v[152:155], v156 offset:2048
	ds_read_b128 v[156:159], v156 offset:3072
	ds_read_b128 v[160:163], v172
	ds_read_b128 v[164:167], v172 offset:1024
	ds_read_b128 v[168:171], v172 offset:2048
	ds_read_b128 v[172:175], v172 offset:3072
	s_add_u32 s22, s26, 0x120000
	s_addc_u32 s23, s27, 0
	s_mov_b32 m0, s40
	ds_read_b128 v[176:179], v147 offset:32768
	ds_read_b128 v[180:183], v147 offset:33792
	ds_read_b128 v[184:187], v147 offset:34816
	ds_read_b128 v[208:211], v147 offset:35840
	ds_read_b128 v[230:233], v147 offset:36864
	ds_read_b128 v[234:237], v147 offset:37888
	ds_read_b128 v[238:241], v147 offset:38912
	ds_read_b128 v[242:245], v147 offset:39936
	global_load_lds_dwordx4 v130, s[22:23]
	s_mov_b32 m0, s41
	s_nop 0
	global_load_lds_dwordx4 v132, s[22:23]
	s_waitcnt vmcnt(8)
	s_waitcnt lgkmcnt(0)
	s_barrier
	s_setprio 1
	s_waitcnt lgkmcnt(0)
	v_mfma_f32_16x16x32_bf16 v[126:129], v[140:143], v[176:179], v[126:129]
	v_mfma_f32_16x16x32_bf16 v[122:125], v[152:155], v[176:179], v[122:125]
	v_mfma_f32_16x16x32_bf16 v[108:111], v[140:143], v[184:187], v[108:111]
	v_mfma_f32_16x16x32_bf16 v[104:107], v[152:155], v[184:187], v[104:107]
	v_mfma_f32_16x16x32_bf16 v[92:95], v[140:143], v[230:233], v[92:95]
	v_mfma_f32_16x16x32_bf16 v[88:91], v[152:155], v[230:233], v[88:91]
	v_mfma_f32_16x16x32_bf16 v[76:79], v[140:143], v[238:241], v[76:79]
	v_mfma_f32_16x16x32_bf16 v[72:75], v[152:155], v[238:241], v[72:75]
	s_setprio 0
	s_setprio 1
	v_mfma_f32_16x16x32_bf16 v[126:129], v[148:151], v[180:183], v[126:129]
	v_mfma_f32_16x16x32_bf16 v[122:125], v[156:159], v[180:183], v[122:125]
	v_mfma_f32_16x16x32_bf16 v[108:111], v[148:151], v[208:211], v[108:111]
	v_mfma_f32_16x16x32_bf16 v[104:107], v[156:159], v[208:211], v[104:107]
	v_mfma_f32_16x16x32_bf16 v[92:95], v[148:151], v[234:237], v[92:95]
	v_mfma_f32_16x16x32_bf16 v[88:91], v[156:159], v[234:237], v[88:91]
	v_mfma_f32_16x16x32_bf16 v[76:79], v[148:151], v[242:245], v[76:79]
	v_mfma_f32_16x16x32_bf16 v[72:75], v[156:159], v[242:245], v[72:75]
	s_setprio 0
	s_setprio 1
	v_mfma_f32_16x16x32_bf16 v[118:121], v[160:163], v[176:179], v[118:121]
	v_mfma_f32_16x16x32_bf16 v[114:117], v[168:171], v[176:179], v[114:117]
	v_mfma_f32_16x16x32_bf16 v[100:103], v[160:163], v[184:187], v[100:103]
	v_mfma_f32_16x16x32_bf16 v[96:99], v[168:171], v[184:187], v[96:99]
	v_mfma_f32_16x16x32_bf16 v[84:87], v[160:163], v[230:233], v[84:87]
	v_mfma_f32_16x16x32_bf16 v[80:83], v[168:171], v[230:233], v[80:83]
	v_mfma_f32_16x16x32_bf16 v[68:71], v[160:163], v[238:241], v[68:71]
	v_mfma_f32_16x16x32_bf16 v[64:67], v[168:171], v[238:241], v[64:67]
	s_setprio 0
	s_setprio 1
	v_mfma_f32_16x16x32_bf16 v[118:121], v[164:167], v[180:183], v[118:121]
	v_mfma_f32_16x16x32_bf16 v[114:117], v[172:175], v[180:183], v[114:117]
	v_mfma_f32_16x16x32_bf16 v[100:103], v[164:167], v[208:211], v[100:103]
	v_mfma_f32_16x16x32_bf16 v[96:99], v[172:175], v[208:211], v[96:99]
	v_mfma_f32_16x16x32_bf16 v[84:87], v[164:167], v[234:237], v[84:87]
	v_mfma_f32_16x16x32_bf16 v[80:83], v[172:175], v[234:237], v[80:83]
	v_mfma_f32_16x16x32_bf16 v[68:71], v[164:167], v[242:245], v[68:71]
	v_mfma_f32_16x16x32_bf16 v[64:67], v[172:175], v[242:245], v[64:67]
	s_setprio 0
	s_barrier
	s_add_i32 s22, s53, s30
	s_mov_b32 m0, s22
	ds_read_b128 v[176:179], v147 offset:49152
	ds_read_b128 v[180:183], v147 offset:50176
	ds_read_b128 v[184:187], v147 offset:51200
	ds_read_b128 v[208:211], v147 offset:52224
	ds_read_b128 v[230:233], v147 offset:53248
	ds_read_b128 v[234:237], v147 offset:54272
	ds_read_b128 v[238:241], v147 offset:55296
	ds_read_b128 v[242:245], v147 offset:56320
	s_add_u32 s98, s24, 0x80
	s_addc_u32 s99, s25, 0
	global_load_lds_dwordx4 v112, s[98:99]
	s_add_i32 m0, s22, 0x2000
	s_add_u32 s22, s24, 0x80080
	v_lshl_add_u64 v[188:189], v[212:213], 0, s[96:97]
	s_addc_u32 s23, s25, 0
	s_add_i32 s24, s54, s30
	global_load_lds_dwordx4 v[188:189], off
	s_mov_b32 m0, s24
	s_nop 0
	global_load_lds_dwordx4 v112, s[22:23]
	s_add_i32 m0, s24, 0x2000
	s_nop 0
	global_load_lds_dwordx4 v134, s[22:23]
	s_mov_b32 m0, s43
	s_nop 0
	s_add_u32 s98, s26, 0x80
	s_addc_u32 s99, s27, 0
	global_load_lds_dwordx4 v130, s[98:99]
	s_mov_b32 m0, s44
	s_nop 0
	s_add_u32 s98, s26, 0x80
	s_addc_u32 s99, s27, 0
	global_load_lds_dwordx4 v132, s[98:99]
	s_waitcnt vmcnt(8)
	s_waitcnt lgkmcnt(0)
	s_barrier
	s_setprio 1
	s_waitcnt lgkmcnt(0)
	v_mfma_f32_16x16x32_bf16 v[60:63], v[140:143], v[176:179], v[60:63]
	v_mfma_f32_16x16x32_bf16 v[56:59], v[152:155], v[176:179], v[56:59]
	v_mfma_f32_16x16x32_bf16 v[44:47], v[140:143], v[184:187], v[44:47]
	v_mfma_f32_16x16x32_bf16 v[40:43], v[152:155], v[184:187], v[40:43]
	v_mfma_f32_16x16x32_bf16 v[28:31], v[140:143], v[230:233], v[28:31]
	v_mfma_f32_16x16x32_bf16 v[24:27], v[152:155], v[230:233], v[24:27]
	v_mfma_f32_16x16x32_bf16 v[12:15], v[140:143], v[238:241], v[12:15]
	v_mfma_f32_16x16x32_bf16 v[8:11], v[152:155], v[238:241], v[8:11]
	s_setprio 0
	s_setprio 1
	v_mfma_f32_16x16x32_bf16 v[60:63], v[148:151], v[180:183], v[60:63]
	v_mfma_f32_16x16x32_bf16 v[56:59], v[156:159], v[180:183], v[56:59]
	v_mfma_f32_16x16x32_bf16 v[44:47], v[148:151], v[208:211], v[44:47]
	v_mfma_f32_16x16x32_bf16 v[40:43], v[156:159], v[208:211], v[40:43]
	v_mfma_f32_16x16x32_bf16 v[28:31], v[148:151], v[234:237], v[28:31]
	v_mfma_f32_16x16x32_bf16 v[24:27], v[156:159], v[234:237], v[24:27]
	v_mfma_f32_16x16x32_bf16 v[12:15], v[148:151], v[242:245], v[12:15]
	v_mfma_f32_16x16x32_bf16 v[8:11], v[156:159], v[242:245], v[8:11]
	s_setprio 0
	s_setprio 1
	v_mfma_f32_16x16x32_bf16 v[52:55], v[160:163], v[176:179], v[52:55]
	v_mfma_f32_16x16x32_bf16 v[48:51], v[168:171], v[176:179], v[48:51]
	v_mfma_f32_16x16x32_bf16 v[36:39], v[160:163], v[184:187], v[36:39]
	v_mfma_f32_16x16x32_bf16 v[32:35], v[168:171], v[184:187], v[32:35]
	v_mfma_f32_16x16x32_bf16 v[20:23], v[160:163], v[230:233], v[20:23]
	v_mfma_f32_16x16x32_bf16 v[16:19], v[168:171], v[230:233], v[16:19]
	v_mfma_f32_16x16x32_bf16 v[4:7], v[160:163], v[238:241], v[4:7]
	v_mfma_f32_16x16x32_bf16 v[0:3], v[168:171], v[238:241], v[0:3]
	s_setprio 0
	s_setprio 1
	v_mfma_f32_16x16x32_bf16 v[52:55], v[164:167], v[180:183], v[52:55]
	v_mfma_f32_16x16x32_bf16 v[48:51], v[172:175], v[180:183], v[48:51]
	v_mfma_f32_16x16x32_bf16 v[36:39], v[164:167], v[208:211], v[36:39]
	v_mfma_f32_16x16x32_bf16 v[32:35], v[172:175], v[208:211], v[32:35]
	v_mfma_f32_16x16x32_bf16 v[20:23], v[164:167], v[234:237], v[20:23]
	v_mfma_f32_16x16x32_bf16 v[16:19], v[172:175], v[234:237], v[16:19]
	v_mfma_f32_16x16x32_bf16 v[4:7], v[164:167], v[242:245], v[4:7]
	v_mfma_f32_16x16x32_bf16 v[0:3], v[172:175], v[242:245], v[0:3]
	s_setprio 0
	s_barrier
	s_add_i32 s52, s52, 2
	s_add_u32 s50, s50, 0x100
	s_addc_u32 s51, s51, 0
	s_cmp_gt_u32 s52, 29
	s_mov_b64 s[22:23], s[0:1]
	s_cbranch_scc0 .LBB0_804

.LBB0_1136:
	s_add_u32 s48, s18, 0x100
	s_addc_u32 s49, s19, 0
	s_mov_b32 s50, -2
	s_waitcnt lgkmcnt(0)
	s_add_u32 s18, s16, 0x100
	s_addc_u32 s19, s17, 0
	s_add_i32 s51, 0, 0x10000
	s_cmp_eq_u32 s50, 40
	s_cselect_b32 s23, s1, s19
	s_cselect_b32 s22, s0, s18
	s_cselect_b32 s21, s15, s49
	s_cselect_b32 s20, s14, s48
	s_add_i32 s52, 0, 0x14000
	v_add_u32_e32 v156, s51, v145
	v_add_u32_e32 v172, s52, v145
	ds_read_b128 v[140:143], v156
	ds_read_b128 v[148:151], v156 offset:1024
	ds_read_b128 v[152:155], v156 offset:2048
	ds_read_b128 v[156:159], v156 offset:3072
	ds_read_b128 v[160:163], v172
	ds_read_b128 v[164:167], v172 offset:1024
	ds_read_b128 v[168:171], v172 offset:2048
	ds_read_b128 v[172:175], v172 offset:3072
	s_add_i32 m0, s31, 0xc000
	ds_read_b128 v[176:179], v147
	ds_read_b128 v[180:183], v147 offset:1024
	ds_read_b128 v[184:187], v147 offset:2048
	ds_read_b128 v[208:211], v147 offset:3072
	ds_read_b128 v[230:233], v147 offset:4096
	ds_read_b128 v[234:237], v147 offset:5120
	ds_read_b128 v[238:241], v147 offset:6144
	ds_read_b128 v[242:245], v147 offset:7168
	global_load_lds_dwordx4 v138, s[16:17]
	s_add_i32 m0, s31, 0xe000
	s_nop 0
	global_load_lds_dwordx4 v136, s[16:17]
	s_waitcnt vmcnt(8)
	s_waitcnt lgkmcnt(0)
	s_barrier
	s_setprio 1
	s_waitcnt lgkmcnt(0)
	v_mfma_f32_16x16x32_bf16 v[126:129], v[140:143], v[176:179], 0
	v_mfma_f32_16x16x32_bf16 v[122:125], v[152:155], v[176:179], 0
	v_mfma_f32_16x16x32_bf16 v[108:111], v[140:143], v[184:187], 0
	v_mfma_f32_16x16x32_bf16 v[104:107], v[152:155], v[184:187], 0
	v_mfma_f32_16x16x32_bf16 v[92:95], v[140:143], v[230:233], 0
	v_mfma_f32_16x16x32_bf16 v[88:91], v[152:155], v[230:233], 0
	v_mfma_f32_16x16x32_bf16 v[76:79], v[140:143], v[238:241], 0
	v_mfma_f32_16x16x32_bf16 v[72:75], v[152:155], v[238:241], 0
	s_setprio 0
	s_setprio 1
	v_mfma_f32_16x16x32_bf16 v[126:129], v[148:151], v[180:183], v[126:129]
	v_mfma_f32_16x16x32_bf16 v[122:125], v[156:159], v[180:183], v[122:125]
	v_mfma_f32_16x16x32_bf16 v[108:111], v[148:151], v[208:211], v[108:111]
	v_mfma_f32_16x16x32_bf16 v[104:107], v[156:159], v[208:211], v[104:107]
	v_mfma_f32_16x16x32_bf16 v[92:95], v[148:151], v[234:237], v[92:95]
	v_mfma_f32_16x16x32_bf16 v[88:91], v[156:159], v[234:237], v[88:91]
	v_mfma_f32_16x16x32_bf16 v[76:79], v[148:151], v[242:245], v[76:79]
	v_mfma_f32_16x16x32_bf16 v[72:75], v[156:159], v[242:245], v[72:75]
	s_setprio 0
	s_setprio 1
	v_mfma_f32_16x16x32_bf16 v[118:121], v[160:163], v[176:179], 0
	v_mfma_f32_16x16x32_bf16 v[114:117], v[168:171], v[176:179], 0
	v_mfma_f32_16x16x32_bf16 v[100:103], v[160:163], v[184:187], 0
	v_mfma_f32_16x16x32_bf16 v[96:99], v[168:171], v[184:187], 0
	v_mfma_f32_16x16x32_bf16 v[84:87], v[160:163], v[230:233], 0
	v_mfma_f32_16x16x32_bf16 v[80:83], v[168:171], v[230:233], 0
	v_mfma_f32_16x16x32_bf16 v[68:71], v[160:163], v[238:241], 0
	v_mfma_f32_16x16x32_bf16 v[64:67], v[168:171], v[238:241], 0
	s_setprio 0
	s_setprio 1
	v_mfma_f32_16x16x32_bf16 v[118:121], v[164:167], v[180:183], v[118:121]
	v_mfma_f32_16x16x32_bf16 v[114:117], v[172:175], v[180:183], v[114:117]
	v_mfma_f32_16x16x32_bf16 v[100:103], v[164:167], v[208:211], v[100:103]
	v_mfma_f32_16x16x32_bf16 v[96:99], v[172:175], v[208:211], v[96:99]
	v_mfma_f32_16x16x32_bf16 v[84:87], v[164:167], v[234:237], v[84:87]
	v_mfma_f32_16x16x32_bf16 v[80:83], v[172:175], v[234:237], v[80:83]
	v_mfma_f32_16x16x32_bf16 v[68:71], v[164:167], v[242:245], v[68:71]
	v_mfma_f32_16x16x32_bf16 v[64:67], v[172:175], v[242:245], v[64:67]
	s_setprio 0
	s_barrier
	s_add_i32 s16, s51, s30
	s_mov_b32 m0, s16
	ds_read_b128 v[176:179], v147 offset:16384
	ds_read_b128 v[180:183], v147 offset:17408
	ds_read_b128 v[184:187], v147 offset:18432
	ds_read_b128 v[208:211], v147 offset:19456
	ds_read_b128 v[230:233], v147 offset:20480
	ds_read_b128 v[234:237], v147 offset:21504
	ds_read_b128 v[238:241], v147 offset:22528
	ds_read_b128 v[242:245], v147 offset:23552
	global_load_lds_dwordx4 v112, s[20:21]
	s_add_i32 m0, s16, 0x2000
	s_add_u32 s16, s20, 0xb0000
	v_lshl_add_u64 v[212:213], s[20:21], 0, v[134:135]
	s_addc_u32 s17, s21, 0
	s_add_i32 s51, s52, s30
	global_load_lds_dwordx4 v134, s[20:21]
	s_mov_b32 m0, s51
	s_nop 0
	global_load_lds_dwordx4 v112, s[16:17]
	s_add_i32 m0, s51, 0x2000
	s_nop 0
	global_load_lds_dwordx4 v134, s[16:17]
	s_mov_b32 m0, s31
	s_nop 0
	global_load_lds_dwordx4 v130, s[22:23]
	s_mov_b32 m0, s35
	s_nop 0
	global_load_lds_dwordx4 v132, s[22:23]
	s_waitcnt vmcnt(8)
	s_waitcnt lgkmcnt(0)
	s_barrier
	s_setprio 1
	s_waitcnt lgkmcnt(0)
	v_mfma_f32_16x16x32_bf16 v[60:63], v[140:143], v[176:179], 0
	v_mfma_f32_16x16x32_bf16 v[56:59], v[152:155], v[176:179], 0
	v_mfma_f32_16x16x32_bf16 v[44:47], v[140:143], v[184:187], 0
	v_mfma_f32_16x16x32_bf16 v[40:43], v[152:155], v[184:187], 0
	v_mfma_f32_16x16x32_bf16 v[28:31], v[140:143], v[230:233], 0
	v_mfma_f32_16x16x32_bf16 v[24:27], v[152:155], v[230:233], 0
	v_mfma_f32_16x16x32_bf16 v[12:15], v[140:143], v[238:241], 0
	v_mfma_f32_16x16x32_bf16 v[8:11], v[152:155], v[238:241], 0
	s_setprio 0
	s_setprio 1
	v_mfma_f32_16x16x32_bf16 v[60:63], v[148:151], v[180:183], v[60:63]
	v_mfma_f32_16x16x32_bf16 v[56:59], v[156:159], v[180:183], v[56:59]
	v_mfma_f32_16x16x32_bf16 v[44:47], v[148:151], v[208:211], v[44:47]
	v_mfma_f32_16x16x32_bf16 v[40:43], v[156:159], v[208:211], v[40:43]
	v_mfma_f32_16x16x32_bf16 v[28:31], v[148:151], v[234:237], v[28:31]
	v_mfma_f32_16x16x32_bf16 v[24:27], v[156:159], v[234:237], v[24:27]
	v_mfma_f32_16x16x32_bf16 v[12:15], v[148:151], v[242:245], v[12:15]
	v_mfma_f32_16x16x32_bf16 v[8:11], v[156:159], v[242:245], v[8:11]
	s_setprio 0
	s_setprio 1
	v_mfma_f32_16x16x32_bf16 v[52:55], v[160:163], v[176:179], 0
	v_mfma_f32_16x16x32_bf16 v[48:51], v[168:171], v[176:179], 0
	v_mfma_f32_16x16x32_bf16 v[36:39], v[160:163], v[184:187], 0
	v_mfma_f32_16x16x32_bf16 v[32:35], v[168:171], v[184:187], 0
	v_mfma_f32_16x16x32_bf16 v[20:23], v[160:163], v[230:233], 0
	v_mfma_f32_16x16x32_bf16 v[16:19], v[168:171], v[230:233], 0
	v_mfma_f32_16x16x32_bf16 v[4:7], v[160:163], v[238:241], 0
	v_mfma_f32_16x16x32_bf16 v[0:3], v[168:171], v[238:241], 0
	s_setprio 0
	s_setprio 1
	v_mfma_f32_16x16x32_bf16 v[52:55], v[164:167], v[180:183], v[52:55]
	v_mfma_f32_16x16x32_bf16 v[48:51], v[172:175], v[180:183], v[48:51]
	v_mfma_f32_16x16x32_bf16 v[36:39], v[164:167], v[208:211], v[36:39]
	v_mfma_f32_16x16x32_bf16 v[32:35], v[172:175], v[208:211], v[32:35]
	v_mfma_f32_16x16x32_bf16 v[20:23], v[164:167], v[234:237], v[20:23]
	v_mfma_f32_16x16x32_bf16 v[16:19], v[172:175], v[234:237], v[16:19]
	v_mfma_f32_16x16x32_bf16 v[4:7], v[164:167], v[242:245], v[4:7]
	v_mfma_f32_16x16x32_bf16 v[0:3], v[172:175], v[242:245], v[0:3]
	s_setprio 0
	s_barrier
	s_add_i32 s51, 0, 0x18000
	s_add_i32 s52, 0, 0x1c000
	v_add_u32_e32 v156, s51, v145
	v_add_u32_e32 v172, s52, v145
	ds_read_b128 v[140:143], v156
	ds_read_b128 v[148:151], v156 offset:1024
	ds_read_b128 v[152:155], v156 offset:2048
	ds_read_b128 v[156:159], v156 offset:3072
	ds_read_b128 v[160:163], v172
	ds_read_b128 v[164:167], v172 offset:1024
	ds_read_b128 v[168:171], v172 offset:2048
	ds_read_b128 v[172:175], v172 offset:3072
	s_add_u32 s16, s22, 0xb0000
	s_addc_u32 s17, s23, 0
	s_mov_b32 m0, s36
	ds_read_b128 v[176:179], v147 offset:32768
	ds_read_b128 v[180:183], v147 offset:33792
	ds_read_b128 v[184:187], v147 offset:34816
	ds_read_b128 v[208:211], v147 offset:35840
	ds_read_b128 v[230:233], v147 offset:36864
	ds_read_b128 v[234:237], v147 offset:37888
	ds_read_b128 v[238:241], v147 offset:38912
	ds_read_b128 v[242:245], v147 offset:39936
	global_load_lds_dwordx4 v130, s[16:17]
	s_mov_b32 m0, s37
	s_nop 0
	global_load_lds_dwordx4 v132, s[16:17]
	s_waitcnt vmcnt(8)
	s_waitcnt lgkmcnt(0)
	s_barrier
	s_setprio 1
	s_waitcnt lgkmcnt(0)
	v_mfma_f32_16x16x32_bf16 v[126:129], v[140:143], v[176:179], v[126:129]
	v_mfma_f32_16x16x32_bf16 v[122:125], v[152:155], v[176:179], v[122:125]
	v_mfma_f32_16x16x32_bf16 v[108:111], v[140:143], v[184:187], v[108:111]
	v_mfma_f32_16x16x32_bf16 v[104:107], v[152:155], v[184:187], v[104:107]
	v_mfma_f32_16x16x32_bf16 v[92:95], v[140:143], v[230:233], v[92:95]
	v_mfma_f32_16x16x32_bf16 v[88:91], v[152:155], v[230:233], v[88:91]
	v_mfma_f32_16x16x32_bf16 v[76:79], v[140:143], v[238:241], v[76:79]
	v_mfma_f32_16x16x32_bf16 v[72:75], v[152:155], v[238:241], v[72:75]
	s_setprio 0
	s_setprio 1
	v_mfma_f32_16x16x32_bf16 v[126:129], v[148:151], v[180:183], v[126:129]
	v_mfma_f32_16x16x32_bf16 v[122:125], v[156:159], v[180:183], v[122:125]
	v_mfma_f32_16x16x32_bf16 v[108:111], v[148:151], v[208:211], v[108:111]
	v_mfma_f32_16x16x32_bf16 v[104:107], v[156:159], v[208:211], v[104:107]
	v_mfma_f32_16x16x32_bf16 v[92:95], v[148:151], v[234:237], v[92:95]
	v_mfma_f32_16x16x32_bf16 v[88:91], v[156:159], v[234:237], v[88:91]
	v_mfma_f32_16x16x32_bf16 v[76:79], v[148:151], v[242:245], v[76:79]
	v_mfma_f32_16x16x32_bf16 v[72:75], v[156:159], v[242:245], v[72:75]
	s_setprio 0
	s_setprio 1
	v_mfma_f32_16x16x32_bf16 v[118:121], v[160:163], v[176:179], v[118:121]
	v_mfma_f32_16x16x32_bf16 v[114:117], v[168:171], v[176:179], v[114:117]
	v_mfma_f32_16x16x32_bf16 v[100:103], v[160:163], v[184:187], v[100:103]
	v_mfma_f32_16x16x32_bf16 v[96:99], v[168:171], v[184:187], v[96:99]
	v_mfma_f32_16x16x32_bf16 v[84:87], v[160:163], v[230:233], v[84:87]
	v_mfma_f32_16x16x32_bf16 v[80:83], v[168:171], v[230:233], v[80:83]
	v_mfma_f32_16x16x32_bf16 v[68:71], v[160:163], v[238:241], v[68:71]
	v_mfma_f32_16x16x32_bf16 v[64:67], v[168:171], v[238:241], v[64:67]
	s_setprio 0
	s_setprio 1
	v_mfma_f32_16x16x32_bf16 v[118:121], v[164:167], v[180:183], v[118:121]
	v_mfma_f32_16x16x32_bf16 v[114:117], v[172:175], v[180:183], v[114:117]
	v_mfma_f32_16x16x32_bf16 v[100:103], v[164:167], v[208:211], v[100:103]
	v_mfma_f32_16x16x32_bf16 v[96:99], v[172:175], v[208:211], v[96:99]
	v_mfma_f32_16x16x32_bf16 v[84:87], v[164:167], v[234:237], v[84:87]
	v_mfma_f32_16x16x32_bf16 v[80:83], v[172:175], v[234:237], v[80:83]
	v_mfma_f32_16x16x32_bf16 v[68:71], v[164:167], v[242:245], v[68:71]
	v_mfma_f32_16x16x32_bf16 v[64:67], v[172:175], v[242:245], v[64:67]
	s_setprio 0
	s_barrier
	s_add_i32 s16, s51, s30
	s_mov_b32 m0, s16
	ds_read_b128 v[176:179], v147 offset:49152
	ds_read_b128 v[180:183], v147 offset:50176
	ds_read_b128 v[184:187], v147 offset:51200
	ds_read_b128 v[208:211], v147 offset:52224
	ds_read_b128 v[230:233], v147 offset:53248
	ds_read_b128 v[234:237], v147 offset:54272
	ds_read_b128 v[238:241], v147 offset:55296
	ds_read_b128 v[242:245], v147 offset:56320
	s_add_u32 s98, s20, 0x80
	s_addc_u32 s99, s21, 0
	global_load_lds_dwordx4 v112, s[98:99]
	s_add_i32 m0, s16, 0x2000
	s_add_u32 s16, s20, 0xb0080
	v_lshl_add_u64 v[188:189], v[212:213], 0, s[96:97]
	s_addc_u32 s17, s21, 0
	s_add_i32 s20, s52, s30
	global_load_lds_dwordx4 v[188:189], off
	s_mov_b32 m0, s20
	s_nop 0
	global_load_lds_dwordx4 v112, s[16:17]
	s_add_i32 m0, s20, 0x2000
	s_nop 0
	global_load_lds_dwordx4 v134, s[16:17]
	s_mov_b32 m0, s39
	s_nop 0
	s_add_u32 s98, s22, 0x80
	s_addc_u32 s99, s23, 0
	global_load_lds_dwordx4 v130, s[98:99]
	s_mov_b32 m0, s40
	s_nop 0
	s_add_u32 s98, s22, 0x80
	s_addc_u32 s99, s23, 0
	global_load_lds_dwordx4 v132, s[98:99]
	s_waitcnt vmcnt(8)
	s_waitcnt lgkmcnt(0)
	s_barrier
	s_setprio 1
	s_waitcnt lgkmcnt(0)
	v_mfma_f32_16x16x32_bf16 v[60:63], v[140:143], v[176:179], v[60:63]
	v_mfma_f32_16x16x32_bf16 v[56:59], v[152:155], v[176:179], v[56:59]
	v_mfma_f32_16x16x32_bf16 v[44:47], v[140:143], v[184:187], v[44:47]
	v_mfma_f32_16x16x32_bf16 v[40:43], v[152:155], v[184:187], v[40:43]
	v_mfma_f32_16x16x32_bf16 v[28:31], v[140:143], v[230:233], v[28:31]
	v_mfma_f32_16x16x32_bf16 v[24:27], v[152:155], v[230:233], v[24:27]
	v_mfma_f32_16x16x32_bf16 v[12:15], v[140:143], v[238:241], v[12:15]
	v_mfma_f32_16x16x32_bf16 v[8:11], v[152:155], v[238:241], v[8:11]
	s_setprio 0
	s_setprio 1
	v_mfma_f32_16x16x32_bf16 v[60:63], v[148:151], v[180:183], v[60:63]
	v_mfma_f32_16x16x32_bf16 v[56:59], v[156:159], v[180:183], v[56:59]
	v_mfma_f32_16x16x32_bf16 v[44:47], v[148:151], v[208:211], v[44:47]
	v_mfma_f32_16x16x32_bf16 v[40:43], v[156:159], v[208:211], v[40:43]
	v_mfma_f32_16x16x32_bf16 v[28:31], v[148:151], v[234:237], v[28:31]
	v_mfma_f32_16x16x32_bf16 v[24:27], v[156:159], v[234:237], v[24:27]
	v_mfma_f32_16x16x32_bf16 v[12:15], v[148:151], v[242:245], v[12:15]
	v_mfma_f32_16x16x32_bf16 v[8:11], v[156:159], v[242:245], v[8:11]
	s_setprio 0
	s_setprio 1
	v_mfma_f32_16x16x32_bf16 v[52:55], v[160:163], v[176:179], v[52:55]
	v_mfma_f32_16x16x32_bf16 v[48:51], v[168:171], v[176:179], v[48:51]
	v_mfma_f32_16x16x32_bf16 v[36:39], v[160:163], v[184:187], v[36:39]
	v_mfma_f32_16x16x32_bf16 v[32:35], v[168:171], v[184:187], v[32:35]
	v_mfma_f32_16x16x32_bf16 v[20:23], v[160:163], v[230:233], v[20:23]
	v_mfma_f32_16x16x32_bf16 v[16:19], v[168:171], v[230:233], v[16:19]
	v_mfma_f32_16x16x32_bf16 v[4:7], v[160:163], v[238:241], v[4:7]
	v_mfma_f32_16x16x32_bf16 v[0:3], v[168:171], v[238:241], v[0:3]
	s_setprio 0
	s_setprio 1
	v_mfma_f32_16x16x32_bf16 v[52:55], v[164:167], v[180:183], v[52:55]
	v_mfma_f32_16x16x32_bf16 v[48:51], v[172:175], v[180:183], v[48:51]
	v_mfma_f32_16x16x32_bf16 v[36:39], v[164:167], v[208:211], v[36:39]
	v_mfma_f32_16x16x32_bf16 v[32:35], v[172:175], v[208:211], v[32:35]
	v_mfma_f32_16x16x32_bf16 v[20:23], v[164:167], v[234:237], v[20:23]
	v_mfma_f32_16x16x32_bf16 v[16:19], v[172:175], v[234:237], v[16:19]
	v_mfma_f32_16x16x32_bf16 v[4:7], v[164:167], v[242:245], v[4:7]
	v_mfma_f32_16x16x32_bf16 v[0:3], v[172:175], v[242:245], v[0:3]
	s_setprio 0
	s_barrier
	s_add_i32 s50, s50, 2
	s_add_u32 s48, s48, 0x100
	s_addc_u32 s49, s49, 0
	s_cmp_gt_u32 s50, 41
	s_mov_b64 s[16:17], s[18:19]
	s_cbranch_scc0 .LBB0_1137
	s_branch .Lpeel_exit_1137
.LBB0_1137:
	s_add_u32 s18, s16, 0x100
	s_addc_u32 s19, s17, 0
	s_add_i32 s51, 0, 0x10000
	s_cmp_eq_u32 s50, 40
	s_cselect_b32 s23, s1, s19
	s_cselect_b32 s22, s0, s18
	s_cselect_b32 s21, s15, s49
	s_cselect_b32 s20, s14, s48
	s_add_i32 s52, 0, 0x14000
	v_add_u32_e32 v156, s51, v145
	v_add_u32_e32 v172, s52, v145
	ds_read_b128 v[140:143], v156
	ds_read_b128 v[148:151], v156 offset:1024
	ds_read_b128 v[152:155], v156 offset:2048
	ds_read_b128 v[156:159], v156 offset:3072
	ds_read_b128 v[160:163], v172
	ds_read_b128 v[164:167], v172 offset:1024
	ds_read_b128 v[168:171], v172 offset:2048
	ds_read_b128 v[172:175], v172 offset:3072
	s_add_i32 m0, s31, 0xc000
	ds_read_b128 v[176:179], v147
	ds_read_b128 v[180:183], v147 offset:1024
	ds_read_b128 v[184:187], v147 offset:2048
	ds_read_b128 v[208:211], v147 offset:3072
	ds_read_b128 v[230:233], v147 offset:4096
	ds_read_b128 v[234:237], v147 offset:5120
	ds_read_b128 v[238:241], v147 offset:6144
	ds_read_b128 v[242:245], v147 offset:7168
	global_load_lds_dwordx4 v138, s[16:17]
	s_add_i32 m0, s31, 0xe000
	s_nop 0
	global_load_lds_dwordx4 v136, s[16:17]
	s_waitcnt vmcnt(8)
	s_waitcnt lgkmcnt(0)
	s_barrier
	s_setprio 1
	s_waitcnt lgkmcnt(0)
	v_mfma_f32_16x16x32_bf16 v[126:129], v[140:143], v[176:179], v[126:129]
	v_mfma_f32_16x16x32_bf16 v[122:125], v[152:155], v[176:179], v[122:125]
	v_mfma_f32_16x16x32_bf16 v[108:111], v[140:143], v[184:187], v[108:111]
	v_mfma_f32_16x16x32_bf16 v[104:107], v[152:155], v[184:187], v[104:107]
	v_mfma_f32_16x16x32_bf16 v[92:95], v[140:143], v[230:233], v[92:95]
	v_mfma_f32_16x16x32_bf16 v[88:91], v[152:155], v[230:233], v[88:91]
	v_mfma_f32_16x16x32_bf16 v[76:79], v[140:143], v[238:241], v[76:79]
	v_mfma_f32_16x16x32_bf16 v[72:75], v[152:155], v[238:241], v[72:75]
	s_setprio 0
	s_setprio 1
	v_mfma_f32_16x16x32_bf16 v[126:129], v[148:151], v[180:183], v[126:129]
	v_mfma_f32_16x16x32_bf16 v[122:125], v[156:159], v[180:183], v[122:125]
	v_mfma_f32_16x16x32_bf16 v[108:111], v[148:151], v[208:211], v[108:111]
	v_mfma_f32_16x16x32_bf16 v[104:107], v[156:159], v[208:211], v[104:107]
	v_mfma_f32_16x16x32_bf16 v[92:95], v[148:151], v[234:237], v[92:95]
	v_mfma_f32_16x16x32_bf16 v[88:91], v[156:159], v[234:237], v[88:91]
	v_mfma_f32_16x16x32_bf16 v[76:79], v[148:151], v[242:245], v[76:79]
	v_mfma_f32_16x16x32_bf16 v[72:75], v[156:159], v[242:245], v[72:75]
	s_setprio 0
	s_setprio 1
	v_mfma_f32_16x16x32_bf16 v[118:121], v[160:163], v[176:179], v[118:121]
	v_mfma_f32_16x16x32_bf16 v[114:117], v[168:171], v[176:179], v[114:117]
	v_mfma_f32_16x16x32_bf16 v[100:103], v[160:163], v[184:187], v[100:103]
	v_mfma_f32_16x16x32_bf16 v[96:99], v[168:171], v[184:187], v[96:99]
	v_mfma_f32_16x16x32_bf16 v[84:87], v[160:163], v[230:233], v[84:87]
	v_mfma_f32_16x16x32_bf16 v[80:83], v[168:171], v[230:233], v[80:83]
	v_mfma_f32_16x16x32_bf16 v[68:71], v[160:163], v[238:241], v[68:71]
	v_mfma_f32_16x16x32_bf16 v[64:67], v[168:171], v[238:241], v[64:67]
	s_setprio 0
	s_setprio 1
	v_mfma_f32_16x16x32_bf16 v[118:121], v[164:167], v[180:183], v[118:121]
	v_mfma_f32_16x16x32_bf16 v[114:117], v[172:175], v[180:183], v[114:117]
	v_mfma_f32_16x16x32_bf16 v[100:103], v[164:167], v[208:211], v[100:103]
	v_mfma_f32_16x16x32_bf16 v[96:99], v[172:175], v[208:211], v[96:99]
	v_mfma_f32_16x16x32_bf16 v[84:87], v[164:167], v[234:237], v[84:87]
	v_mfma_f32_16x16x32_bf16 v[80:83], v[172:175], v[234:237], v[80:83]
	v_mfma_f32_16x16x32_bf16 v[68:71], v[164:167], v[242:245], v[68:71]
	v_mfma_f32_16x16x32_bf16 v[64:67], v[172:175], v[242:245], v[64:67]
	s_setprio 0
	s_barrier
	s_add_i32 s16, s51, s30
	s_mov_b32 m0, s16
	ds_read_b128 v[176:179], v147 offset:16384
	ds_read_b128 v[180:183], v147 offset:17408
	ds_read_b128 v[184:187], v147 offset:18432
	ds_read_b128 v[208:211], v147 offset:19456
	ds_read_b128 v[230:233], v147 offset:20480
	ds_read_b128 v[234:237], v147 offset:21504
	ds_read_b128 v[238:241], v147 offset:22528
	ds_read_b128 v[242:245], v147 offset:23552
	global_load_lds_dwordx4 v112, s[20:21]
	s_add_i32 m0, s16, 0x2000
	s_add_u32 s16, s20, 0xb0000
	v_lshl_add_u64 v[212:213], s[20:21], 0, v[134:135]
	s_addc_u32 s17, s21, 0
	s_add_i32 s51, s52, s30
	global_load_lds_dwordx4 v134, s[20:21]
	s_mov_b32 m0, s51
	s_nop 0
	global_load_lds_dwordx4 v112, s[16:17]
	s_add_i32 m0, s51, 0x2000
	s_nop 0
	global_load_lds_dwordx4 v134, s[16:17]
	s_mov_b32 m0, s31
	s_nop 0
	global_load_lds_dwordx4 v130, s[22:23]
	s_mov_b32 m0, s35
	s_nop 0
	global_load_lds_dwordx4 v132, s[22:23]
	s_waitcnt vmcnt(8)
	s_waitcnt lgkmcnt(0)
	s_barrier
	s_setprio 1
	s_waitcnt lgkmcnt(0)
	v_mfma_f32_16x16x32_bf16 v[60:63], v[140:143], v[176:179], v[60:63]
	v_mfma_f32_16x16x32_bf16 v[56:59], v[152:155], v[176:179], v[56:59]
	v_mfma_f32_16x16x32_bf16 v[44:47], v[140:143], v[184:187], v[44:47]
	v_mfma_f32_16x16x32_bf16 v[40:43], v[152:155], v[184:187], v[40:43]
	v_mfma_f32_16x16x32_bf16 v[28:31], v[140:143], v[230:233], v[28:31]
	v_mfma_f32_16x16x32_bf16 v[24:27], v[152:155], v[230:233], v[24:27]
	v_mfma_f32_16x16x32_bf16 v[12:15], v[140:143], v[238:241], v[12:15]
	v_mfma_f32_16x16x32_bf16 v[8:11], v[152:155], v[238:241], v[8:11]
	s_setprio 0
	s_setprio 1
	v_mfma_f32_16x16x32_bf16 v[60:63], v[148:151], v[180:183], v[60:63]
	v_mfma_f32_16x16x32_bf16 v[56:59], v[156:159], v[180:183], v[56:59]
	v_mfma_f32_16x16x32_bf16 v[44:47], v[148:151], v[208:211], v[44:47]
	v_mfma_f32_16x16x32_bf16 v[40:43], v[156:159], v[208:211], v[40:43]
	v_mfma_f32_16x16x32_bf16 v[28:31], v[148:151], v[234:237], v[28:31]
	v_mfma_f32_16x16x32_bf16 v[24:27], v[156:159], v[234:237], v[24:27]
	v_mfma_f32_16x16x32_bf16 v[12:15], v[148:151], v[242:245], v[12:15]
	v_mfma_f32_16x16x32_bf16 v[8:11], v[156:159], v[242:245], v[8:11]
	s_setprio 0
	s_setprio 1
	v_mfma_f32_16x16x32_bf16 v[52:55], v[160:163], v[176:179], v[52:55]
	v_mfma_f32_16x16x32_bf16 v[48:51], v[168:171], v[176:179], v[48:51]
	v_mfma_f32_16x16x32_bf16 v[36:39], v[160:163], v[184:187], v[36:39]
	v_mfma_f32_16x16x32_bf16 v[32:35], v[168:171], v[184:187], v[32:35]
	v_mfma_f32_16x16x32_bf16 v[20:23], v[160:163], v[230:233], v[20:23]
	v_mfma_f32_16x16x32_bf16 v[16:19], v[168:171], v[230:233], v[16:19]
	v_mfma_f32_16x16x32_bf16 v[4:7], v[160:163], v[238:241], v[4:7]
	v_mfma_f32_16x16x32_bf16 v[0:3], v[168:171], v[238:241], v[0:3]
	s_setprio 0
	s_setprio 1
	v_mfma_f32_16x16x32_bf16 v[52:55], v[164:167], v[180:183], v[52:55]
	v_mfma_f32_16x16x32_bf16 v[48:51], v[172:175], v[180:183], v[48:51]
	v_mfma_f32_16x16x32_bf16 v[36:39], v[164:167], v[208:211], v[36:39]
	v_mfma_f32_16x16x32_bf16 v[32:35], v[172:175], v[208:211], v[32:35]
	v_mfma_f32_16x16x32_bf16 v[20:23], v[164:167], v[234:237], v[20:23]
	v_mfma_f32_16x16x32_bf16 v[16:19], v[172:175], v[234:237], v[16:19]
	v_mfma_f32_16x16x32_bf16 v[4:7], v[164:167], v[242:245], v[4:7]
	v_mfma_f32_16x16x32_bf16 v[0:3], v[172:175], v[242:245], v[0:3]
	s_setprio 0
	s_barrier
	s_add_i32 s51, 0, 0x18000
	s_add_i32 s52, 0, 0x1c000
	v_add_u32_e32 v156, s51, v145
	v_add_u32_e32 v172, s52, v145
	ds_read_b128 v[140:143], v156
	ds_read_b128 v[148:151], v156 offset:1024
	ds_read_b128 v[152:155], v156 offset:2048
	ds_read_b128 v[156:159], v156 offset:3072
	ds_read_b128 v[160:163], v172
	ds_read_b128 v[164:167], v172 offset:1024
	ds_read_b128 v[168:171], v172 offset:2048
	ds_read_b128 v[172:175], v172 offset:3072
	s_add_u32 s16, s22, 0xb0000
	s_addc_u32 s17, s23, 0
	s_mov_b32 m0, s36
	ds_read_b128 v[176:179], v147 offset:32768
	ds_read_b128 v[180:183], v147 offset:33792
	ds_read_b128 v[184:187], v147 offset:34816
	ds_read_b128 v[208:211], v147 offset:35840
	ds_read_b128 v[230:233], v147 offset:36864
	ds_read_b128 v[234:237], v147 offset:37888
	ds_read_b128 v[238:241], v147 offset:38912
	ds_read_b128 v[242:245], v147 offset:39936
	global_load_lds_dwordx4 v130, s[16:17]
	s_mov_b32 m0, s37
	s_nop 0
	global_load_lds_dwordx4 v132, s[16:17]
	s_waitcnt vmcnt(8)
	s_waitcnt lgkmcnt(0)
	s_barrier
	s_setprio 1
	s_waitcnt lgkmcnt(0)
	v_mfma_f32_16x16x32_bf16 v[126:129], v[140:143], v[176:179], v[126:129]
	v_mfma_f32_16x16x32_bf16 v[122:125], v[152:155], v[176:179], v[122:125]
	v_mfma_f32_16x16x32_bf16 v[108:111], v[140:143], v[184:187], v[108:111]
	v_mfma_f32_16x16x32_bf16 v[104:107], v[152:155], v[184:187], v[104:107]
	v_mfma_f32_16x16x32_bf16 v[92:95], v[140:143], v[230:233], v[92:95]
	v_mfma_f32_16x16x32_bf16 v[88:91], v[152:155], v[230:233], v[88:91]
	v_mfma_f32_16x16x32_bf16 v[76:79], v[140:143], v[238:241], v[76:79]
	v_mfma_f32_16x16x32_bf16 v[72:75], v[152:155], v[238:241], v[72:75]
	s_setprio 0
	s_setprio 1
	v_mfma_f32_16x16x32_bf16 v[126:129], v[148:151], v[180:183], v[126:129]
	v_mfma_f32_16x16x32_bf16 v[122:125], v[156:159], v[180:183], v[122:125]
	v_mfma_f32_16x16x32_bf16 v[108:111], v[148:151], v[208:211], v[108:111]
	v_mfma_f32_16x16x32_bf16 v[104:107], v[156:159], v[208:211], v[104:107]
	v_mfma_f32_16x16x32_bf16 v[92:95], v[148:151], v[234:237], v[92:95]
	v_mfma_f32_16x16x32_bf16 v[88:91], v[156:159], v[234:237], v[88:91]
	v_mfma_f32_16x16x32_bf16 v[76:79], v[148:151], v[242:245], v[76:79]
	v_mfma_f32_16x16x32_bf16 v[72:75], v[156:159], v[242:245], v[72:75]
	s_setprio 0
	s_setprio 1
	v_mfma_f32_16x16x32_bf16 v[118:121], v[160:163], v[176:179], v[118:121]
	v_mfma_f32_16x16x32_bf16 v[114:117], v[168:171], v[176:179], v[114:117]
	v_mfma_f32_16x16x32_bf16 v[100:103], v[160:163], v[184:187], v[100:103]
	v_mfma_f32_16x16x32_bf16 v[96:99], v[168:171], v[184:187], v[96:99]
	v_mfma_f32_16x16x32_bf16 v[84:87], v[160:163], v[230:233], v[84:87]
	v_mfma_f32_16x16x32_bf16 v[80:83], v[168:171], v[230:233], v[80:83]
	v_mfma_f32_16x16x32_bf16 v[68:71], v[160:163], v[238:241], v[68:71]
	v_mfma_f32_16x16x32_bf16 v[64:67], v[168:171], v[238:241], v[64:67]
	s_setprio 0
	s_setprio 1
	v_mfma_f32_16x16x32_bf16 v[118:121], v[164:167], v[180:183], v[118:121]
	v_mfma_f32_16x16x32_bf16 v[114:117], v[172:175], v[180:183], v[114:117]
	v_mfma_f32_16x16x32_bf16 v[100:103], v[164:167], v[208:211], v[100:103]
	v_mfma_f32_16x16x32_bf16 v[96:99], v[172:175], v[208:211], v[96:99]
	v_mfma_f32_16x16x32_bf16 v[84:87], v[164:167], v[234:237], v[84:87]
	v_mfma_f32_16x16x32_bf16 v[80:83], v[172:175], v[234:237], v[80:83]
	v_mfma_f32_16x16x32_bf16 v[68:71], v[164:167], v[242:245], v[68:71]
	v_mfma_f32_16x16x32_bf16 v[64:67], v[172:175], v[242:245], v[64:67]
	s_setprio 0
	s_barrier
	s_add_i32 s16, s51, s30
	s_mov_b32 m0, s16
	ds_read_b128 v[176:179], v147 offset:49152
	ds_read_b128 v[180:183], v147 offset:50176
	ds_read_b128 v[184:187], v147 offset:51200
	ds_read_b128 v[208:211], v147 offset:52224
	ds_read_b128 v[230:233], v147 offset:53248
	ds_read_b128 v[234:237], v147 offset:54272
	ds_read_b128 v[238:241], v147 offset:55296
	ds_read_b128 v[242:245], v147 offset:56320
	s_add_u32 s98, s20, 0x80
	s_addc_u32 s99, s21, 0
	global_load_lds_dwordx4 v112, s[98:99]
	s_add_i32 m0, s16, 0x2000
	s_add_u32 s16, s20, 0xb0080
	v_lshl_add_u64 v[188:189], v[212:213], 0, s[96:97]
	s_addc_u32 s17, s21, 0
	s_add_i32 s20, s52, s30
	global_load_lds_dwordx4 v[188:189], off
	s_mov_b32 m0, s20
	s_nop 0
	global_load_lds_dwordx4 v112, s[16:17]
	s_add_i32 m0, s20, 0x2000
	s_nop 0
	global_load_lds_dwordx4 v134, s[16:17]
	s_mov_b32 m0, s39
	s_nop 0
	s_add_u32 s98, s22, 0x80
	s_addc_u32 s99, s23, 0
	global_load_lds_dwordx4 v130, s[98:99]
	s_mov_b32 m0, s40
	s_nop 0
	s_add_u32 s98, s22, 0x80
	s_addc_u32 s99, s23, 0
	global_load_lds_dwordx4 v132, s[98:99]
	s_waitcnt vmcnt(8)
	s_waitcnt lgkmcnt(0)
	s_barrier
	s_setprio 1
	s_waitcnt lgkmcnt(0)
	v_mfma_f32_16x16x32_bf16 v[60:63], v[140:143], v[176:179], v[60:63]
	v_mfma_f32_16x16x32_bf16 v[56:59], v[152:155], v[176:179], v[56:59]
	v_mfma_f32_16x16x32_bf16 v[44:47], v[140:143], v[184:187], v[44:47]
	v_mfma_f32_16x16x32_bf16 v[40:43], v[152:155], v[184:187], v[40:43]
	v_mfma_f32_16x16x32_bf16 v[28:31], v[140:143], v[230:233], v[28:31]
	v_mfma_f32_16x16x32_bf16 v[24:27], v[152:155], v[230:233], v[24:27]
	v_mfma_f32_16x16x32_bf16 v[12:15], v[140:143], v[238:241], v[12:15]
	v_mfma_f32_16x16x32_bf16 v[8:11], v[152:155], v[238:241], v[8:11]
	s_setprio 0
	s_setprio 1
	v_mfma_f32_16x16x32_bf16 v[60:63], v[148:151], v[180:183], v[60:63]
	v_mfma_f32_16x16x32_bf16 v[56:59], v[156:159], v[180:183], v[56:59]
	v_mfma_f32_16x16x32_bf16 v[44:47], v[148:151], v[208:211], v[44:47]
	v_mfma_f32_16x16x32_bf16 v[40:43], v[156:159], v[208:211], v[40:43]
	v_mfma_f32_16x16x32_bf16 v[28:31], v[148:151], v[234:237], v[28:31]
	v_mfma_f32_16x16x32_bf16 v[24:27], v[156:159], v[234:237], v[24:27]
	v_mfma_f32_16x16x32_bf16 v[12:15], v[148:151], v[242:245], v[12:15]
	v_mfma_f32_16x16x32_bf16 v[8:11], v[156:159], v[242:245], v[8:11]
	s_setprio 0
	s_setprio 1
	v_mfma_f32_16x16x32_bf16 v[52:55], v[160:163], v[176:179], v[52:55]
	v_mfma_f32_16x16x32_bf16 v[48:51], v[168:171], v[176:179], v[48:51]
	v_mfma_f32_16x16x32_bf16 v[36:39], v[160:163], v[184:187], v[36:39]
	v_mfma_f32_16x16x32_bf16 v[32:35], v[168:171], v[184:187], v[32:35]
	v_mfma_f32_16x16x32_bf16 v[20:23], v[160:163], v[230:233], v[20:23]
	v_mfma_f32_16x16x32_bf16 v[16:19], v[168:171], v[230:233], v[16:19]
	v_mfma_f32_16x16x32_bf16 v[4:7], v[160:163], v[238:241], v[4:7]
	v_mfma_f32_16x16x32_bf16 v[0:3], v[168:171], v[238:241], v[0:3]
	s_setprio 0
	s_setprio 1
	v_mfma_f32_16x16x32_bf16 v[52:55], v[164:167], v[180:183], v[52:55]
	v_mfma_f32_16x16x32_bf16 v[48:51], v[172:175], v[180:183], v[48:51]
	v_mfma_f32_16x16x32_bf16 v[36:39], v[164:167], v[208:211], v[36:39]
	v_mfma_f32_16x16x32_bf16 v[32:35], v[172:175], v[208:211], v[32:35]
	v_mfma_f32_16x16x32_bf16 v[20:23], v[164:167], v[234:237], v[20:23]
	v_mfma_f32_16x16x32_bf16 v[16:19], v[172:175], v[234:237], v[16:19]
	v_mfma_f32_16x16x32_bf16 v[4:7], v[164:167], v[242:245], v[4:7]
	v_mfma_f32_16x16x32_bf16 v[0:3], v[172:175], v[242:245], v[0:3]
	s_setprio 0
	s_barrier
	s_add_i32 s50, s50, 2
	s_add_u32 s48, s48, 0x100
	s_addc_u32 s49, s49, 0
	s_cmp_gt_u32 s50, 41
	s_mov_b64 s[16:17], s[18:19]
	s_cbranch_scc0 .LBB0_1137

.LBB0_1951:
	s_ashr_i32 s17, s16, 31
	s_lshl_b64 s[18:19], s[16:17], 19
	s_add_u32 s18, s42, s18
	s_addc_u32 s19, s43, s19
	s_and_b64 s[20:21], s[2:3], exec
	s_cselect_b32 s5, s19, s27
	s_cselect_b32 s17, s18, s26
	s_ashr_i32 s15, s14, 31
	s_lshl_b64 s[20:21], s[14:15], 19
	s_add_u32 s20, s40, s20
	s_addc_u32 s21, s41, s21
	s_and_b64 s[28:29], s[2:3], exec
	s_cselect_b32 s15, s21, s25
	s_cselect_b32 s51, s20, s24
	s_add_u32 s52, s24, 0x100
	s_addc_u32 s53, s25, 0
	s_add_u32 s24, s26, 0x40080
	s_addc_u32 s25, s27, 0
	s_mov_b32 s54, -2
	s_add_u32 s26, s24, 0xfffc0080
	s_addc_u32 s27, s25, -1
	s_add_i32 s55, 0, 0x10000
	s_cmp_eq_u32 s54, 12
	s_cselect_b32 s29, s5, s27
	s_cselect_b32 s28, s17, s26
	v_add_u32_e32 v144, s55, v146
	s_cselect_b32 s27, s15, s53
	s_cselect_b32 s26, s51, s52
	s_add_i32 s58, 0, 0x14000
	ds_read_b128 v[140:143], v144
	ds_read_b128 v[150:153], v144 offset:1024
	ds_read_b128 v[154:157], v144 offset:2048
	ds_read_b128 v[158:161], v144 offset:3072
	v_add_u32_e32 v144, s58, v146
	ds_read_b128 v[162:165], v144
	ds_read_b128 v[166:169], v144 offset:1024
	ds_read_b128 v[170:173], v144 offset:2048
	ds_read_b128 v[174:177], v144 offset:3072
	s_add_i32 m0, s23, 0xc000
	ds_read_b128 v[178:181], v149
	ds_read_b128 v[182:185], v149 offset:1024
	ds_read_b128 v[186:189], v149 offset:2048
	ds_read_b128 v[208:211], v149 offset:3072
	ds_read_b128 v[230:233], v149 offset:4096
	ds_read_b128 v[234:237], v149 offset:5120
	ds_read_b128 v[238:241], v149 offset:6144
	ds_read_b128 v[242:245], v149 offset:7168
	global_load_lds_dwordx4 v138, s[24:25]
	s_add_i32 m0, s23, 0xe000
	s_nop 0
	global_load_lds_dwordx4 v136, s[24:25]
	s_waitcnt vmcnt(8)
	s_waitcnt lgkmcnt(0)
	s_barrier
	s_setprio 1
	s_waitcnt lgkmcnt(0)
	v_mfma_f32_16x16x32_bf16 v[126:129], v[140:143], v[178:181], 0
	v_mfma_f32_16x16x32_bf16 v[118:121], v[154:157], v[178:181], 0
	v_mfma_f32_16x16x32_bf16 v[108:111], v[140:143], v[186:189], 0
	v_mfma_f32_16x16x32_bf16 v[100:103], v[154:157], v[186:189], 0
	v_mfma_f32_16x16x32_bf16 v[92:95], v[140:143], v[230:233], 0
	v_mfma_f32_16x16x32_bf16 v[84:87], v[154:157], v[230:233], 0
	v_mfma_f32_16x16x32_bf16 v[76:79], v[140:143], v[238:241], 0
	v_mfma_f32_16x16x32_bf16 v[68:71], v[154:157], v[238:241], 0
	s_setprio 0
	s_setprio 1
	v_mfma_f32_16x16x32_bf16 v[126:129], v[150:153], v[182:185], v[126:129]
	v_mfma_f32_16x16x32_bf16 v[118:121], v[158:161], v[182:185], v[118:121]
	v_mfma_f32_16x16x32_bf16 v[108:111], v[150:153], v[208:211], v[108:111]
	v_mfma_f32_16x16x32_bf16 v[100:103], v[158:161], v[208:211], v[100:103]
	v_mfma_f32_16x16x32_bf16 v[92:95], v[150:153], v[234:237], v[92:95]
	v_mfma_f32_16x16x32_bf16 v[84:87], v[158:161], v[234:237], v[84:87]
	v_mfma_f32_16x16x32_bf16 v[76:79], v[150:153], v[242:245], v[76:79]
	v_mfma_f32_16x16x32_bf16 v[68:71], v[158:161], v[242:245], v[68:71]
	s_setprio 0
	s_setprio 1
	v_mfma_f32_16x16x32_bf16 v[122:125], v[162:165], v[178:181], 0
	v_mfma_f32_16x16x32_bf16 v[114:117], v[170:173], v[178:181], 0
	v_mfma_f32_16x16x32_bf16 v[104:107], v[162:165], v[186:189], 0
	v_mfma_f32_16x16x32_bf16 v[96:99], v[170:173], v[186:189], 0
	v_mfma_f32_16x16x32_bf16 v[88:91], v[162:165], v[230:233], 0
	v_mfma_f32_16x16x32_bf16 v[80:83], v[170:173], v[230:233], 0
	v_mfma_f32_16x16x32_bf16 v[72:75], v[162:165], v[238:241], 0
	v_mfma_f32_16x16x32_bf16 v[64:67], v[170:173], v[238:241], 0
	s_setprio 0
	s_setprio 1
	v_mfma_f32_16x16x32_bf16 v[122:125], v[166:169], v[182:185], v[122:125]
	v_mfma_f32_16x16x32_bf16 v[114:117], v[174:177], v[182:185], v[114:117]
	v_mfma_f32_16x16x32_bf16 v[104:107], v[166:169], v[208:211], v[104:107]
	v_mfma_f32_16x16x32_bf16 v[96:99], v[174:177], v[208:211], v[96:99]
	v_mfma_f32_16x16x32_bf16 v[88:91], v[166:169], v[234:237], v[88:91]
	v_mfma_f32_16x16x32_bf16 v[80:83], v[174:177], v[234:237], v[80:83]
	v_mfma_f32_16x16x32_bf16 v[72:75], v[166:169], v[242:245], v[72:75]
	v_mfma_f32_16x16x32_bf16 v[64:67], v[174:177], v[242:245], v[64:67]
	s_setprio 0
	s_barrier
	s_add_i32 s55, s55, s35
	s_mov_b32 m0, s55
	ds_read_b128 v[178:181], v149 offset:16384
	ds_read_b128 v[182:185], v149 offset:17408
	ds_read_b128 v[186:189], v149 offset:18432
	ds_read_b128 v[208:211], v149 offset:19456
	ds_read_b128 v[230:233], v149 offset:20480
	ds_read_b128 v[234:237], v149 offset:21504
	ds_read_b128 v[238:241], v149 offset:22528
	ds_read_b128 v[242:245], v149 offset:23552
	global_load_lds_dwordx4 v112, s[26:27]
	s_add_i32 m0, s55, 0x2000
	s_add_u32 s56, s26, 0x40000
	v_lshl_add_u64 v[246:247], s[26:27], 0, v[134:135]
	s_addc_u32 s57, s27, 0
	s_add_i32 s55, s58, s35
	global_load_lds_dwordx4 v134, s[26:27]
	s_mov_b32 m0, s55
	v_lshl_add_u64 v[250:251], s[28:29], 0, v[132:133]
	global_load_lds_dwordx4 v112, s[56:57]
	s_add_i32 m0, s55, 0x2000
	s_nop 0
	global_load_lds_dwordx4 v134, s[56:57]
	v_lshl_add_u64 v[248:249], s[28:29], 0, v[130:131]
	s_mov_b32 m0, s23
	s_nop 0
	global_load_lds_dwordx4 v130, s[28:29]
	s_mov_b32 m0, s44
	s_nop 0
	global_load_lds_dwordx4 v132, s[28:29]
	s_waitcnt vmcnt(8)
	s_waitcnt lgkmcnt(0)
	s_barrier
	s_setprio 1
	s_waitcnt lgkmcnt(0)
	v_mfma_f32_16x16x32_bf16 v[60:63], v[140:143], v[178:181], 0
	v_mfma_f32_16x16x32_bf16 v[52:55], v[154:157], v[178:181], 0
	v_mfma_f32_16x16x32_bf16 v[44:47], v[140:143], v[186:189], 0
	v_mfma_f32_16x16x32_bf16 v[36:39], v[154:157], v[186:189], 0
	v_mfma_f32_16x16x32_bf16 v[28:31], v[140:143], v[230:233], 0
	v_mfma_f32_16x16x32_bf16 v[20:23], v[154:157], v[230:233], 0
	v_mfma_f32_16x16x32_bf16 v[12:15], v[140:143], v[238:241], 0
	v_mfma_f32_16x16x32_bf16 v[4:7], v[154:157], v[238:241], 0
	s_setprio 0
	s_setprio 1
	v_mfma_f32_16x16x32_bf16 v[60:63], v[150:153], v[182:185], v[60:63]
	v_mfma_f32_16x16x32_bf16 v[52:55], v[158:161], v[182:185], v[52:55]
	v_mfma_f32_16x16x32_bf16 v[44:47], v[150:153], v[208:211], v[44:47]
	v_mfma_f32_16x16x32_bf16 v[36:39], v[158:161], v[208:211], v[36:39]
	v_mfma_f32_16x16x32_bf16 v[28:31], v[150:153], v[234:237], v[28:31]
	v_mfma_f32_16x16x32_bf16 v[20:23], v[158:161], v[234:237], v[20:23]
	v_mfma_f32_16x16x32_bf16 v[12:15], v[150:153], v[242:245], v[12:15]
	v_mfma_f32_16x16x32_bf16 v[4:7], v[158:161], v[242:245], v[4:7]
	s_setprio 0
	s_setprio 1
	v_mfma_f32_16x16x32_bf16 v[56:59], v[162:165], v[178:181], 0
	v_mfma_f32_16x16x32_bf16 v[48:51], v[170:173], v[178:181], 0
	v_mfma_f32_16x16x32_bf16 v[40:43], v[162:165], v[186:189], 0
	v_mfma_f32_16x16x32_bf16 v[32:35], v[170:173], v[186:189], 0
	v_mfma_f32_16x16x32_bf16 v[24:27], v[162:165], v[230:233], 0
	v_mfma_f32_16x16x32_bf16 v[16:19], v[170:173], v[230:233], 0
	v_mfma_f32_16x16x32_bf16 v[8:11], v[162:165], v[238:241], 0
	v_mfma_f32_16x16x32_bf16 v[0:3], v[170:173], v[238:241], 0
	s_setprio 0
	s_setprio 1
	v_mfma_f32_16x16x32_bf16 v[56:59], v[166:169], v[182:185], v[56:59]
	v_mfma_f32_16x16x32_bf16 v[48:51], v[174:177], v[182:185], v[48:51]
	v_mfma_f32_16x16x32_bf16 v[40:43], v[166:169], v[208:211], v[40:43]
	v_mfma_f32_16x16x32_bf16 v[32:35], v[174:177], v[208:211], v[32:35]
	v_mfma_f32_16x16x32_bf16 v[24:27], v[166:169], v[234:237], v[24:27]
	v_mfma_f32_16x16x32_bf16 v[16:19], v[174:177], v[234:237], v[16:19]
	v_mfma_f32_16x16x32_bf16 v[8:11], v[166:169], v[242:245], v[8:11]
	v_mfma_f32_16x16x32_bf16 v[0:3], v[174:177], v[242:245], v[0:3]
	s_setprio 0
	s_barrier
	s_add_i32 s55, 0, 0x18000
	v_add_u32_e32 v144, s55, v146
	s_add_i32 s56, 0, 0x1c000
	ds_read_b128 v[140:143], v144
	ds_read_b128 v[150:153], v144 offset:1024
	ds_read_b128 v[154:157], v144 offset:2048
	ds_read_b128 v[158:161], v144 offset:3072
	v_add_u32_e32 v144, s56, v146
	ds_read_b128 v[162:165], v144
	ds_read_b128 v[166:169], v144 offset:1024
	ds_read_b128 v[170:173], v144 offset:2048
	ds_read_b128 v[174:177], v144 offset:3072
	s_add_u32 s28, s28, 0x40000
	s_addc_u32 s29, s29, 0
	s_mov_b32 m0, s45
	ds_read_b128 v[178:181], v149 offset:32768
	ds_read_b128 v[182:185], v149 offset:33792
	ds_read_b128 v[186:189], v149 offset:34816
	ds_read_b128 v[208:211], v149 offset:35840
	ds_read_b128 v[230:233], v149 offset:36864
	ds_read_b128 v[234:237], v149 offset:37888
	ds_read_b128 v[238:241], v149 offset:38912
	ds_read_b128 v[242:245], v149 offset:39936
	global_load_lds_dwordx4 v130, s[28:29]
	s_mov_b32 m0, s46
	s_nop 0
	global_load_lds_dwordx4 v132, s[28:29]
	s_waitcnt vmcnt(8)
	s_waitcnt lgkmcnt(0)
	s_barrier
	s_setprio 1
	s_waitcnt lgkmcnt(0)
	v_mfma_f32_16x16x32_bf16 v[126:129], v[140:143], v[178:181], v[126:129]
	v_mfma_f32_16x16x32_bf16 v[118:121], v[154:157], v[178:181], v[118:121]
	v_mfma_f32_16x16x32_bf16 v[108:111], v[140:143], v[186:189], v[108:111]
	v_mfma_f32_16x16x32_bf16 v[100:103], v[154:157], v[186:189], v[100:103]
	v_mfma_f32_16x16x32_bf16 v[92:95], v[140:143], v[230:233], v[92:95]
	v_mfma_f32_16x16x32_bf16 v[84:87], v[154:157], v[230:233], v[84:87]
	v_mfma_f32_16x16x32_bf16 v[76:79], v[140:143], v[238:241], v[76:79]
	v_mfma_f32_16x16x32_bf16 v[68:71], v[154:157], v[238:241], v[68:71]
	s_setprio 0
	s_setprio 1
	v_mfma_f32_16x16x32_bf16 v[126:129], v[150:153], v[182:185], v[126:129]
	v_mfma_f32_16x16x32_bf16 v[118:121], v[158:161], v[182:185], v[118:121]
	v_mfma_f32_16x16x32_bf16 v[108:111], v[150:153], v[208:211], v[108:111]
	v_mfma_f32_16x16x32_bf16 v[100:103], v[158:161], v[208:211], v[100:103]
	v_mfma_f32_16x16x32_bf16 v[92:95], v[150:153], v[234:237], v[92:95]
	v_mfma_f32_16x16x32_bf16 v[84:87], v[158:161], v[234:237], v[84:87]
	v_mfma_f32_16x16x32_bf16 v[76:79], v[150:153], v[242:245], v[76:79]
	v_mfma_f32_16x16x32_bf16 v[68:71], v[158:161], v[242:245], v[68:71]
	s_setprio 0
	s_setprio 1
	v_mfma_f32_16x16x32_bf16 v[122:125], v[162:165], v[178:181], v[122:125]
	v_mfma_f32_16x16x32_bf16 v[114:117], v[170:173], v[178:181], v[114:117]
	v_mfma_f32_16x16x32_bf16 v[104:107], v[162:165], v[186:189], v[104:107]
	v_mfma_f32_16x16x32_bf16 v[96:99], v[170:173], v[186:189], v[96:99]
	v_mfma_f32_16x16x32_bf16 v[88:91], v[162:165], v[230:233], v[88:91]
	v_mfma_f32_16x16x32_bf16 v[80:83], v[170:173], v[230:233], v[80:83]
	v_mfma_f32_16x16x32_bf16 v[72:75], v[162:165], v[238:241], v[72:75]
	v_mfma_f32_16x16x32_bf16 v[64:67], v[170:173], v[238:241], v[64:67]
	s_setprio 0
	s_setprio 1
	v_mfma_f32_16x16x32_bf16 v[122:125], v[166:169], v[182:185], v[122:125]
	v_mfma_f32_16x16x32_bf16 v[114:117], v[174:177], v[182:185], v[114:117]
	v_mfma_f32_16x16x32_bf16 v[104:107], v[166:169], v[208:211], v[104:107]
	v_mfma_f32_16x16x32_bf16 v[96:99], v[174:177], v[208:211], v[96:99]
	v_mfma_f32_16x16x32_bf16 v[88:91], v[166:169], v[234:237], v[88:91]
	v_mfma_f32_16x16x32_bf16 v[80:83], v[174:177], v[234:237], v[80:83]
	v_mfma_f32_16x16x32_bf16 v[72:75], v[166:169], v[242:245], v[72:75]
	v_mfma_f32_16x16x32_bf16 v[64:67], v[174:177], v[242:245], v[64:67]
	s_setprio 0
	s_barrier
	s_add_i32 s28, s55, s35
	s_mov_b32 m0, s28
	ds_read_b128 v[178:181], v149 offset:49152
	ds_read_b128 v[182:185], v149 offset:50176
	ds_read_b128 v[186:189], v149 offset:51200
	ds_read_b128 v[208:211], v149 offset:52224
	ds_read_b128 v[230:233], v149 offset:53248
	ds_read_b128 v[234:237], v149 offset:54272
	ds_read_b128 v[238:241], v149 offset:55296
	ds_read_b128 v[242:245], v149 offset:56320
	s_add_u32 s98, s26, 0x80
	s_addc_u32 s99, s27, 0
	global_load_lds_dwordx4 v112, s[98:99]
	s_add_i32 m0, s28, 0x2000
	s_add_u32 s26, s26, 0x40080
	v_lshl_add_u64 v[212:213], v[246:247], 0, s[96:97]
	s_addc_u32 s27, s27, 0
	s_add_i32 s28, s56, s35
	global_load_lds_dwordx4 v[212:213], off
	s_mov_b32 m0, s28
	s_nop 0
	global_load_lds_dwordx4 v112, s[26:27]
	s_add_i32 m0, s28, 0x2000
	s_nop 0
	global_load_lds_dwordx4 v134, s[26:27]
	v_lshl_add_u64 v[212:213], v[248:249], 0, s[96:97]
	s_mov_b32 m0, s47
	s_nop 0
	global_load_lds_dwordx4 v[212:213], off
	v_lshl_add_u64 v[212:213], v[250:251], 0, s[96:97]
	s_mov_b32 m0, s48
	s_nop 0
	global_load_lds_dwordx4 v[212:213], off
	s_waitcnt vmcnt(8)
	s_waitcnt lgkmcnt(0)
	s_barrier
	s_setprio 1
	s_waitcnt lgkmcnt(0)
	v_mfma_f32_16x16x32_bf16 v[60:63], v[140:143], v[178:181], v[60:63]
	v_mfma_f32_16x16x32_bf16 v[52:55], v[154:157], v[178:181], v[52:55]
	v_mfma_f32_16x16x32_bf16 v[44:47], v[140:143], v[186:189], v[44:47]
	v_mfma_f32_16x16x32_bf16 v[36:39], v[154:157], v[186:189], v[36:39]
	v_mfma_f32_16x16x32_bf16 v[28:31], v[140:143], v[230:233], v[28:31]
	v_mfma_f32_16x16x32_bf16 v[20:23], v[154:157], v[230:233], v[20:23]
	v_mfma_f32_16x16x32_bf16 v[12:15], v[140:143], v[238:241], v[12:15]
	v_mfma_f32_16x16x32_bf16 v[4:7], v[154:157], v[238:241], v[4:7]
	s_setprio 0
	s_setprio 1
	v_mfma_f32_16x16x32_bf16 v[60:63], v[150:153], v[182:185], v[60:63]
	v_mfma_f32_16x16x32_bf16 v[52:55], v[158:161], v[182:185], v[52:55]
	v_mfma_f32_16x16x32_bf16 v[44:47], v[150:153], v[208:211], v[44:47]
	v_mfma_f32_16x16x32_bf16 v[36:39], v[158:161], v[208:211], v[36:39]
	v_mfma_f32_16x16x32_bf16 v[28:31], v[150:153], v[234:237], v[28:31]
	v_mfma_f32_16x16x32_bf16 v[20:23], v[158:161], v[234:237], v[20:23]
	v_mfma_f32_16x16x32_bf16 v[12:15], v[150:153], v[242:245], v[12:15]
	v_mfma_f32_16x16x32_bf16 v[4:7], v[158:161], v[242:245], v[4:7]
	s_setprio 0
	s_setprio 1
	v_mfma_f32_16x16x32_bf16 v[56:59], v[162:165], v[178:181], v[56:59]
	v_mfma_f32_16x16x32_bf16 v[48:51], v[170:173], v[178:181], v[48:51]
	v_mfma_f32_16x16x32_bf16 v[40:43], v[162:165], v[186:189], v[40:43]
	v_mfma_f32_16x16x32_bf16 v[32:35], v[170:173], v[186:189], v[32:35]
	v_mfma_f32_16x16x32_bf16 v[24:27], v[162:165], v[230:233], v[24:27]
	v_mfma_f32_16x16x32_bf16 v[16:19], v[170:173], v[230:233], v[16:19]
	v_mfma_f32_16x16x32_bf16 v[8:11], v[162:165], v[238:241], v[8:11]
	v_mfma_f32_16x16x32_bf16 v[0:3], v[170:173], v[238:241], v[0:3]
	s_setprio 0
	s_setprio 1
	v_mfma_f32_16x16x32_bf16 v[56:59], v[166:169], v[182:185], v[56:59]
	v_mfma_f32_16x16x32_bf16 v[48:51], v[174:177], v[182:185], v[48:51]
	v_mfma_f32_16x16x32_bf16 v[40:43], v[166:169], v[208:211], v[40:43]
	v_mfma_f32_16x16x32_bf16 v[32:35], v[174:177], v[208:211], v[32:35]
	v_mfma_f32_16x16x32_bf16 v[24:27], v[166:169], v[234:237], v[24:27]
	v_mfma_f32_16x16x32_bf16 v[16:19], v[174:177], v[234:237], v[16:19]
	v_mfma_f32_16x16x32_bf16 v[8:11], v[166:169], v[242:245], v[8:11]
	v_mfma_f32_16x16x32_bf16 v[0:3], v[174:177], v[242:245], v[0:3]
	s_setprio 0
	s_barrier
	s_add_i32 s54, s54, 2
	s_add_u32 s52, s52, 0x100
	s_addc_u32 s53, s53, 0
	s_add_u32 s24, s24, 0x100
	s_addc_u32 s25, s25, 0
	s_cmp_gt_u32 s54, 13
	s_cbranch_scc0 .LBB0_1952
	s_branch .Lpeel_exit_1952
.LBB0_1952:
	s_add_u32 s26, s24, 0xfffc0080
	s_addc_u32 s27, s25, -1
	s_add_i32 s55, 0, 0x10000
	s_cmp_eq_u32 s54, 12
	s_cselect_b32 s29, s5, s27
	s_cselect_b32 s28, s17, s26
	v_add_u32_e32 v144, s55, v146
	s_cselect_b32 s27, s15, s53
	s_cselect_b32 s26, s51, s52
	s_add_i32 s58, 0, 0x14000
	ds_read_b128 v[140:143], v144
	ds_read_b128 v[150:153], v144 offset:1024
	ds_read_b128 v[154:157], v144 offset:2048
	ds_read_b128 v[158:161], v144 offset:3072
	v_add_u32_e32 v144, s58, v146
	ds_read_b128 v[162:165], v144
	ds_read_b128 v[166:169], v144 offset:1024
	ds_read_b128 v[170:173], v144 offset:2048
	ds_read_b128 v[174:177], v144 offset:3072
	s_add_i32 m0, s23, 0xc000
	ds_read_b128 v[178:181], v149
	ds_read_b128 v[182:185], v149 offset:1024
	ds_read_b128 v[186:189], v149 offset:2048
	ds_read_b128 v[208:211], v149 offset:3072
	ds_read_b128 v[230:233], v149 offset:4096
	ds_read_b128 v[234:237], v149 offset:5120
	ds_read_b128 v[238:241], v149 offset:6144
	ds_read_b128 v[242:245], v149 offset:7168
	global_load_lds_dwordx4 v138, s[24:25]
	s_add_i32 m0, s23, 0xe000
	s_nop 0
	global_load_lds_dwordx4 v136, s[24:25]
	s_waitcnt vmcnt(8)
	s_waitcnt lgkmcnt(0)
	s_barrier
	s_setprio 1
	s_waitcnt lgkmcnt(0)
	v_mfma_f32_16x16x32_bf16 v[126:129], v[140:143], v[178:181], v[126:129]
	v_mfma_f32_16x16x32_bf16 v[118:121], v[154:157], v[178:181], v[118:121]
	v_mfma_f32_16x16x32_bf16 v[108:111], v[140:143], v[186:189], v[108:111]
	v_mfma_f32_16x16x32_bf16 v[100:103], v[154:157], v[186:189], v[100:103]
	v_mfma_f32_16x16x32_bf16 v[92:95], v[140:143], v[230:233], v[92:95]
	v_mfma_f32_16x16x32_bf16 v[84:87], v[154:157], v[230:233], v[84:87]
	v_mfma_f32_16x16x32_bf16 v[76:79], v[140:143], v[238:241], v[76:79]
	v_mfma_f32_16x16x32_bf16 v[68:71], v[154:157], v[238:241], v[68:71]
	s_setprio 0
	s_setprio 1
	v_mfma_f32_16x16x32_bf16 v[126:129], v[150:153], v[182:185], v[126:129]
	v_mfma_f32_16x16x32_bf16 v[118:121], v[158:161], v[182:185], v[118:121]
	v_mfma_f32_16x16x32_bf16 v[108:111], v[150:153], v[208:211], v[108:111]
	v_mfma_f32_16x16x32_bf16 v[100:103], v[158:161], v[208:211], v[100:103]
	v_mfma_f32_16x16x32_bf16 v[92:95], v[150:153], v[234:237], v[92:95]
	v_mfma_f32_16x16x32_bf16 v[84:87], v[158:161], v[234:237], v[84:87]
	v_mfma_f32_16x16x32_bf16 v[76:79], v[150:153], v[242:245], v[76:79]
	v_mfma_f32_16x16x32_bf16 v[68:71], v[158:161], v[242:245], v[68:71]
	s_setprio 0
	s_setprio 1
	v_mfma_f32_16x16x32_bf16 v[122:125], v[162:165], v[178:181], v[122:125]
	v_mfma_f32_16x16x32_bf16 v[114:117], v[170:173], v[178:181], v[114:117]
	v_mfma_f32_16x16x32_bf16 v[104:107], v[162:165], v[186:189], v[104:107]
	v_mfma_f32_16x16x32_bf16 v[96:99], v[170:173], v[186:189], v[96:99]
	v_mfma_f32_16x16x32_bf16 v[88:91], v[162:165], v[230:233], v[88:91]
	v_mfma_f32_16x16x32_bf16 v[80:83], v[170:173], v[230:233], v[80:83]
	v_mfma_f32_16x16x32_bf16 v[72:75], v[162:165], v[238:241], v[72:75]
	v_mfma_f32_16x16x32_bf16 v[64:67], v[170:173], v[238:241], v[64:67]
	s_setprio 0
	s_setprio 1
	v_mfma_f32_16x16x32_bf16 v[122:125], v[166:169], v[182:185], v[122:125]
	v_mfma_f32_16x16x32_bf16 v[114:117], v[174:177], v[182:185], v[114:117]
	v_mfma_f32_16x16x32_bf16 v[104:107], v[166:169], v[208:211], v[104:107]
	v_mfma_f32_16x16x32_bf16 v[96:99], v[174:177], v[208:211], v[96:99]
	v_mfma_f32_16x16x32_bf16 v[88:91], v[166:169], v[234:237], v[88:91]
	v_mfma_f32_16x16x32_bf16 v[80:83], v[174:177], v[234:237], v[80:83]
	v_mfma_f32_16x16x32_bf16 v[72:75], v[166:169], v[242:245], v[72:75]
	v_mfma_f32_16x16x32_bf16 v[64:67], v[174:177], v[242:245], v[64:67]
	s_setprio 0
	s_barrier
	s_add_i32 s55, s55, s35
	s_mov_b32 m0, s55
	ds_read_b128 v[178:181], v149 offset:16384
	ds_read_b128 v[182:185], v149 offset:17408
	ds_read_b128 v[186:189], v149 offset:18432
	ds_read_b128 v[208:211], v149 offset:19456
	ds_read_b128 v[230:233], v149 offset:20480
	ds_read_b128 v[234:237], v149 offset:21504
	ds_read_b128 v[238:241], v149 offset:22528
	ds_read_b128 v[242:245], v149 offset:23552
	global_load_lds_dwordx4 v112, s[26:27]
	s_add_i32 m0, s55, 0x2000
	s_add_u32 s56, s26, 0x40000
	v_lshl_add_u64 v[246:247], s[26:27], 0, v[134:135]
	s_addc_u32 s57, s27, 0
	s_add_i32 s55, s58, s35
	global_load_lds_dwordx4 v134, s[26:27]
	s_mov_b32 m0, s55
	v_lshl_add_u64 v[250:251], s[28:29], 0, v[132:133]
	global_load_lds_dwordx4 v112, s[56:57]
	s_add_i32 m0, s55, 0x2000
	s_nop 0
	global_load_lds_dwordx4 v134, s[56:57]
	v_lshl_add_u64 v[248:249], s[28:29], 0, v[130:131]
	s_mov_b32 m0, s23
	s_nop 0
	global_load_lds_dwordx4 v130, s[28:29]
	s_mov_b32 m0, s44
	s_nop 0
	global_load_lds_dwordx4 v132, s[28:29]
	s_waitcnt vmcnt(8)
	s_waitcnt lgkmcnt(0)
	s_barrier
	s_setprio 1
	s_waitcnt lgkmcnt(0)
	v_mfma_f32_16x16x32_bf16 v[60:63], v[140:143], v[178:181], v[60:63]
	v_mfma_f32_16x16x32_bf16 v[52:55], v[154:157], v[178:181], v[52:55]
	v_mfma_f32_16x16x32_bf16 v[44:47], v[140:143], v[186:189], v[44:47]
	v_mfma_f32_16x16x32_bf16 v[36:39], v[154:157], v[186:189], v[36:39]
	v_mfma_f32_16x16x32_bf16 v[28:31], v[140:143], v[230:233], v[28:31]
	v_mfma_f32_16x16x32_bf16 v[20:23], v[154:157], v[230:233], v[20:23]
	v_mfma_f32_16x16x32_bf16 v[12:15], v[140:143], v[238:241], v[12:15]
	v_mfma_f32_16x16x32_bf16 v[4:7], v[154:157], v[238:241], v[4:7]
	s_setprio 0
	s_setprio 1
	v_mfma_f32_16x16x32_bf16 v[60:63], v[150:153], v[182:185], v[60:63]
	v_mfma_f32_16x16x32_bf16 v[52:55], v[158:161], v[182:185], v[52:55]
	v_mfma_f32_16x16x32_bf16 v[44:47], v[150:153], v[208:211], v[44:47]
	v_mfma_f32_16x16x32_bf16 v[36:39], v[158:161], v[208:211], v[36:39]
	v_mfma_f32_16x16x32_bf16 v[28:31], v[150:153], v[234:237], v[28:31]
	v_mfma_f32_16x16x32_bf16 v[20:23], v[158:161], v[234:237], v[20:23]
	v_mfma_f32_16x16x32_bf16 v[12:15], v[150:153], v[242:245], v[12:15]
	v_mfma_f32_16x16x32_bf16 v[4:7], v[158:161], v[242:245], v[4:7]
	s_setprio 0
	s_setprio 1
	v_mfma_f32_16x16x32_bf16 v[56:59], v[162:165], v[178:181], v[56:59]
	v_mfma_f32_16x16x32_bf16 v[48:51], v[170:173], v[178:181], v[48:51]
	v_mfma_f32_16x16x32_bf16 v[40:43], v[162:165], v[186:189], v[40:43]
	v_mfma_f32_16x16x32_bf16 v[32:35], v[170:173], v[186:189], v[32:35]
	v_mfma_f32_16x16x32_bf16 v[24:27], v[162:165], v[230:233], v[24:27]
	v_mfma_f32_16x16x32_bf16 v[16:19], v[170:173], v[230:233], v[16:19]
	v_mfma_f32_16x16x32_bf16 v[8:11], v[162:165], v[238:241], v[8:11]
	v_mfma_f32_16x16x32_bf16 v[0:3], v[170:173], v[238:241], v[0:3]
	s_setprio 0
	s_setprio 1
	v_mfma_f32_16x16x32_bf16 v[56:59], v[166:169], v[182:185], v[56:59]
	v_mfma_f32_16x16x32_bf16 v[48:51], v[174:177], v[182:185], v[48:51]
	v_mfma_f32_16x16x32_bf16 v[40:43], v[166:169], v[208:211], v[40:43]
	v_mfma_f32_16x16x32_bf16 v[32:35], v[174:177], v[208:211], v[32:35]
	v_mfma_f32_16x16x32_bf16 v[24:27], v[166:169], v[234:237], v[24:27]
	v_mfma_f32_16x16x32_bf16 v[16:19], v[174:177], v[234:237], v[16:19]
	v_mfma_f32_16x16x32_bf16 v[8:11], v[166:169], v[242:245], v[8:11]
	v_mfma_f32_16x16x32_bf16 v[0:3], v[174:177], v[242:245], v[0:3]
	s_setprio 0
	s_barrier
	s_add_i32 s55, 0, 0x18000
	v_add_u32_e32 v144, s55, v146
	s_add_i32 s56, 0, 0x1c000
	ds_read_b128 v[140:143], v144
	ds_read_b128 v[150:153], v144 offset:1024
	ds_read_b128 v[154:157], v144 offset:2048
	ds_read_b128 v[158:161], v144 offset:3072
	v_add_u32_e32 v144, s56, v146
	ds_read_b128 v[162:165], v144
	ds_read_b128 v[166:169], v144 offset:1024
	ds_read_b128 v[170:173], v144 offset:2048
	ds_read_b128 v[174:177], v144 offset:3072
	s_add_u32 s28, s28, 0x40000
	s_addc_u32 s29, s29, 0
	s_mov_b32 m0, s45
	ds_read_b128 v[178:181], v149 offset:32768
	ds_read_b128 v[182:185], v149 offset:33792
	ds_read_b128 v[186:189], v149 offset:34816
	ds_read_b128 v[208:211], v149 offset:35840
	ds_read_b128 v[230:233], v149 offset:36864
	ds_read_b128 v[234:237], v149 offset:37888
	ds_read_b128 v[238:241], v149 offset:38912
	ds_read_b128 v[242:245], v149 offset:39936
	global_load_lds_dwordx4 v130, s[28:29]
	s_mov_b32 m0, s46
	s_nop 0
	global_load_lds_dwordx4 v132, s[28:29]
	s_waitcnt vmcnt(8)
	s_waitcnt lgkmcnt(0)
	s_barrier
	s_setprio 1
	s_waitcnt lgkmcnt(0)
	v_mfma_f32_16x16x32_bf16 v[126:129], v[140:143], v[178:181], v[126:129]
	v_mfma_f32_16x16x32_bf16 v[118:121], v[154:157], v[178:181], v[118:121]
	v_mfma_f32_16x16x32_bf16 v[108:111], v[140:143], v[186:189], v[108:111]
	v_mfma_f32_16x16x32_bf16 v[100:103], v[154:157], v[186:189], v[100:103]
	v_mfma_f32_16x16x32_bf16 v[92:95], v[140:143], v[230:233], v[92:95]
	v_mfma_f32_16x16x32_bf16 v[84:87], v[154:157], v[230:233], v[84:87]
	v_mfma_f32_16x16x32_bf16 v[76:79], v[140:143], v[238:241], v[76:79]
	v_mfma_f32_16x16x32_bf16 v[68:71], v[154:157], v[238:241], v[68:71]
	s_setprio 0
	s_setprio 1
	v_mfma_f32_16x16x32_bf16 v[126:129], v[150:153], v[182:185], v[126:129]
	v_mfma_f32_16x16x32_bf16 v[118:121], v[158:161], v[182:185], v[118:121]
	v_mfma_f32_16x16x32_bf16 v[108:111], v[150:153], v[208:211], v[108:111]
	v_mfma_f32_16x16x32_bf16 v[100:103], v[158:161], v[208:211], v[100:103]
	v_mfma_f32_16x16x32_bf16 v[92:95], v[150:153], v[234:237], v[92:95]
	v_mfma_f32_16x16x32_bf16 v[84:87], v[158:161], v[234:237], v[84:87]
	v_mfma_f32_16x16x32_bf16 v[76:79], v[150:153], v[242:245], v[76:79]
	v_mfma_f32_16x16x32_bf16 v[68:71], v[158:161], v[242:245], v[68:71]
	s_setprio 0
	s_setprio 1
	v_mfma_f32_16x16x32_bf16 v[122:125], v[162:165], v[178:181], v[122:125]
	v_mfma_f32_16x16x32_bf16 v[114:117], v[170:173], v[178:181], v[114:117]
	v_mfma_f32_16x16x32_bf16 v[104:107], v[162:165], v[186:189], v[104:107]
	v_mfma_f32_16x16x32_bf16 v[96:99], v[170:173], v[186:189], v[96:99]
	v_mfma_f32_16x16x32_bf16 v[88:91], v[162:165], v[230:233], v[88:91]
	v_mfma_f32_16x16x32_bf16 v[80:83], v[170:173], v[230:233], v[80:83]
	v_mfma_f32_16x16x32_bf16 v[72:75], v[162:165], v[238:241], v[72:75]
	v_mfma_f32_16x16x32_bf16 v[64:67], v[170:173], v[238:241], v[64:67]
	s_setprio 0
	s_setprio 1
	v_mfma_f32_16x16x32_bf16 v[122:125], v[166:169], v[182:185], v[122:125]
	v_mfma_f32_16x16x32_bf16 v[114:117], v[174:177], v[182:185], v[114:117]
	v_mfma_f32_16x16x32_bf16 v[104:107], v[166:169], v[208:211], v[104:107]
	v_mfma_f32_16x16x32_bf16 v[96:99], v[174:177], v[208:211], v[96:99]
	v_mfma_f32_16x16x32_bf16 v[88:91], v[166:169], v[234:237], v[88:91]
	v_mfma_f32_16x16x32_bf16 v[80:83], v[174:177], v[234:237], v[80:83]
	v_mfma_f32_16x16x32_bf16 v[72:75], v[166:169], v[242:245], v[72:75]
	v_mfma_f32_16x16x32_bf16 v[64:67], v[174:177], v[242:245], v[64:67]
	s_setprio 0
	s_barrier
	s_add_i32 s28, s55, s35
	s_mov_b32 m0, s28
	ds_read_b128 v[178:181], v149 offset:49152
	ds_read_b128 v[182:185], v149 offset:50176
	ds_read_b128 v[186:189], v149 offset:51200
	ds_read_b128 v[208:211], v149 offset:52224
	ds_read_b128 v[230:233], v149 offset:53248
	ds_read_b128 v[234:237], v149 offset:54272
	ds_read_b128 v[238:241], v149 offset:55296
	ds_read_b128 v[242:245], v149 offset:56320
	s_add_u32 s98, s26, 0x80
	s_addc_u32 s99, s27, 0
	global_load_lds_dwordx4 v112, s[98:99]
	s_add_i32 m0, s28, 0x2000
	s_add_u32 s26, s26, 0x40080
	v_lshl_add_u64 v[212:213], v[246:247], 0, s[96:97]
	s_addc_u32 s27, s27, 0
	s_add_i32 s28, s56, s35
	global_load_lds_dwordx4 v[212:213], off
	s_mov_b32 m0, s28
	s_nop 0
	global_load_lds_dwordx4 v112, s[26:27]
	s_add_i32 m0, s28, 0x2000
	s_nop 0
	global_load_lds_dwordx4 v134, s[26:27]
	v_lshl_add_u64 v[212:213], v[248:249], 0, s[96:97]
	s_mov_b32 m0, s47
	s_nop 0
	global_load_lds_dwordx4 v[212:213], off
	v_lshl_add_u64 v[212:213], v[250:251], 0, s[96:97]
	s_mov_b32 m0, s48
	s_nop 0
	global_load_lds_dwordx4 v[212:213], off
	s_waitcnt vmcnt(8)
	s_waitcnt lgkmcnt(0)
	s_barrier
	s_setprio 1
	s_waitcnt lgkmcnt(0)
	v_mfma_f32_16x16x32_bf16 v[60:63], v[140:143], v[178:181], v[60:63]
	v_mfma_f32_16x16x32_bf16 v[52:55], v[154:157], v[178:181], v[52:55]
	v_mfma_f32_16x16x32_bf16 v[44:47], v[140:143], v[186:189], v[44:47]
	v_mfma_f32_16x16x32_bf16 v[36:39], v[154:157], v[186:189], v[36:39]
	v_mfma_f32_16x16x32_bf16 v[28:31], v[140:143], v[230:233], v[28:31]
	v_mfma_f32_16x16x32_bf16 v[20:23], v[154:157], v[230:233], v[20:23]
	v_mfma_f32_16x16x32_bf16 v[12:15], v[140:143], v[238:241], v[12:15]
	v_mfma_f32_16x16x32_bf16 v[4:7], v[154:157], v[238:241], v[4:7]
	s_setprio 0
	s_setprio 1
	v_mfma_f32_16x16x32_bf16 v[60:63], v[150:153], v[182:185], v[60:63]
	v_mfma_f32_16x16x32_bf16 v[52:55], v[158:161], v[182:185], v[52:55]
	v_mfma_f32_16x16x32_bf16 v[44:47], v[150:153], v[208:211], v[44:47]
	v_mfma_f32_16x16x32_bf16 v[36:39], v[158:161], v[208:211], v[36:39]
	v_mfma_f32_16x16x32_bf16 v[28:31], v[150:153], v[234:237], v[28:31]
	v_mfma_f32_16x16x32_bf16 v[20:23], v[158:161], v[234:237], v[20:23]
	v_mfma_f32_16x16x32_bf16 v[12:15], v[150:153], v[242:245], v[12:15]
	v_mfma_f32_16x16x32_bf16 v[4:7], v[158:161], v[242:245], v[4:7]
	s_setprio 0
	s_setprio 1
	v_mfma_f32_16x16x32_bf16 v[56:59], v[162:165], v[178:181], v[56:59]
	v_mfma_f32_16x16x32_bf16 v[48:51], v[170:173], v[178:181], v[48:51]
	v_mfma_f32_16x16x32_bf16 v[40:43], v[162:165], v[186:189], v[40:43]
	v_mfma_f32_16x16x32_bf16 v[32:35], v[170:173], v[186:189], v[32:35]
	v_mfma_f32_16x16x32_bf16 v[24:27], v[162:165], v[230:233], v[24:27]
	v_mfma_f32_16x16x32_bf16 v[16:19], v[170:173], v[230:233], v[16:19]
	v_mfma_f32_16x16x32_bf16 v[8:11], v[162:165], v[238:241], v[8:11]
	v_mfma_f32_16x16x32_bf16 v[0:3], v[170:173], v[238:241], v[0:3]
	s_setprio 0
	s_setprio 1
	v_mfma_f32_16x16x32_bf16 v[56:59], v[166:169], v[182:185], v[56:59]
	v_mfma_f32_16x16x32_bf16 v[48:51], v[174:177], v[182:185], v[48:51]
	v_mfma_f32_16x16x32_bf16 v[40:43], v[166:169], v[208:211], v[40:43]
	v_mfma_f32_16x16x32_bf16 v[32:35], v[174:177], v[208:211], v[32:35]
	v_mfma_f32_16x16x32_bf16 v[24:27], v[166:169], v[234:237], v[24:27]
	v_mfma_f32_16x16x32_bf16 v[16:19], v[174:177], v[234:237], v[16:19]
	v_mfma_f32_16x16x32_bf16 v[8:11], v[166:169], v[242:245], v[8:11]
	v_mfma_f32_16x16x32_bf16 v[0:3], v[174:177], v[242:245], v[0:3]
	s_setprio 0
	s_barrier
	s_add_i32 s54, s54, 2
	s_add_u32 s52, s52, 0x100
	s_addc_u32 s53, s53, 0
	s_add_u32 s24, s24, 0x100
	s_addc_u32 s25, s25, 0
	s_cmp_gt_u32 s54, 13
	s_cbranch_scc0 .LBB0_1952

.LBB0_2150:
	s_ashr_i32 s29, s28, 31
	s_lshl_b64 s[30:31], s[28:29], 19
	s_add_u32 s30, s49, s30
	s_addc_u32 s31, s50, s31
	s_and_b64 s[40:41], s[6:7], exec
	s_cselect_b32 s11, s31, s39
	s_cselect_b32 s29, s30, s38
	s_ashr_i32 s27, s26, 31
	s_lshl_b64 s[40:41], s[26:27], 19
	s_add_u32 s46, s51, s40
	s_addc_u32 s47, s52, s41
	s_and_b64 s[40:41], s[6:7], exec
	s_cselect_b32 s27, s47, s9
	s_cselect_b32 s35, s46, s8
	s_add_u32 s42, s8, 0x100
	s_addc_u32 s43, s9, 0
	s_add_u32 s8, s38, 0x40080
	s_addc_u32 s9, s39, 0
	s_mov_b32 s44, -2
	s_add_u32 s38, s8, 0xfffc0080
	s_addc_u32 s39, s9, -1
	s_add_i32 s45, 0, 0x10000
	s_cmp_eq_u32 s44, 12
	s_cselect_b32 s41, s11, s39
	s_cselect_b32 s40, s29, s38
	v_add_u32_e32 v112, s45, v169
	s_cselect_b32 s39, s27, s43
	s_cselect_b32 s38, s35, s42
	s_add_i32 s68, 0, 0x14000
	ds_read_b128 v[130:133], v112
	ds_read_b128 v[134:137], v112 offset:1024
	ds_read_b128 v[150:153], v112 offset:2048
	ds_read_b128 v[154:157], v112 offset:3072
	v_add_u32_e32 v112, s68, v169
	ds_read_b128 v[158:161], v112
	ds_read_b128 v[162:165], v112 offset:1024
	ds_read_b128 v[174:177], v112 offset:2048
	ds_read_b128 v[178:181], v112 offset:3072
	s_add_i32 m0, s37, 0xc000
	ds_read_b128 v[182:185], v172
	ds_read_b128 v[186:189], v172 offset:1024
	ds_read_b128 v[208:211], v172 offset:2048
	ds_read_b128 v[230:233], v172 offset:3072
	ds_read_b128 v[234:237], v172 offset:4096
	ds_read_b128 v[238:241], v172 offset:5120
	ds_read_b128 v[242:245], v172 offset:6144
	ds_read_b128 v[246:249], v172 offset:7168
	global_load_lds_dwordx4 v148, s[8:9]
	s_add_i32 m0, s37, 0xe000
	s_nop 0
	global_load_lds_dwordx4 v146, s[8:9]
	s_waitcnt vmcnt(8)
	s_waitcnt lgkmcnt(0)
	s_barrier
	s_setprio 1
	s_waitcnt lgkmcnt(0)
	v_mfma_f32_16x16x32_bf16 v[126:129], v[130:133], v[182:185], 0
	v_mfma_f32_16x16x32_bf16 v[122:125], v[150:153], v[182:185], 0
	v_mfma_f32_16x16x32_bf16 v[108:111], v[130:133], v[208:211], 0
	v_mfma_f32_16x16x32_bf16 v[104:107], v[150:153], v[208:211], 0
	v_mfma_f32_16x16x32_bf16 v[92:95], v[130:133], v[234:237], 0
	v_mfma_f32_16x16x32_bf16 v[88:91], v[150:153], v[234:237], 0
	v_mfma_f32_16x16x32_bf16 v[76:79], v[130:133], v[242:245], 0
	v_mfma_f32_16x16x32_bf16 v[72:75], v[150:153], v[242:245], 0
	s_setprio 0
	s_setprio 1
	v_mfma_f32_16x16x32_bf16 v[126:129], v[134:137], v[186:189], v[126:129]
	v_mfma_f32_16x16x32_bf16 v[122:125], v[154:157], v[186:189], v[122:125]
	v_mfma_f32_16x16x32_bf16 v[108:111], v[134:137], v[230:233], v[108:111]
	v_mfma_f32_16x16x32_bf16 v[104:107], v[154:157], v[230:233], v[104:107]
	v_mfma_f32_16x16x32_bf16 v[92:95], v[134:137], v[238:241], v[92:95]
	v_mfma_f32_16x16x32_bf16 v[88:91], v[154:157], v[238:241], v[88:91]
	v_mfma_f32_16x16x32_bf16 v[76:79], v[134:137], v[246:249], v[76:79]
	v_mfma_f32_16x16x32_bf16 v[72:75], v[154:157], v[246:249], v[72:75]
	s_setprio 0
	s_setprio 1
	v_mfma_f32_16x16x32_bf16 v[118:121], v[158:161], v[182:185], 0
	v_mfma_f32_16x16x32_bf16 v[114:117], v[174:177], v[182:185], 0
	v_mfma_f32_16x16x32_bf16 v[100:103], v[158:161], v[208:211], 0
	v_mfma_f32_16x16x32_bf16 v[96:99], v[174:177], v[208:211], 0
	v_mfma_f32_16x16x32_bf16 v[84:87], v[158:161], v[234:237], 0
	v_mfma_f32_16x16x32_bf16 v[80:83], v[174:177], v[234:237], 0
	v_mfma_f32_16x16x32_bf16 v[68:71], v[158:161], v[242:245], 0
	v_mfma_f32_16x16x32_bf16 v[64:67], v[174:177], v[242:245], 0
	s_setprio 0
	s_setprio 1
	v_mfma_f32_16x16x32_bf16 v[118:121], v[162:165], v[186:189], v[118:121]
	v_mfma_f32_16x16x32_bf16 v[114:117], v[178:181], v[186:189], v[114:117]
	v_mfma_f32_16x16x32_bf16 v[100:103], v[162:165], v[230:233], v[100:103]
	v_mfma_f32_16x16x32_bf16 v[96:99], v[178:181], v[230:233], v[96:99]
	v_mfma_f32_16x16x32_bf16 v[84:87], v[162:165], v[238:241], v[84:87]
	v_mfma_f32_16x16x32_bf16 v[80:83], v[178:181], v[238:241], v[80:83]
	v_mfma_f32_16x16x32_bf16 v[68:71], v[162:165], v[246:249], v[68:71]
	v_mfma_f32_16x16x32_bf16 v[64:67], v[178:181], v[246:249], v[64:67]
	s_setprio 0
	s_barrier
	s_add_i32 s45, s45, s58
	s_mov_b32 m0, s45
	ds_read_b128 v[182:185], v172 offset:16384
	ds_read_b128 v[186:189], v172 offset:17408
	ds_read_b128 v[208:211], v172 offset:18432
	ds_read_b128 v[230:233], v172 offset:19456
	ds_read_b128 v[234:237], v172 offset:20480
	ds_read_b128 v[238:241], v172 offset:21504
	ds_read_b128 v[242:245], v172 offset:22528
	ds_read_b128 v[246:249], v172 offset:23552
	global_load_lds_dwordx4 v140, s[38:39]
	s_add_i32 m0, s45, 0x2000
	s_add_u32 s66, s38, 0x40000
	v_lshl_add_u64 v[212:213], s[38:39], 0, v[144:145]
	s_addc_u32 s67, s39, 0
	s_add_i32 s45, s68, s58
	global_load_lds_dwordx4 v144, s[38:39]
	s_mov_b32 m0, s45
	v_lshl_add_u64 v[250:251], s[40:41], 0, v[142:143]
	global_load_lds_dwordx4 v140, s[66:67]
	s_add_i32 m0, s45, 0x2000
	s_nop 0
	global_load_lds_dwordx4 v144, s[66:67]
	v_lshl_add_u64 v[228:229], s[40:41], 0, v[138:139]
	s_mov_b32 m0, s37
	s_nop 0
	global_load_lds_dwordx4 v138, s[40:41]
	s_mov_b32 m0, s59
	s_nop 0
	global_load_lds_dwordx4 v142, s[40:41]
	s_waitcnt vmcnt(8)
	s_waitcnt lgkmcnt(0)
	s_barrier
	s_setprio 1
	s_waitcnt lgkmcnt(0)
	v_mfma_f32_16x16x32_bf16 v[60:63], v[130:133], v[182:185], 0
	v_mfma_f32_16x16x32_bf16 v[56:59], v[150:153], v[182:185], 0
	v_mfma_f32_16x16x32_bf16 v[44:47], v[130:133], v[208:211], 0
	v_mfma_f32_16x16x32_bf16 v[40:43], v[150:153], v[208:211], 0
	v_mfma_f32_16x16x32_bf16 v[28:31], v[130:133], v[234:237], 0
	v_mfma_f32_16x16x32_bf16 v[24:27], v[150:153], v[234:237], 0
	v_mfma_f32_16x16x32_bf16 v[12:15], v[130:133], v[242:245], 0
	v_mfma_f32_16x16x32_bf16 v[8:11], v[150:153], v[242:245], 0
	s_setprio 0
	s_setprio 1
	v_mfma_f32_16x16x32_bf16 v[60:63], v[134:137], v[186:189], v[60:63]
	v_mfma_f32_16x16x32_bf16 v[56:59], v[154:157], v[186:189], v[56:59]
	v_mfma_f32_16x16x32_bf16 v[44:47], v[134:137], v[230:233], v[44:47]
	v_mfma_f32_16x16x32_bf16 v[40:43], v[154:157], v[230:233], v[40:43]
	v_mfma_f32_16x16x32_bf16 v[28:31], v[134:137], v[238:241], v[28:31]
	v_mfma_f32_16x16x32_bf16 v[24:27], v[154:157], v[238:241], v[24:27]
	v_mfma_f32_16x16x32_bf16 v[12:15], v[134:137], v[246:249], v[12:15]
	v_mfma_f32_16x16x32_bf16 v[8:11], v[154:157], v[246:249], v[8:11]
	s_setprio 0
	s_setprio 1
	v_mfma_f32_16x16x32_bf16 v[52:55], v[158:161], v[182:185], 0
	v_mfma_f32_16x16x32_bf16 v[48:51], v[174:177], v[182:185], 0
	v_mfma_f32_16x16x32_bf16 v[36:39], v[158:161], v[208:211], 0
	v_mfma_f32_16x16x32_bf16 v[32:35], v[174:177], v[208:211], 0
	v_mfma_f32_16x16x32_bf16 v[20:23], v[158:161], v[234:237], 0
	v_mfma_f32_16x16x32_bf16 v[16:19], v[174:177], v[234:237], 0
	v_mfma_f32_16x16x32_bf16 v[4:7], v[158:161], v[242:245], 0
	v_mfma_f32_16x16x32_bf16 v[0:3], v[174:177], v[242:245], 0
	s_setprio 0
	s_setprio 1
	v_mfma_f32_16x16x32_bf16 v[52:55], v[162:165], v[186:189], v[52:55]
	v_mfma_f32_16x16x32_bf16 v[48:51], v[178:181], v[186:189], v[48:51]
	v_mfma_f32_16x16x32_bf16 v[36:39], v[162:165], v[230:233], v[36:39]
	v_mfma_f32_16x16x32_bf16 v[32:35], v[178:181], v[230:233], v[32:35]
	v_mfma_f32_16x16x32_bf16 v[20:23], v[162:165], v[238:241], v[20:23]
	v_mfma_f32_16x16x32_bf16 v[16:19], v[178:181], v[238:241], v[16:19]
	v_mfma_f32_16x16x32_bf16 v[4:7], v[162:165], v[246:249], v[4:7]
	v_mfma_f32_16x16x32_bf16 v[0:3], v[178:181], v[246:249], v[0:3]
	s_setprio 0
	s_barrier
	s_add_i32 s45, 0, 0x18000
	v_add_u32_e32 v112, s45, v169
	s_add_i32 s66, 0, 0x1c000
	ds_read_b128 v[130:133], v112
	ds_read_b128 v[134:137], v112 offset:1024
	ds_read_b128 v[150:153], v112 offset:2048
	ds_read_b128 v[154:157], v112 offset:3072
	v_add_u32_e32 v112, s66, v169
	ds_read_b128 v[158:161], v112
	ds_read_b128 v[162:165], v112 offset:1024
	ds_read_b128 v[174:177], v112 offset:2048
	ds_read_b128 v[178:181], v112 offset:3072
	s_add_u32 s40, s40, 0x40000
	s_addc_u32 s41, s41, 0
	s_mov_b32 m0, s60
	ds_read_b128 v[182:185], v172 offset:32768
	ds_read_b128 v[186:189], v172 offset:33792
	ds_read_b128 v[208:211], v172 offset:34816
	ds_read_b128 v[230:233], v172 offset:35840
	ds_read_b128 v[234:237], v172 offset:36864
	ds_read_b128 v[238:241], v172 offset:37888
	ds_read_b128 v[242:245], v172 offset:38912
	ds_read_b128 v[246:249], v172 offset:39936
	global_load_lds_dwordx4 v138, s[40:41]
	s_mov_b32 m0, s61
	s_nop 0
	global_load_lds_dwordx4 v142, s[40:41]
	s_waitcnt vmcnt(8)
	s_waitcnt lgkmcnt(0)
	s_barrier
	s_setprio 1
	s_waitcnt lgkmcnt(0)
	v_mfma_f32_16x16x32_bf16 v[126:129], v[130:133], v[182:185], v[126:129]
	v_mfma_f32_16x16x32_bf16 v[122:125], v[150:153], v[182:185], v[122:125]
	v_mfma_f32_16x16x32_bf16 v[108:111], v[130:133], v[208:211], v[108:111]
	v_mfma_f32_16x16x32_bf16 v[104:107], v[150:153], v[208:211], v[104:107]
	v_mfma_f32_16x16x32_bf16 v[92:95], v[130:133], v[234:237], v[92:95]
	v_mfma_f32_16x16x32_bf16 v[88:91], v[150:153], v[234:237], v[88:91]
	v_mfma_f32_16x16x32_bf16 v[76:79], v[130:133], v[242:245], v[76:79]
	v_mfma_f32_16x16x32_bf16 v[72:75], v[150:153], v[242:245], v[72:75]
	s_setprio 0
	s_setprio 1
	v_mfma_f32_16x16x32_bf16 v[126:129], v[134:137], v[186:189], v[126:129]
	v_mfma_f32_16x16x32_bf16 v[122:125], v[154:157], v[186:189], v[122:125]
	v_mfma_f32_16x16x32_bf16 v[108:111], v[134:137], v[230:233], v[108:111]
	v_mfma_f32_16x16x32_bf16 v[104:107], v[154:157], v[230:233], v[104:107]
	v_mfma_f32_16x16x32_bf16 v[92:95], v[134:137], v[238:241], v[92:95]
	v_mfma_f32_16x16x32_bf16 v[88:91], v[154:157], v[238:241], v[88:91]
	v_mfma_f32_16x16x32_bf16 v[76:79], v[134:137], v[246:249], v[76:79]
	v_mfma_f32_16x16x32_bf16 v[72:75], v[154:157], v[246:249], v[72:75]
	s_setprio 0
	s_setprio 1
	v_mfma_f32_16x16x32_bf16 v[118:121], v[158:161], v[182:185], v[118:121]
	v_mfma_f32_16x16x32_bf16 v[114:117], v[174:177], v[182:185], v[114:117]
	v_mfma_f32_16x16x32_bf16 v[100:103], v[158:161], v[208:211], v[100:103]
	v_mfma_f32_16x16x32_bf16 v[96:99], v[174:177], v[208:211], v[96:99]
	v_mfma_f32_16x16x32_bf16 v[84:87], v[158:161], v[234:237], v[84:87]
	v_mfma_f32_16x16x32_bf16 v[80:83], v[174:177], v[234:237], v[80:83]
	v_mfma_f32_16x16x32_bf16 v[68:71], v[158:161], v[242:245], v[68:71]
	v_mfma_f32_16x16x32_bf16 v[64:67], v[174:177], v[242:245], v[64:67]
	s_setprio 0
	s_setprio 1
	v_mfma_f32_16x16x32_bf16 v[118:121], v[162:165], v[186:189], v[118:121]
	v_mfma_f32_16x16x32_bf16 v[114:117], v[178:181], v[186:189], v[114:117]
	v_mfma_f32_16x16x32_bf16 v[100:103], v[162:165], v[230:233], v[100:103]
	v_mfma_f32_16x16x32_bf16 v[96:99], v[178:181], v[230:233], v[96:99]
	v_mfma_f32_16x16x32_bf16 v[84:87], v[162:165], v[238:241], v[84:87]
	v_mfma_f32_16x16x32_bf16 v[80:83], v[178:181], v[238:241], v[80:83]
	v_mfma_f32_16x16x32_bf16 v[68:71], v[162:165], v[246:249], v[68:71]
	v_mfma_f32_16x16x32_bf16 v[64:67], v[178:181], v[246:249], v[64:67]
	s_setprio 0
	s_barrier
	s_add_i32 s40, s45, s58
	s_mov_b32 m0, s40
	ds_read_b128 v[182:185], v172 offset:49152
	ds_read_b128 v[186:189], v172 offset:50176
	ds_read_b128 v[208:211], v172 offset:51200
	ds_read_b128 v[230:233], v172 offset:52224
	ds_read_b128 v[234:237], v172 offset:53248
	ds_read_b128 v[238:241], v172 offset:54272
	ds_read_b128 v[242:245], v172 offset:55296
	ds_read_b128 v[246:249], v172 offset:56320
	s_add_u32 s98, s38, 0x80
	s_addc_u32 s99, s39, 0
	global_load_lds_dwordx4 v140, s[98:99]
	s_add_i32 m0, s40, 0x2000
	s_add_u32 s38, s38, 0x40080
	v_lshl_add_u64 v[166:167], v[212:213], 0, s[96:97]
	s_addc_u32 s39, s39, 0
	s_add_i32 s40, s66, s58
	global_load_lds_dwordx4 v[166:167], off
	s_mov_b32 m0, s40
	s_nop 0
	global_load_lds_dwordx4 v140, s[38:39]
	s_add_i32 m0, s40, 0x2000
	s_nop 0
	global_load_lds_dwordx4 v144, s[38:39]
	v_lshl_add_u64 v[166:167], v[228:229], 0, s[96:97]
	s_mov_b32 m0, s62
	s_nop 0
	global_load_lds_dwordx4 v[166:167], off
	v_lshl_add_u64 v[166:167], v[250:251], 0, s[96:97]
	s_mov_b32 m0, s63
	s_nop 0
	global_load_lds_dwordx4 v[166:167], off
	s_waitcnt vmcnt(8)
	s_waitcnt lgkmcnt(0)
	s_barrier
	s_setprio 1
	s_waitcnt lgkmcnt(0)
	v_mfma_f32_16x16x32_bf16 v[60:63], v[130:133], v[182:185], v[60:63]
	v_mfma_f32_16x16x32_bf16 v[56:59], v[150:153], v[182:185], v[56:59]
	v_mfma_f32_16x16x32_bf16 v[44:47], v[130:133], v[208:211], v[44:47]
	v_mfma_f32_16x16x32_bf16 v[40:43], v[150:153], v[208:211], v[40:43]
	v_mfma_f32_16x16x32_bf16 v[28:31], v[130:133], v[234:237], v[28:31]
	v_mfma_f32_16x16x32_bf16 v[24:27], v[150:153], v[234:237], v[24:27]
	v_mfma_f32_16x16x32_bf16 v[12:15], v[130:133], v[242:245], v[12:15]
	v_mfma_f32_16x16x32_bf16 v[8:11], v[150:153], v[242:245], v[8:11]
	s_setprio 0
	s_setprio 1
	v_mfma_f32_16x16x32_bf16 v[60:63], v[134:137], v[186:189], v[60:63]
	v_mfma_f32_16x16x32_bf16 v[56:59], v[154:157], v[186:189], v[56:59]
	v_mfma_f32_16x16x32_bf16 v[44:47], v[134:137], v[230:233], v[44:47]
	v_mfma_f32_16x16x32_bf16 v[40:43], v[154:157], v[230:233], v[40:43]
	v_mfma_f32_16x16x32_bf16 v[28:31], v[134:137], v[238:241], v[28:31]
	v_mfma_f32_16x16x32_bf16 v[24:27], v[154:157], v[238:241], v[24:27]
	v_mfma_f32_16x16x32_bf16 v[12:15], v[134:137], v[246:249], v[12:15]
	v_mfma_f32_16x16x32_bf16 v[8:11], v[154:157], v[246:249], v[8:11]
	s_setprio 0
	s_setprio 1
	v_mfma_f32_16x16x32_bf16 v[52:55], v[158:161], v[182:185], v[52:55]
	v_mfma_f32_16x16x32_bf16 v[48:51], v[174:177], v[182:185], v[48:51]
	v_mfma_f32_16x16x32_bf16 v[36:39], v[158:161], v[208:211], v[36:39]
	v_mfma_f32_16x16x32_bf16 v[32:35], v[174:177], v[208:211], v[32:35]
	v_mfma_f32_16x16x32_bf16 v[20:23], v[158:161], v[234:237], v[20:23]
	v_mfma_f32_16x16x32_bf16 v[16:19], v[174:177], v[234:237], v[16:19]
	v_mfma_f32_16x16x32_bf16 v[4:7], v[158:161], v[242:245], v[4:7]
	v_mfma_f32_16x16x32_bf16 v[0:3], v[174:177], v[242:245], v[0:3]
	s_setprio 0
	s_setprio 1
	v_mfma_f32_16x16x32_bf16 v[52:55], v[162:165], v[186:189], v[52:55]
	v_mfma_f32_16x16x32_bf16 v[48:51], v[178:181], v[186:189], v[48:51]
	v_mfma_f32_16x16x32_bf16 v[36:39], v[162:165], v[230:233], v[36:39]
	v_mfma_f32_16x16x32_bf16 v[32:35], v[178:181], v[230:233], v[32:35]
	v_mfma_f32_16x16x32_bf16 v[20:23], v[162:165], v[238:241], v[20:23]
	v_mfma_f32_16x16x32_bf16 v[16:19], v[178:181], v[238:241], v[16:19]
	v_mfma_f32_16x16x32_bf16 v[4:7], v[162:165], v[246:249], v[4:7]
	v_mfma_f32_16x16x32_bf16 v[0:3], v[178:181], v[246:249], v[0:3]
	s_setprio 0
	s_barrier
	s_add_i32 s44, s44, 2
	s_add_u32 s42, s42, 0x100
	s_addc_u32 s43, s43, 0
	s_add_u32 s8, s8, 0x100
	s_addc_u32 s9, s9, 0
	s_cmp_gt_u32 s44, 13
	s_cbranch_scc0 .LBB0_2151
	s_branch .Lpeel_exit_2151
.LBB0_2151:
	s_add_u32 s38, s8, 0xfffc0080
	s_addc_u32 s39, s9, -1
	s_add_i32 s45, 0, 0x10000
	s_cmp_eq_u32 s44, 12
	s_cselect_b32 s41, s11, s39
	s_cselect_b32 s40, s29, s38
	v_add_u32_e32 v112, s45, v169
	s_cselect_b32 s39, s27, s43
	s_cselect_b32 s38, s35, s42
	s_add_i32 s68, 0, 0x14000
	ds_read_b128 v[130:133], v112
	ds_read_b128 v[134:137], v112 offset:1024
	ds_read_b128 v[150:153], v112 offset:2048
	ds_read_b128 v[154:157], v112 offset:3072
	v_add_u32_e32 v112, s68, v169
	ds_read_b128 v[158:161], v112
	ds_read_b128 v[162:165], v112 offset:1024
	ds_read_b128 v[174:177], v112 offset:2048
	ds_read_b128 v[178:181], v112 offset:3072
	s_add_i32 m0, s37, 0xc000
	ds_read_b128 v[182:185], v172
	ds_read_b128 v[186:189], v172 offset:1024
	ds_read_b128 v[208:211], v172 offset:2048
	ds_read_b128 v[230:233], v172 offset:3072
	ds_read_b128 v[234:237], v172 offset:4096
	ds_read_b128 v[238:241], v172 offset:5120
	ds_read_b128 v[242:245], v172 offset:6144
	ds_read_b128 v[246:249], v172 offset:7168
	global_load_lds_dwordx4 v148, s[8:9]
	s_add_i32 m0, s37, 0xe000
	s_nop 0
	global_load_lds_dwordx4 v146, s[8:9]
	s_waitcnt vmcnt(8)
	s_waitcnt lgkmcnt(0)
	s_barrier
	s_setprio 1
	s_waitcnt lgkmcnt(0)
	v_mfma_f32_16x16x32_bf16 v[126:129], v[130:133], v[182:185], v[126:129]
	v_mfma_f32_16x16x32_bf16 v[122:125], v[150:153], v[182:185], v[122:125]
	v_mfma_f32_16x16x32_bf16 v[108:111], v[130:133], v[208:211], v[108:111]
	v_mfma_f32_16x16x32_bf16 v[104:107], v[150:153], v[208:211], v[104:107]
	v_mfma_f32_16x16x32_bf16 v[92:95], v[130:133], v[234:237], v[92:95]
	v_mfma_f32_16x16x32_bf16 v[88:91], v[150:153], v[234:237], v[88:91]
	v_mfma_f32_16x16x32_bf16 v[76:79], v[130:133], v[242:245], v[76:79]
	v_mfma_f32_16x16x32_bf16 v[72:75], v[150:153], v[242:245], v[72:75]
	s_setprio 0
	s_setprio 1
	v_mfma_f32_16x16x32_bf16 v[126:129], v[134:137], v[186:189], v[126:129]
	v_mfma_f32_16x16x32_bf16 v[122:125], v[154:157], v[186:189], v[122:125]
	v_mfma_f32_16x16x32_bf16 v[108:111], v[134:137], v[230:233], v[108:111]
	v_mfma_f32_16x16x32_bf16 v[104:107], v[154:157], v[230:233], v[104:107]
	v_mfma_f32_16x16x32_bf16 v[92:95], v[134:137], v[238:241], v[92:95]
	v_mfma_f32_16x16x32_bf16 v[88:91], v[154:157], v[238:241], v[88:91]
	v_mfma_f32_16x16x32_bf16 v[76:79], v[134:137], v[246:249], v[76:79]
	v_mfma_f32_16x16x32_bf16 v[72:75], v[154:157], v[246:249], v[72:75]
	s_setprio 0
	s_setprio 1
	v_mfma_f32_16x16x32_bf16 v[118:121], v[158:161], v[182:185], v[118:121]
	v_mfma_f32_16x16x32_bf16 v[114:117], v[174:177], v[182:185], v[114:117]
	v_mfma_f32_16x16x32_bf16 v[100:103], v[158:161], v[208:211], v[100:103]
	v_mfma_f32_16x16x32_bf16 v[96:99], v[174:177], v[208:211], v[96:99]
	v_mfma_f32_16x16x32_bf16 v[84:87], v[158:161], v[234:237], v[84:87]
	v_mfma_f32_16x16x32_bf16 v[80:83], v[174:177], v[234:237], v[80:83]
	v_mfma_f32_16x16x32_bf16 v[68:71], v[158:161], v[242:245], v[68:71]
	v_mfma_f32_16x16x32_bf16 v[64:67], v[174:177], v[242:245], v[64:67]
	s_setprio 0
	s_setprio 1
	v_mfma_f32_16x16x32_bf16 v[118:121], v[162:165], v[186:189], v[118:121]
	v_mfma_f32_16x16x32_bf16 v[114:117], v[178:181], v[186:189], v[114:117]
	v_mfma_f32_16x16x32_bf16 v[100:103], v[162:165], v[230:233], v[100:103]
	v_mfma_f32_16x16x32_bf16 v[96:99], v[178:181], v[230:233], v[96:99]
	v_mfma_f32_16x16x32_bf16 v[84:87], v[162:165], v[238:241], v[84:87]
	v_mfma_f32_16x16x32_bf16 v[80:83], v[178:181], v[238:241], v[80:83]
	v_mfma_f32_16x16x32_bf16 v[68:71], v[162:165], v[246:249], v[68:71]
	v_mfma_f32_16x16x32_bf16 v[64:67], v[178:181], v[246:249], v[64:67]
	s_setprio 0
	s_barrier
	s_add_i32 s45, s45, s58
	s_mov_b32 m0, s45
	ds_read_b128 v[182:185], v172 offset:16384
	ds_read_b128 v[186:189], v172 offset:17408
	ds_read_b128 v[208:211], v172 offset:18432
	ds_read_b128 v[230:233], v172 offset:19456
	ds_read_b128 v[234:237], v172 offset:20480
	ds_read_b128 v[238:241], v172 offset:21504
	ds_read_b128 v[242:245], v172 offset:22528
	ds_read_b128 v[246:249], v172 offset:23552
	global_load_lds_dwordx4 v140, s[38:39]
	s_add_i32 m0, s45, 0x2000
	s_add_u32 s66, s38, 0x40000
	v_lshl_add_u64 v[212:213], s[38:39], 0, v[144:145]
	s_addc_u32 s67, s39, 0
	s_add_i32 s45, s68, s58
	global_load_lds_dwordx4 v144, s[38:39]
	s_mov_b32 m0, s45
	v_lshl_add_u64 v[250:251], s[40:41], 0, v[142:143]
	global_load_lds_dwordx4 v140, s[66:67]
	s_add_i32 m0, s45, 0x2000
	s_nop 0
	global_load_lds_dwordx4 v144, s[66:67]
	v_lshl_add_u64 v[228:229], s[40:41], 0, v[138:139]
	s_mov_b32 m0, s37
	s_nop 0
	global_load_lds_dwordx4 v138, s[40:41]
	s_mov_b32 m0, s59
	s_nop 0
	global_load_lds_dwordx4 v142, s[40:41]
	s_waitcnt vmcnt(8)
	s_waitcnt lgkmcnt(0)
	s_barrier
	s_setprio 1
	s_waitcnt lgkmcnt(0)
	v_mfma_f32_16x16x32_bf16 v[60:63], v[130:133], v[182:185], v[60:63]
	v_mfma_f32_16x16x32_bf16 v[56:59], v[150:153], v[182:185], v[56:59]
	v_mfma_f32_16x16x32_bf16 v[44:47], v[130:133], v[208:211], v[44:47]
	v_mfma_f32_16x16x32_bf16 v[40:43], v[150:153], v[208:211], v[40:43]
	v_mfma_f32_16x16x32_bf16 v[28:31], v[130:133], v[234:237], v[28:31]
	v_mfma_f32_16x16x32_bf16 v[24:27], v[150:153], v[234:237], v[24:27]
	v_mfma_f32_16x16x32_bf16 v[12:15], v[130:133], v[242:245], v[12:15]
	v_mfma_f32_16x16x32_bf16 v[8:11], v[150:153], v[242:245], v[8:11]
	s_setprio 0
	s_setprio 1
	v_mfma_f32_16x16x32_bf16 v[60:63], v[134:137], v[186:189], v[60:63]
	v_mfma_f32_16x16x32_bf16 v[56:59], v[154:157], v[186:189], v[56:59]
	v_mfma_f32_16x16x32_bf16 v[44:47], v[134:137], v[230:233], v[44:47]
	v_mfma_f32_16x16x32_bf16 v[40:43], v[154:157], v[230:233], v[40:43]
	v_mfma_f32_16x16x32_bf16 v[28:31], v[134:137], v[238:241], v[28:31]
	v_mfma_f32_16x16x32_bf16 v[24:27], v[154:157], v[238:241], v[24:27]
	v_mfma_f32_16x16x32_bf16 v[12:15], v[134:137], v[246:249], v[12:15]
	v_mfma_f32_16x16x32_bf16 v[8:11], v[154:157], v[246:249], v[8:11]
	s_setprio 0
	s_setprio 1
	v_mfma_f32_16x16x32_bf16 v[52:55], v[158:161], v[182:185], v[52:55]
	v_mfma_f32_16x16x32_bf16 v[48:51], v[174:177], v[182:185], v[48:51]
	v_mfma_f32_16x16x32_bf16 v[36:39], v[158:161], v[208:211], v[36:39]
	v_mfma_f32_16x16x32_bf16 v[32:35], v[174:177], v[208:211], v[32:35]
	v_mfma_f32_16x16x32_bf16 v[20:23], v[158:161], v[234:237], v[20:23]
	v_mfma_f32_16x16x32_bf16 v[16:19], v[174:177], v[234:237], v[16:19]
	v_mfma_f32_16x16x32_bf16 v[4:7], v[158:161], v[242:245], v[4:7]
	v_mfma_f32_16x16x32_bf16 v[0:3], v[174:177], v[242:245], v[0:3]
	s_setprio 0
	s_setprio 1
	v_mfma_f32_16x16x32_bf16 v[52:55], v[162:165], v[186:189], v[52:55]
	v_mfma_f32_16x16x32_bf16 v[48:51], v[178:181], v[186:189], v[48:51]
	v_mfma_f32_16x16x32_bf16 v[36:39], v[162:165], v[230:233], v[36:39]
	v_mfma_f32_16x16x32_bf16 v[32:35], v[178:181], v[230:233], v[32:35]
	v_mfma_f32_16x16x32_bf16 v[20:23], v[162:165], v[238:241], v[20:23]
	v_mfma_f32_16x16x32_bf16 v[16:19], v[178:181], v[238:241], v[16:19]
	v_mfma_f32_16x16x32_bf16 v[4:7], v[162:165], v[246:249], v[4:7]
	v_mfma_f32_16x16x32_bf16 v[0:3], v[178:181], v[246:249], v[0:3]
	s_setprio 0
	s_barrier
	s_add_i32 s45, 0, 0x18000
	v_add_u32_e32 v112, s45, v169
	s_add_i32 s66, 0, 0x1c000
	ds_read_b128 v[130:133], v112
	ds_read_b128 v[134:137], v112 offset:1024
	ds_read_b128 v[150:153], v112 offset:2048
	ds_read_b128 v[154:157], v112 offset:3072
	v_add_u32_e32 v112, s66, v169
	ds_read_b128 v[158:161], v112
	ds_read_b128 v[162:165], v112 offset:1024
	ds_read_b128 v[174:177], v112 offset:2048
	ds_read_b128 v[178:181], v112 offset:3072
	s_add_u32 s40, s40, 0x40000
	s_addc_u32 s41, s41, 0
	s_mov_b32 m0, s60
	ds_read_b128 v[182:185], v172 offset:32768
	ds_read_b128 v[186:189], v172 offset:33792
	ds_read_b128 v[208:211], v172 offset:34816
	ds_read_b128 v[230:233], v172 offset:35840
	ds_read_b128 v[234:237], v172 offset:36864
	ds_read_b128 v[238:241], v172 offset:37888
	ds_read_b128 v[242:245], v172 offset:38912
	ds_read_b128 v[246:249], v172 offset:39936
	global_load_lds_dwordx4 v138, s[40:41]
	s_mov_b32 m0, s61
	s_nop 0
	global_load_lds_dwordx4 v142, s[40:41]
	s_waitcnt vmcnt(8)
	s_waitcnt lgkmcnt(0)
	s_barrier
	s_setprio 1
	s_waitcnt lgkmcnt(0)
	v_mfma_f32_16x16x32_bf16 v[126:129], v[130:133], v[182:185], v[126:129]
	v_mfma_f32_16x16x32_bf16 v[122:125], v[150:153], v[182:185], v[122:125]
	v_mfma_f32_16x16x32_bf16 v[108:111], v[130:133], v[208:211], v[108:111]
	v_mfma_f32_16x16x32_bf16 v[104:107], v[150:153], v[208:211], v[104:107]
	v_mfma_f32_16x16x32_bf16 v[92:95], v[130:133], v[234:237], v[92:95]
	v_mfma_f32_16x16x32_bf16 v[88:91], v[150:153], v[234:237], v[88:91]
	v_mfma_f32_16x16x32_bf16 v[76:79], v[130:133], v[242:245], v[76:79]
	v_mfma_f32_16x16x32_bf16 v[72:75], v[150:153], v[242:245], v[72:75]
	s_setprio 0
	s_setprio 1
	v_mfma_f32_16x16x32_bf16 v[126:129], v[134:137], v[186:189], v[126:129]
	v_mfma_f32_16x16x32_bf16 v[122:125], v[154:157], v[186:189], v[122:125]
	v_mfma_f32_16x16x32_bf16 v[108:111], v[134:137], v[230:233], v[108:111]
	v_mfma_f32_16x16x32_bf16 v[104:107], v[154:157], v[230:233], v[104:107]
	v_mfma_f32_16x16x32_bf16 v[92:95], v[134:137], v[238:241], v[92:95]
	v_mfma_f32_16x16x32_bf16 v[88:91], v[154:157], v[238:241], v[88:91]
	v_mfma_f32_16x16x32_bf16 v[76:79], v[134:137], v[246:249], v[76:79]
	v_mfma_f32_16x16x32_bf16 v[72:75], v[154:157], v[246:249], v[72:75]
	s_setprio 0
	s_setprio 1
	v_mfma_f32_16x16x32_bf16 v[118:121], v[158:161], v[182:185], v[118:121]
	v_mfma_f32_16x16x32_bf16 v[114:117], v[174:177], v[182:185], v[114:117]
	v_mfma_f32_16x16x32_bf16 v[100:103], v[158:161], v[208:211], v[100:103]
	v_mfma_f32_16x16x32_bf16 v[96:99], v[174:177], v[208:211], v[96:99]
	v_mfma_f32_16x16x32_bf16 v[84:87], v[158:161], v[234:237], v[84:87]
	v_mfma_f32_16x16x32_bf16 v[80:83], v[174:177], v[234:237], v[80:83]
	v_mfma_f32_16x16x32_bf16 v[68:71], v[158:161], v[242:245], v[68:71]
	v_mfma_f32_16x16x32_bf16 v[64:67], v[174:177], v[242:245], v[64:67]
	s_setprio 0
	s_setprio 1
	v_mfma_f32_16x16x32_bf16 v[118:121], v[162:165], v[186:189], v[118:121]
	v_mfma_f32_16x16x32_bf16 v[114:117], v[178:181], v[186:189], v[114:117]
	v_mfma_f32_16x16x32_bf16 v[100:103], v[162:165], v[230:233], v[100:103]
	v_mfma_f32_16x16x32_bf16 v[96:99], v[178:181], v[230:233], v[96:99]
	v_mfma_f32_16x16x32_bf16 v[84:87], v[162:165], v[238:241], v[84:87]
	v_mfma_f32_16x16x32_bf16 v[80:83], v[178:181], v[238:241], v[80:83]
	v_mfma_f32_16x16x32_bf16 v[68:71], v[162:165], v[246:249], v[68:71]
	v_mfma_f32_16x16x32_bf16 v[64:67], v[178:181], v[246:249], v[64:67]
	s_setprio 0
	s_barrier
	s_add_i32 s40, s45, s58
	s_mov_b32 m0, s40
	ds_read_b128 v[182:185], v172 offset:49152
	ds_read_b128 v[186:189], v172 offset:50176
	ds_read_b128 v[208:211], v172 offset:51200
	ds_read_b128 v[230:233], v172 offset:52224
	ds_read_b128 v[234:237], v172 offset:53248
	ds_read_b128 v[238:241], v172 offset:54272
	ds_read_b128 v[242:245], v172 offset:55296
	ds_read_b128 v[246:249], v172 offset:56320
	s_add_u32 s98, s38, 0x80
	s_addc_u32 s99, s39, 0
	global_load_lds_dwordx4 v140, s[98:99]
	s_add_i32 m0, s40, 0x2000
	s_add_u32 s38, s38, 0x40080
	v_lshl_add_u64 v[166:167], v[212:213], 0, s[96:97]
	s_addc_u32 s39, s39, 0
	s_add_i32 s40, s66, s58
	global_load_lds_dwordx4 v[166:167], off
	s_mov_b32 m0, s40
	s_nop 0
	global_load_lds_dwordx4 v140, s[38:39]
	s_add_i32 m0, s40, 0x2000
	s_nop 0
	global_load_lds_dwordx4 v144, s[38:39]
	v_lshl_add_u64 v[166:167], v[228:229], 0, s[96:97]
	s_mov_b32 m0, s62
	s_nop 0
	global_load_lds_dwordx4 v[166:167], off
	v_lshl_add_u64 v[166:167], v[250:251], 0, s[96:97]
	s_mov_b32 m0, s63
	s_nop 0
	global_load_lds_dwordx4 v[166:167], off
	s_waitcnt vmcnt(8)
	s_waitcnt lgkmcnt(0)
	s_barrier
	s_setprio 1
	s_waitcnt lgkmcnt(0)
	v_mfma_f32_16x16x32_bf16 v[60:63], v[130:133], v[182:185], v[60:63]
	v_mfma_f32_16x16x32_bf16 v[56:59], v[150:153], v[182:185], v[56:59]
	v_mfma_f32_16x16x32_bf16 v[44:47], v[130:133], v[208:211], v[44:47]
	v_mfma_f32_16x16x32_bf16 v[40:43], v[150:153], v[208:211], v[40:43]
	v_mfma_f32_16x16x32_bf16 v[28:31], v[130:133], v[234:237], v[28:31]
	v_mfma_f32_16x16x32_bf16 v[24:27], v[150:153], v[234:237], v[24:27]
	v_mfma_f32_16x16x32_bf16 v[12:15], v[130:133], v[242:245], v[12:15]
	v_mfma_f32_16x16x32_bf16 v[8:11], v[150:153], v[242:245], v[8:11]
	s_setprio 0
	s_setprio 1
	v_mfma_f32_16x16x32_bf16 v[60:63], v[134:137], v[186:189], v[60:63]
	v_mfma_f32_16x16x32_bf16 v[56:59], v[154:157], v[186:189], v[56:59]
	v_mfma_f32_16x16x32_bf16 v[44:47], v[134:137], v[230:233], v[44:47]
	v_mfma_f32_16x16x32_bf16 v[40:43], v[154:157], v[230:233], v[40:43]
	v_mfma_f32_16x16x32_bf16 v[28:31], v[134:137], v[238:241], v[28:31]
	v_mfma_f32_16x16x32_bf16 v[24:27], v[154:157], v[238:241], v[24:27]
	v_mfma_f32_16x16x32_bf16 v[12:15], v[134:137], v[246:249], v[12:15]
	v_mfma_f32_16x16x32_bf16 v[8:11], v[154:157], v[246:249], v[8:11]
	s_setprio 0
	s_setprio 1
	v_mfma_f32_16x16x32_bf16 v[52:55], v[158:161], v[182:185], v[52:55]
	v_mfma_f32_16x16x32_bf16 v[48:51], v[174:177], v[182:185], v[48:51]
	v_mfma_f32_16x16x32_bf16 v[36:39], v[158:161], v[208:211], v[36:39]
	v_mfma_f32_16x16x32_bf16 v[32:35], v[174:177], v[208:211], v[32:35]
	v_mfma_f32_16x16x32_bf16 v[20:23], v[158:161], v[234:237], v[20:23]
	v_mfma_f32_16x16x32_bf16 v[16:19], v[174:177], v[234:237], v[16:19]
	v_mfma_f32_16x16x32_bf16 v[4:7], v[158:161], v[242:245], v[4:7]
	v_mfma_f32_16x16x32_bf16 v[0:3], v[174:177], v[242:245], v[0:3]
	s_setprio 0
	s_setprio 1
	v_mfma_f32_16x16x32_bf16 v[52:55], v[162:165], v[186:189], v[52:55]
	v_mfma_f32_16x16x32_bf16 v[48:51], v[178:181], v[186:189], v[48:51]
	v_mfma_f32_16x16x32_bf16 v[36:39], v[162:165], v[230:233], v[36:39]
	v_mfma_f32_16x16x32_bf16 v[32:35], v[178:181], v[230:233], v[32:35]
	v_mfma_f32_16x16x32_bf16 v[20:23], v[162:165], v[238:241], v[20:23]
	v_mfma_f32_16x16x32_bf16 v[16:19], v[178:181], v[238:241], v[16:19]
	v_mfma_f32_16x16x32_bf16 v[4:7], v[162:165], v[246:249], v[4:7]
	v_mfma_f32_16x16x32_bf16 v[0:3], v[178:181], v[246:249], v[0:3]
	s_setprio 0
	s_barrier
	s_add_i32 s44, s44, 2
	s_add_u32 s42, s42, 0x100
	s_addc_u32 s43, s43, 0
	s_add_u32 s8, s8, 0x100
	s_addc_u32 s9, s9, 0
	s_cmp_gt_u32 s44, 13
	s_cbranch_scc0 .LBB0_2151

.LBB0_2368:
	s_ashr_i32 s23, s22, 31
	s_lshl_b64 s[24:25], s[22:23], 19
	s_add_u32 s24, s49, s24
	s_addc_u32 s25, s50, s25
	s_and_b64 s[26:27], s[2:3], exec
	s_cselect_b32 s5, s25, s29
	s_cselect_b32 s23, s24, s28
	s_ashr_i32 s15, s14, 31
	s_lshl_b64 s[26:27], s[14:15], 19
	s_add_u32 s26, s51, s26
	s_addc_u32 s27, s52, s27
	s_and_b64 s[30:31], s[2:3], exec
	s_cselect_b32 s15, s27, s7
	s_cselect_b32 s47, s26, s6
	s_add_u32 s54, s6, 0x100
	s_addc_u32 s55, s7, 0
	s_add_u32 s6, s28, 0x40080
	s_addc_u32 s7, s29, 0
	s_mov_b32 s56, -2
	s_waitcnt lgkmcnt(0)
	s_add_u32 s28, s6, 0xfffc0080
	s_addc_u32 s29, s7, -1
	s_add_i32 s57, 0, 0x10000
	s_cmp_eq_u32 s56, 12
	s_cselect_b32 s31, s5, s29
	s_cselect_b32 s30, s23, s28
	v_add_u32_e32 v146, s57, v148
	s_cselect_b32 s29, s15, s55
	s_cselect_b32 s28, s47, s54
	s_add_i32 s60, 0, 0x14000
	ds_read_b128 v[142:145], v146
	ds_read_b128 v[152:155], v146 offset:1024
	ds_read_b128 v[156:159], v146 offset:2048
	ds_read_b128 v[160:163], v146 offset:3072
	v_add_u32_e32 v146, s60, v148
	ds_read_b128 v[164:167], v146
	ds_read_b128 v[168:171], v146 offset:1024
	ds_read_b128 v[172:175], v146 offset:2048
	ds_read_b128 v[176:179], v146 offset:3072
	s_add_i32 m0, s21, 0xc000
	ds_read_b128 v[180:183], v151
	ds_read_b128 v[184:187], v151 offset:1024
	ds_read_b128 v[208:211], v151 offset:2048
	ds_read_b128 v[230:233], v151 offset:3072
	ds_read_b128 v[234:237], v151 offset:4096
	ds_read_b128 v[238:241], v151 offset:5120
	ds_read_b128 v[242:245], v151 offset:6144
	ds_read_b128 v[246:249], v151 offset:7168
	global_load_lds_dwordx4 v140, s[6:7]
	s_add_i32 m0, s21, 0xe000
	s_nop 0
	global_load_lds_dwordx4 v138, s[6:7]
	s_waitcnt vmcnt(8)
	s_waitcnt lgkmcnt(0)
	s_barrier
	s_setprio 1
	s_waitcnt lgkmcnt(0)
	v_mfma_f32_16x16x32_bf16 v[126:129], v[142:145], v[180:183], 0
	v_mfma_f32_16x16x32_bf16 v[122:125], v[156:159], v[180:183], 0
	v_mfma_f32_16x16x32_bf16 v[108:111], v[142:145], v[208:211], 0
	v_mfma_f32_16x16x32_bf16 v[104:107], v[156:159], v[208:211], 0
	v_mfma_f32_16x16x32_bf16 v[92:95], v[142:145], v[234:237], 0
	v_mfma_f32_16x16x32_bf16 v[88:91], v[156:159], v[234:237], 0
	v_mfma_f32_16x16x32_bf16 v[76:79], v[142:145], v[242:245], 0
	v_mfma_f32_16x16x32_bf16 v[72:75], v[156:159], v[242:245], 0
	s_setprio 0
	s_setprio 1
	v_mfma_f32_16x16x32_bf16 v[126:129], v[152:155], v[184:187], v[126:129]
	v_mfma_f32_16x16x32_bf16 v[122:125], v[160:163], v[184:187], v[122:125]
	v_mfma_f32_16x16x32_bf16 v[108:111], v[152:155], v[230:233], v[108:111]
	v_mfma_f32_16x16x32_bf16 v[104:107], v[160:163], v[230:233], v[104:107]
	v_mfma_f32_16x16x32_bf16 v[92:95], v[152:155], v[238:241], v[92:95]
	v_mfma_f32_16x16x32_bf16 v[88:91], v[160:163], v[238:241], v[88:91]
	v_mfma_f32_16x16x32_bf16 v[76:79], v[152:155], v[246:249], v[76:79]
	v_mfma_f32_16x16x32_bf16 v[72:75], v[160:163], v[246:249], v[72:75]
	s_setprio 0
	s_setprio 1
	v_mfma_f32_16x16x32_bf16 v[118:121], v[164:167], v[180:183], 0
	v_mfma_f32_16x16x32_bf16 v[114:117], v[172:175], v[180:183], 0
	v_mfma_f32_16x16x32_bf16 v[100:103], v[164:167], v[208:211], 0
	v_mfma_f32_16x16x32_bf16 v[96:99], v[172:175], v[208:211], 0
	v_mfma_f32_16x16x32_bf16 v[84:87], v[164:167], v[234:237], 0
	v_mfma_f32_16x16x32_bf16 v[80:83], v[172:175], v[234:237], 0
	v_mfma_f32_16x16x32_bf16 v[68:71], v[164:167], v[242:245], 0
	v_mfma_f32_16x16x32_bf16 v[64:67], v[172:175], v[242:245], 0
	s_setprio 0
	s_setprio 1
	v_mfma_f32_16x16x32_bf16 v[118:121], v[168:171], v[184:187], v[118:121]
	v_mfma_f32_16x16x32_bf16 v[114:117], v[176:179], v[184:187], v[114:117]
	v_mfma_f32_16x16x32_bf16 v[100:103], v[168:171], v[230:233], v[100:103]
	v_mfma_f32_16x16x32_bf16 v[96:99], v[176:179], v[230:233], v[96:99]
	v_mfma_f32_16x16x32_bf16 v[84:87], v[168:171], v[238:241], v[84:87]
	v_mfma_f32_16x16x32_bf16 v[80:83], v[176:179], v[238:241], v[80:83]
	v_mfma_f32_16x16x32_bf16 v[68:71], v[168:171], v[246:249], v[68:71]
	v_mfma_f32_16x16x32_bf16 v[64:67], v[176:179], v[246:249], v[64:67]
	s_setprio 0
	s_barrier
	s_add_i32 s57, s57, s39
	s_mov_b32 m0, s57
	ds_read_b128 v[180:183], v151 offset:16384
	ds_read_b128 v[184:187], v151 offset:17408
	ds_read_b128 v[208:211], v151 offset:18432
	ds_read_b128 v[230:233], v151 offset:19456
	ds_read_b128 v[234:237], v151 offset:20480
	ds_read_b128 v[238:241], v151 offset:21504
	ds_read_b128 v[242:245], v151 offset:22528
	ds_read_b128 v[246:249], v151 offset:23552
	global_load_lds_dwordx4 v112, s[28:29]
	s_add_i32 m0, s57, 0x2000
	s_add_u32 s58, s28, 0x40000
	v_lshl_add_u64 v[212:213], s[28:29], 0, v[134:135]
	s_addc_u32 s59, s29, 0
	s_add_i32 s57, s60, s39
	global_load_lds_dwordx4 v134, s[28:29]
	s_mov_b32 m0, s57
	v_lshl_add_u64 v[252:253], s[30:31], 0, v[132:133]
	global_load_lds_dwordx4 v112, s[58:59]
	s_add_i32 m0, s57, 0x2000
	s_nop 0
	global_load_lds_dwordx4 v134, s[58:59]
	v_lshl_add_u64 v[250:251], s[30:31], 0, v[130:131]
	s_mov_b32 m0, s21
	s_nop 0
	global_load_lds_dwordx4 v130, s[30:31]
	s_mov_b32 m0, s40
	s_nop 0
	global_load_lds_dwordx4 v132, s[30:31]
	s_waitcnt vmcnt(8)
	s_waitcnt lgkmcnt(0)
	s_barrier
	s_setprio 1
	s_waitcnt lgkmcnt(0)
	v_mfma_f32_16x16x32_bf16 v[60:63], v[142:145], v[180:183], 0
	v_mfma_f32_16x16x32_bf16 v[56:59], v[156:159], v[180:183], 0
	v_mfma_f32_16x16x32_bf16 v[44:47], v[142:145], v[208:211], 0
	v_mfma_f32_16x16x32_bf16 v[40:43], v[156:159], v[208:211], 0
	v_mfma_f32_16x16x32_bf16 v[28:31], v[142:145], v[234:237], 0
	v_mfma_f32_16x16x32_bf16 v[24:27], v[156:159], v[234:237], 0
	v_mfma_f32_16x16x32_bf16 v[12:15], v[142:145], v[242:245], 0
	v_mfma_f32_16x16x32_bf16 v[8:11], v[156:159], v[242:245], 0
	s_setprio 0
	s_setprio 1
	v_mfma_f32_16x16x32_bf16 v[60:63], v[152:155], v[184:187], v[60:63]
	v_mfma_f32_16x16x32_bf16 v[56:59], v[160:163], v[184:187], v[56:59]
	v_mfma_f32_16x16x32_bf16 v[44:47], v[152:155], v[230:233], v[44:47]
	v_mfma_f32_16x16x32_bf16 v[40:43], v[160:163], v[230:233], v[40:43]
	v_mfma_f32_16x16x32_bf16 v[28:31], v[152:155], v[238:241], v[28:31]
	v_mfma_f32_16x16x32_bf16 v[24:27], v[160:163], v[238:241], v[24:27]
	v_mfma_f32_16x16x32_bf16 v[12:15], v[152:155], v[246:249], v[12:15]
	v_mfma_f32_16x16x32_bf16 v[8:11], v[160:163], v[246:249], v[8:11]
	s_setprio 0
	s_setprio 1
	v_mfma_f32_16x16x32_bf16 v[52:55], v[164:167], v[180:183], 0
	v_mfma_f32_16x16x32_bf16 v[48:51], v[172:175], v[180:183], 0
	v_mfma_f32_16x16x32_bf16 v[36:39], v[164:167], v[208:211], 0
	v_mfma_f32_16x16x32_bf16 v[32:35], v[172:175], v[208:211], 0
	v_mfma_f32_16x16x32_bf16 v[20:23], v[164:167], v[234:237], 0
	v_mfma_f32_16x16x32_bf16 v[16:19], v[172:175], v[234:237], 0
	v_mfma_f32_16x16x32_bf16 v[4:7], v[164:167], v[242:245], 0
	v_mfma_f32_16x16x32_bf16 v[0:3], v[172:175], v[242:245], 0
	s_setprio 0
	s_setprio 1
	v_mfma_f32_16x16x32_bf16 v[52:55], v[168:171], v[184:187], v[52:55]
	v_mfma_f32_16x16x32_bf16 v[48:51], v[176:179], v[184:187], v[48:51]
	v_mfma_f32_16x16x32_bf16 v[36:39], v[168:171], v[230:233], v[36:39]
	v_mfma_f32_16x16x32_bf16 v[32:35], v[176:179], v[230:233], v[32:35]
	v_mfma_f32_16x16x32_bf16 v[20:23], v[168:171], v[238:241], v[20:23]
	v_mfma_f32_16x16x32_bf16 v[16:19], v[176:179], v[238:241], v[16:19]
	v_mfma_f32_16x16x32_bf16 v[4:7], v[168:171], v[246:249], v[4:7]
	v_mfma_f32_16x16x32_bf16 v[0:3], v[176:179], v[246:249], v[0:3]
	s_setprio 0
	s_barrier
	s_add_i32 s57, 0, 0x18000
	v_add_u32_e32 v146, s57, v148
	s_add_i32 s58, 0, 0x1c000
	ds_read_b128 v[142:145], v146
	ds_read_b128 v[152:155], v146 offset:1024
	ds_read_b128 v[156:159], v146 offset:2048
	ds_read_b128 v[160:163], v146 offset:3072
	v_add_u32_e32 v146, s58, v148
	ds_read_b128 v[164:167], v146
	ds_read_b128 v[168:171], v146 offset:1024
	ds_read_b128 v[172:175], v146 offset:2048
	ds_read_b128 v[176:179], v146 offset:3072
	s_add_u32 s30, s30, 0x40000
	s_addc_u32 s31, s31, 0
	s_mov_b32 m0, s41
	ds_read_b128 v[180:183], v151 offset:32768
	ds_read_b128 v[184:187], v151 offset:33792
	ds_read_b128 v[208:211], v151 offset:34816
	ds_read_b128 v[230:233], v151 offset:35840
	ds_read_b128 v[234:237], v151 offset:36864
	ds_read_b128 v[238:241], v151 offset:37888
	ds_read_b128 v[242:245], v151 offset:38912
	ds_read_b128 v[246:249], v151 offset:39936
	global_load_lds_dwordx4 v130, s[30:31]
	s_mov_b32 m0, s42
	s_nop 0
	global_load_lds_dwordx4 v132, s[30:31]
	s_waitcnt vmcnt(8)
	s_waitcnt lgkmcnt(0)
	s_barrier
	s_setprio 1
	s_waitcnt lgkmcnt(0)
	v_mfma_f32_16x16x32_bf16 v[126:129], v[142:145], v[180:183], v[126:129]
	v_mfma_f32_16x16x32_bf16 v[122:125], v[156:159], v[180:183], v[122:125]
	v_mfma_f32_16x16x32_bf16 v[108:111], v[142:145], v[208:211], v[108:111]
	v_mfma_f32_16x16x32_bf16 v[104:107], v[156:159], v[208:211], v[104:107]
	v_mfma_f32_16x16x32_bf16 v[92:95], v[142:145], v[234:237], v[92:95]
	v_mfma_f32_16x16x32_bf16 v[88:91], v[156:159], v[234:237], v[88:91]
	v_mfma_f32_16x16x32_bf16 v[76:79], v[142:145], v[242:245], v[76:79]
	v_mfma_f32_16x16x32_bf16 v[72:75], v[156:159], v[242:245], v[72:75]
	s_setprio 0
	s_setprio 1
	v_mfma_f32_16x16x32_bf16 v[126:129], v[152:155], v[184:187], v[126:129]
	v_mfma_f32_16x16x32_bf16 v[122:125], v[160:163], v[184:187], v[122:125]
	v_mfma_f32_16x16x32_bf16 v[108:111], v[152:155], v[230:233], v[108:111]
	v_mfma_f32_16x16x32_bf16 v[104:107], v[160:163], v[230:233], v[104:107]
	v_mfma_f32_16x16x32_bf16 v[92:95], v[152:155], v[238:241], v[92:95]
	v_mfma_f32_16x16x32_bf16 v[88:91], v[160:163], v[238:241], v[88:91]
	v_mfma_f32_16x16x32_bf16 v[76:79], v[152:155], v[246:249], v[76:79]
	v_mfma_f32_16x16x32_bf16 v[72:75], v[160:163], v[246:249], v[72:75]
	s_setprio 0
	s_setprio 1
	v_mfma_f32_16x16x32_bf16 v[118:121], v[164:167], v[180:183], v[118:121]
	v_mfma_f32_16x16x32_bf16 v[114:117], v[172:175], v[180:183], v[114:117]
	v_mfma_f32_16x16x32_bf16 v[100:103], v[164:167], v[208:211], v[100:103]
	v_mfma_f32_16x16x32_bf16 v[96:99], v[172:175], v[208:211], v[96:99]
	v_mfma_f32_16x16x32_bf16 v[84:87], v[164:167], v[234:237], v[84:87]
	v_mfma_f32_16x16x32_bf16 v[80:83], v[172:175], v[234:237], v[80:83]
	v_mfma_f32_16x16x32_bf16 v[68:71], v[164:167], v[242:245], v[68:71]
	v_mfma_f32_16x16x32_bf16 v[64:67], v[172:175], v[242:245], v[64:67]
	s_setprio 0
	s_setprio 1
	v_mfma_f32_16x16x32_bf16 v[118:121], v[168:171], v[184:187], v[118:121]
	v_mfma_f32_16x16x32_bf16 v[114:117], v[176:179], v[184:187], v[114:117]
	v_mfma_f32_16x16x32_bf16 v[100:103], v[168:171], v[230:233], v[100:103]
	v_mfma_f32_16x16x32_bf16 v[96:99], v[176:179], v[230:233], v[96:99]
	v_mfma_f32_16x16x32_bf16 v[84:87], v[168:171], v[238:241], v[84:87]
	v_mfma_f32_16x16x32_bf16 v[80:83], v[176:179], v[238:241], v[80:83]
	v_mfma_f32_16x16x32_bf16 v[68:71], v[168:171], v[246:249], v[68:71]
	v_mfma_f32_16x16x32_bf16 v[64:67], v[176:179], v[246:249], v[64:67]
	s_setprio 0
	s_barrier
	s_add_i32 s30, s57, s39
	s_mov_b32 m0, s30
	ds_read_b128 v[180:183], v151 offset:49152
	ds_read_b128 v[184:187], v151 offset:50176
	ds_read_b128 v[208:211], v151 offset:51200
	ds_read_b128 v[230:233], v151 offset:52224
	ds_read_b128 v[234:237], v151 offset:53248
	ds_read_b128 v[238:241], v151 offset:54272
	ds_read_b128 v[242:245], v151 offset:55296
	ds_read_b128 v[246:249], v151 offset:56320
	s_add_u32 s98, s28, 0x80
	s_addc_u32 s99, s29, 0
	global_load_lds_dwordx4 v112, s[98:99]
	s_add_i32 m0, s30, 0x2000
	s_add_u32 s28, s28, 0x40080
	v_lshl_add_u64 v[188:189], v[212:213], 0, s[96:97]
	s_addc_u32 s29, s29, 0
	s_add_i32 s30, s58, s39
	global_load_lds_dwordx4 v[188:189], off
	s_mov_b32 m0, s30
	s_nop 0
	global_load_lds_dwordx4 v112, s[28:29]
	s_add_i32 m0, s30, 0x2000
	s_nop 0
	global_load_lds_dwordx4 v134, s[28:29]
	v_lshl_add_u64 v[188:189], v[250:251], 0, s[96:97]
	s_mov_b32 m0, s43
	s_nop 0
	global_load_lds_dwordx4 v[188:189], off
	v_lshl_add_u64 v[188:189], v[252:253], 0, s[96:97]
	s_mov_b32 m0, s44
	s_nop 0
	global_load_lds_dwordx4 v[188:189], off
	s_waitcnt vmcnt(8)
	s_waitcnt lgkmcnt(0)
	s_barrier
	s_setprio 1
	s_waitcnt lgkmcnt(0)
	v_mfma_f32_16x16x32_bf16 v[60:63], v[142:145], v[180:183], v[60:63]
	v_mfma_f32_16x16x32_bf16 v[56:59], v[156:159], v[180:183], v[56:59]
	v_mfma_f32_16x16x32_bf16 v[44:47], v[142:145], v[208:211], v[44:47]
	v_mfma_f32_16x16x32_bf16 v[40:43], v[156:159], v[208:211], v[40:43]
	v_mfma_f32_16x16x32_bf16 v[28:31], v[142:145], v[234:237], v[28:31]
	v_mfma_f32_16x16x32_bf16 v[24:27], v[156:159], v[234:237], v[24:27]
	v_mfma_f32_16x16x32_bf16 v[12:15], v[142:145], v[242:245], v[12:15]
	v_mfma_f32_16x16x32_bf16 v[8:11], v[156:159], v[242:245], v[8:11]
	s_setprio 0
	s_setprio 1
	v_mfma_f32_16x16x32_bf16 v[60:63], v[152:155], v[184:187], v[60:63]
	v_mfma_f32_16x16x32_bf16 v[56:59], v[160:163], v[184:187], v[56:59]
	v_mfma_f32_16x16x32_bf16 v[44:47], v[152:155], v[230:233], v[44:47]
	v_mfma_f32_16x16x32_bf16 v[40:43], v[160:163], v[230:233], v[40:43]
	v_mfma_f32_16x16x32_bf16 v[28:31], v[152:155], v[238:241], v[28:31]
	v_mfma_f32_16x16x32_bf16 v[24:27], v[160:163], v[238:241], v[24:27]
	v_mfma_f32_16x16x32_bf16 v[12:15], v[152:155], v[246:249], v[12:15]
	v_mfma_f32_16x16x32_bf16 v[8:11], v[160:163], v[246:249], v[8:11]
	s_setprio 0
	s_setprio 1
	v_mfma_f32_16x16x32_bf16 v[52:55], v[164:167], v[180:183], v[52:55]
	v_mfma_f32_16x16x32_bf16 v[48:51], v[172:175], v[180:183], v[48:51]
	v_mfma_f32_16x16x32_bf16 v[36:39], v[164:167], v[208:211], v[36:39]
	v_mfma_f32_16x16x32_bf16 v[32:35], v[172:175], v[208:211], v[32:35]
	v_mfma_f32_16x16x32_bf16 v[20:23], v[164:167], v[234:237], v[20:23]
	v_mfma_f32_16x16x32_bf16 v[16:19], v[172:175], v[234:237], v[16:19]
	v_mfma_f32_16x16x32_bf16 v[4:7], v[164:167], v[242:245], v[4:7]
	v_mfma_f32_16x16x32_bf16 v[0:3], v[172:175], v[242:245], v[0:3]
	s_setprio 0
	s_setprio 1
	v_mfma_f32_16x16x32_bf16 v[52:55], v[168:171], v[184:187], v[52:55]
	v_mfma_f32_16x16x32_bf16 v[48:51], v[176:179], v[184:187], v[48:51]
	v_mfma_f32_16x16x32_bf16 v[36:39], v[168:171], v[230:233], v[36:39]
	v_mfma_f32_16x16x32_bf16 v[32:35], v[176:179], v[230:233], v[32:35]
	v_mfma_f32_16x16x32_bf16 v[20:23], v[168:171], v[238:241], v[20:23]
	v_mfma_f32_16x16x32_bf16 v[16:19], v[176:179], v[238:241], v[16:19]
	v_mfma_f32_16x16x32_bf16 v[4:7], v[168:171], v[246:249], v[4:7]
	v_mfma_f32_16x16x32_bf16 v[0:3], v[176:179], v[246:249], v[0:3]
	s_setprio 0
	s_barrier
	s_add_i32 s56, s56, 2
	s_add_u32 s54, s54, 0x100
	s_addc_u32 s55, s55, 0
	s_add_u32 s6, s6, 0x100
	s_addc_u32 s7, s7, 0
	s_cmp_gt_u32 s56, 13
	s_cbranch_scc0 .LBB0_2369
	s_branch .Lpeel_exit_2369
.LBB0_2369:
	s_add_u32 s28, s6, 0xfffc0080
	s_addc_u32 s29, s7, -1
	s_add_i32 s57, 0, 0x10000
	s_cmp_eq_u32 s56, 12
	s_cselect_b32 s31, s5, s29
	s_cselect_b32 s30, s23, s28
	v_add_u32_e32 v146, s57, v148
	s_cselect_b32 s29, s15, s55
	s_cselect_b32 s28, s47, s54
	s_add_i32 s60, 0, 0x14000
	ds_read_b128 v[142:145], v146
	ds_read_b128 v[152:155], v146 offset:1024
	ds_read_b128 v[156:159], v146 offset:2048
	ds_read_b128 v[160:163], v146 offset:3072
	v_add_u32_e32 v146, s60, v148
	ds_read_b128 v[164:167], v146
	ds_read_b128 v[168:171], v146 offset:1024
	ds_read_b128 v[172:175], v146 offset:2048
	ds_read_b128 v[176:179], v146 offset:3072
	s_add_i32 m0, s21, 0xc000
	ds_read_b128 v[180:183], v151
	ds_read_b128 v[184:187], v151 offset:1024
	ds_read_b128 v[208:211], v151 offset:2048
	ds_read_b128 v[230:233], v151 offset:3072
	ds_read_b128 v[234:237], v151 offset:4096
	ds_read_b128 v[238:241], v151 offset:5120
	ds_read_b128 v[242:245], v151 offset:6144
	ds_read_b128 v[246:249], v151 offset:7168
	global_load_lds_dwordx4 v140, s[6:7]
	s_add_i32 m0, s21, 0xe000
	s_nop 0
	global_load_lds_dwordx4 v138, s[6:7]
	s_waitcnt vmcnt(8)
	s_waitcnt lgkmcnt(0)
	s_barrier
	s_setprio 1
	s_waitcnt lgkmcnt(0)
	v_mfma_f32_16x16x32_bf16 v[126:129], v[142:145], v[180:183], v[126:129]
	v_mfma_f32_16x16x32_bf16 v[122:125], v[156:159], v[180:183], v[122:125]
	v_mfma_f32_16x16x32_bf16 v[108:111], v[142:145], v[208:211], v[108:111]
	v_mfma_f32_16x16x32_bf16 v[104:107], v[156:159], v[208:211], v[104:107]
	v_mfma_f32_16x16x32_bf16 v[92:95], v[142:145], v[234:237], v[92:95]
	v_mfma_f32_16x16x32_bf16 v[88:91], v[156:159], v[234:237], v[88:91]
	v_mfma_f32_16x16x32_bf16 v[76:79], v[142:145], v[242:245], v[76:79]
	v_mfma_f32_16x16x32_bf16 v[72:75], v[156:159], v[242:245], v[72:75]
	s_setprio 0
	s_setprio 1
	v_mfma_f32_16x16x32_bf16 v[126:129], v[152:155], v[184:187], v[126:129]
	v_mfma_f32_16x16x32_bf16 v[122:125], v[160:163], v[184:187], v[122:125]
	v_mfma_f32_16x16x32_bf16 v[108:111], v[152:155], v[230:233], v[108:111]
	v_mfma_f32_16x16x32_bf16 v[104:107], v[160:163], v[230:233], v[104:107]
	v_mfma_f32_16x16x32_bf16 v[92:95], v[152:155], v[238:241], v[92:95]
	v_mfma_f32_16x16x32_bf16 v[88:91], v[160:163], v[238:241], v[88:91]
	v_mfma_f32_16x16x32_bf16 v[76:79], v[152:155], v[246:249], v[76:79]
	v_mfma_f32_16x16x32_bf16 v[72:75], v[160:163], v[246:249], v[72:75]
	s_setprio 0
	s_setprio 1
	v_mfma_f32_16x16x32_bf16 v[118:121], v[164:167], v[180:183], v[118:121]
	v_mfma_f32_16x16x32_bf16 v[114:117], v[172:175], v[180:183], v[114:117]
	v_mfma_f32_16x16x32_bf16 v[100:103], v[164:167], v[208:211], v[100:103]
	v_mfma_f32_16x16x32_bf16 v[96:99], v[172:175], v[208:211], v[96:99]
	v_mfma_f32_16x16x32_bf16 v[84:87], v[164:167], v[234:237], v[84:87]
	v_mfma_f32_16x16x32_bf16 v[80:83], v[172:175], v[234:237], v[80:83]
	v_mfma_f32_16x16x32_bf16 v[68:71], v[164:167], v[242:245], v[68:71]
	v_mfma_f32_16x16x32_bf16 v[64:67], v[172:175], v[242:245], v[64:67]
	s_setprio 0
	s_setprio 1
	v_mfma_f32_16x16x32_bf16 v[118:121], v[168:171], v[184:187], v[118:121]
	v_mfma_f32_16x16x32_bf16 v[114:117], v[176:179], v[184:187], v[114:117]
	v_mfma_f32_16x16x32_bf16 v[100:103], v[168:171], v[230:233], v[100:103]
	v_mfma_f32_16x16x32_bf16 v[96:99], v[176:179], v[230:233], v[96:99]
	v_mfma_f32_16x16x32_bf16 v[84:87], v[168:171], v[238:241], v[84:87]
	v_mfma_f32_16x16x32_bf16 v[80:83], v[176:179], v[238:241], v[80:83]
	v_mfma_f32_16x16x32_bf16 v[68:71], v[168:171], v[246:249], v[68:71]
	v_mfma_f32_16x16x32_bf16 v[64:67], v[176:179], v[246:249], v[64:67]
	s_setprio 0
	s_barrier
	s_add_i32 s57, s57, s39
	s_mov_b32 m0, s57
	ds_read_b128 v[180:183], v151 offset:16384
	ds_read_b128 v[184:187], v151 offset:17408
	ds_read_b128 v[208:211], v151 offset:18432
	ds_read_b128 v[230:233], v151 offset:19456
	ds_read_b128 v[234:237], v151 offset:20480
	ds_read_b128 v[238:241], v151 offset:21504
	ds_read_b128 v[242:245], v151 offset:22528
	ds_read_b128 v[246:249], v151 offset:23552
	global_load_lds_dwordx4 v112, s[28:29]
	s_add_i32 m0, s57, 0x2000
	s_add_u32 s58, s28, 0x40000
	v_lshl_add_u64 v[212:213], s[28:29], 0, v[134:135]
	s_addc_u32 s59, s29, 0
	s_add_i32 s57, s60, s39
	global_load_lds_dwordx4 v134, s[28:29]
	s_mov_b32 m0, s57
	v_lshl_add_u64 v[252:253], s[30:31], 0, v[132:133]
	global_load_lds_dwordx4 v112, s[58:59]
	s_add_i32 m0, s57, 0x2000
	s_nop 0
	global_load_lds_dwordx4 v134, s[58:59]
	v_lshl_add_u64 v[250:251], s[30:31], 0, v[130:131]
	s_mov_b32 m0, s21
	s_nop 0
	global_load_lds_dwordx4 v130, s[30:31]
	s_mov_b32 m0, s40
	s_nop 0
	global_load_lds_dwordx4 v132, s[30:31]
	s_waitcnt vmcnt(8)
	s_waitcnt lgkmcnt(0)
	s_barrier
	s_setprio 1
	s_waitcnt lgkmcnt(0)
	v_mfma_f32_16x16x32_bf16 v[60:63], v[142:145], v[180:183], v[60:63]
	v_mfma_f32_16x16x32_bf16 v[56:59], v[156:159], v[180:183], v[56:59]
	v_mfma_f32_16x16x32_bf16 v[44:47], v[142:145], v[208:211], v[44:47]
	v_mfma_f32_16x16x32_bf16 v[40:43], v[156:159], v[208:211], v[40:43]
	v_mfma_f32_16x16x32_bf16 v[28:31], v[142:145], v[234:237], v[28:31]
	v_mfma_f32_16x16x32_bf16 v[24:27], v[156:159], v[234:237], v[24:27]
	v_mfma_f32_16x16x32_bf16 v[12:15], v[142:145], v[242:245], v[12:15]
	v_mfma_f32_16x16x32_bf16 v[8:11], v[156:159], v[242:245], v[8:11]
	s_setprio 0
	s_setprio 1
	v_mfma_f32_16x16x32_bf16 v[60:63], v[152:155], v[184:187], v[60:63]
	v_mfma_f32_16x16x32_bf16 v[56:59], v[160:163], v[184:187], v[56:59]
	v_mfma_f32_16x16x32_bf16 v[44:47], v[152:155], v[230:233], v[44:47]
	v_mfma_f32_16x16x32_bf16 v[40:43], v[160:163], v[230:233], v[40:43]
	v_mfma_f32_16x16x32_bf16 v[28:31], v[152:155], v[238:241], v[28:31]
	v_mfma_f32_16x16x32_bf16 v[24:27], v[160:163], v[238:241], v[24:27]
	v_mfma_f32_16x16x32_bf16 v[12:15], v[152:155], v[246:249], v[12:15]
	v_mfma_f32_16x16x32_bf16 v[8:11], v[160:163], v[246:249], v[8:11]
	s_setprio 0
	s_setprio 1
	v_mfma_f32_16x16x32_bf16 v[52:55], v[164:167], v[180:183], v[52:55]
	v_mfma_f32_16x16x32_bf16 v[48:51], v[172:175], v[180:183], v[48:51]
	v_mfma_f32_16x16x32_bf16 v[36:39], v[164:167], v[208:211], v[36:39]
	v_mfma_f32_16x16x32_bf16 v[32:35], v[172:175], v[208:211], v[32:35]
	v_mfma_f32_16x16x32_bf16 v[20:23], v[164:167], v[234:237], v[20:23]
	v_mfma_f32_16x16x32_bf16 v[16:19], v[172:175], v[234:237], v[16:19]
	v_mfma_f32_16x16x32_bf16 v[4:7], v[164:167], v[242:245], v[4:7]
	v_mfma_f32_16x16x32_bf16 v[0:3], v[172:175], v[242:245], v[0:3]
	s_setprio 0
	s_setprio 1
	v_mfma_f32_16x16x32_bf16 v[52:55], v[168:171], v[184:187], v[52:55]
	v_mfma_f32_16x16x32_bf16 v[48:51], v[176:179], v[184:187], v[48:51]
	v_mfma_f32_16x16x32_bf16 v[36:39], v[168:171], v[230:233], v[36:39]
	v_mfma_f32_16x16x32_bf16 v[32:35], v[176:179], v[230:233], v[32:35]
	v_mfma_f32_16x16x32_bf16 v[20:23], v[168:171], v[238:241], v[20:23]
	v_mfma_f32_16x16x32_bf16 v[16:19], v[176:179], v[238:241], v[16:19]
	v_mfma_f32_16x16x32_bf16 v[4:7], v[168:171], v[246:249], v[4:7]
	v_mfma_f32_16x16x32_bf16 v[0:3], v[176:179], v[246:249], v[0:3]
	s_setprio 0
	s_barrier
	s_add_i32 s57, 0, 0x18000
	v_add_u32_e32 v146, s57, v148
	s_add_i32 s58, 0, 0x1c000
	ds_read_b128 v[142:145], v146
	ds_read_b128 v[152:155], v146 offset:1024
	ds_read_b128 v[156:159], v146 offset:2048
	ds_read_b128 v[160:163], v146 offset:3072
	v_add_u32_e32 v146, s58, v148
	ds_read_b128 v[164:167], v146
	ds_read_b128 v[168:171], v146 offset:1024
	ds_read_b128 v[172:175], v146 offset:2048
	ds_read_b128 v[176:179], v146 offset:3072
	s_add_u32 s30, s30, 0x40000
	s_addc_u32 s31, s31, 0
	s_mov_b32 m0, s41
	ds_read_b128 v[180:183], v151 offset:32768
	ds_read_b128 v[184:187], v151 offset:33792
	ds_read_b128 v[208:211], v151 offset:34816
	ds_read_b128 v[230:233], v151 offset:35840
	ds_read_b128 v[234:237], v151 offset:36864
	ds_read_b128 v[238:241], v151 offset:37888
	ds_read_b128 v[242:245], v151 offset:38912
	ds_read_b128 v[246:249], v151 offset:39936
	global_load_lds_dwordx4 v130, s[30:31]
	s_mov_b32 m0, s42
	s_nop 0
	global_load_lds_dwordx4 v132, s[30:31]
	s_waitcnt vmcnt(8)
	s_waitcnt lgkmcnt(0)
	s_barrier
	s_setprio 1
	s_waitcnt lgkmcnt(0)
	v_mfma_f32_16x16x32_bf16 v[126:129], v[142:145], v[180:183], v[126:129]
	v_mfma_f32_16x16x32_bf16 v[122:125], v[156:159], v[180:183], v[122:125]
	v_mfma_f32_16x16x32_bf16 v[108:111], v[142:145], v[208:211], v[108:111]
	v_mfma_f32_16x16x32_bf16 v[104:107], v[156:159], v[208:211], v[104:107]
	v_mfma_f32_16x16x32_bf16 v[92:95], v[142:145], v[234:237], v[92:95]
	v_mfma_f32_16x16x32_bf16 v[88:91], v[156:159], v[234:237], v[88:91]
	v_mfma_f32_16x16x32_bf16 v[76:79], v[142:145], v[242:245], v[76:79]
	v_mfma_f32_16x16x32_bf16 v[72:75], v[156:159], v[242:245], v[72:75]
	s_setprio 0
	s_setprio 1
	v_mfma_f32_16x16x32_bf16 v[126:129], v[152:155], v[184:187], v[126:129]
	v_mfma_f32_16x16x32_bf16 v[122:125], v[160:163], v[184:187], v[122:125]
	v_mfma_f32_16x16x32_bf16 v[108:111], v[152:155], v[230:233], v[108:111]
	v_mfma_f32_16x16x32_bf16 v[104:107], v[160:163], v[230:233], v[104:107]
	v_mfma_f32_16x16x32_bf16 v[92:95], v[152:155], v[238:241], v[92:95]
	v_mfma_f32_16x16x32_bf16 v[88:91], v[160:163], v[238:241], v[88:91]
	v_mfma_f32_16x16x32_bf16 v[76:79], v[152:155], v[246:249], v[76:79]
	v_mfma_f32_16x16x32_bf16 v[72:75], v[160:163], v[246:249], v[72:75]
	s_setprio 0
	s_setprio 1
	v_mfma_f32_16x16x32_bf16 v[118:121], v[164:167], v[180:183], v[118:121]
	v_mfma_f32_16x16x32_bf16 v[114:117], v[172:175], v[180:183], v[114:117]
	v_mfma_f32_16x16x32_bf16 v[100:103], v[164:167], v[208:211], v[100:103]
	v_mfma_f32_16x16x32_bf16 v[96:99], v[172:175], v[208:211], v[96:99]
	v_mfma_f32_16x16x32_bf16 v[84:87], v[164:167], v[234:237], v[84:87]
	v_mfma_f32_16x16x32_bf16 v[80:83], v[172:175], v[234:237], v[80:83]
	v_mfma_f32_16x16x32_bf16 v[68:71], v[164:167], v[242:245], v[68:71]
	v_mfma_f32_16x16x32_bf16 v[64:67], v[172:175], v[242:245], v[64:67]
	s_setprio 0
	s_setprio 1
	v_mfma_f32_16x16x32_bf16 v[118:121], v[168:171], v[184:187], v[118:121]
	v_mfma_f32_16x16x32_bf16 v[114:117], v[176:179], v[184:187], v[114:117]
	v_mfma_f32_16x16x32_bf16 v[100:103], v[168:171], v[230:233], v[100:103]
	v_mfma_f32_16x16x32_bf16 v[96:99], v[176:179], v[230:233], v[96:99]
	v_mfma_f32_16x16x32_bf16 v[84:87], v[168:171], v[238:241], v[84:87]
	v_mfma_f32_16x16x32_bf16 v[80:83], v[176:179], v[238:241], v[80:83]
	v_mfma_f32_16x16x32_bf16 v[68:71], v[168:171], v[246:249], v[68:71]
	v_mfma_f32_16x16x32_bf16 v[64:67], v[176:179], v[246:249], v[64:67]
	s_setprio 0
	s_barrier
	s_add_i32 s30, s57, s39
	s_mov_b32 m0, s30
	ds_read_b128 v[180:183], v151 offset:49152
	ds_read_b128 v[184:187], v151 offset:50176
	ds_read_b128 v[208:211], v151 offset:51200
	ds_read_b128 v[230:233], v151 offset:52224
	ds_read_b128 v[234:237], v151 offset:53248
	ds_read_b128 v[238:241], v151 offset:54272
	ds_read_b128 v[242:245], v151 offset:55296
	ds_read_b128 v[246:249], v151 offset:56320
	s_add_u32 s98, s28, 0x80
	s_addc_u32 s99, s29, 0
	global_load_lds_dwordx4 v112, s[98:99]
	s_add_i32 m0, s30, 0x2000
	s_add_u32 s28, s28, 0x40080
	v_lshl_add_u64 v[188:189], v[212:213], 0, s[96:97]
	s_addc_u32 s29, s29, 0
	s_add_i32 s30, s58, s39
	global_load_lds_dwordx4 v[188:189], off
	s_mov_b32 m0, s30
	s_nop 0
	global_load_lds_dwordx4 v112, s[28:29]
	s_add_i32 m0, s30, 0x2000
	s_nop 0
	global_load_lds_dwordx4 v134, s[28:29]
	v_lshl_add_u64 v[188:189], v[250:251], 0, s[96:97]
	s_mov_b32 m0, s43
	s_nop 0
	global_load_lds_dwordx4 v[188:189], off
	v_lshl_add_u64 v[188:189], v[252:253], 0, s[96:97]
	s_mov_b32 m0, s44
	s_nop 0
	global_load_lds_dwordx4 v[188:189], off
	s_waitcnt vmcnt(8)
	s_waitcnt lgkmcnt(0)
	s_barrier
	s_setprio 1
	s_waitcnt lgkmcnt(0)
	v_mfma_f32_16x16x32_bf16 v[60:63], v[142:145], v[180:183], v[60:63]
	v_mfma_f32_16x16x32_bf16 v[56:59], v[156:159], v[180:183], v[56:59]
	v_mfma_f32_16x16x32_bf16 v[44:47], v[142:145], v[208:211], v[44:47]
	v_mfma_f32_16x16x32_bf16 v[40:43], v[156:159], v[208:211], v[40:43]
	v_mfma_f32_16x16x32_bf16 v[28:31], v[142:145], v[234:237], v[28:31]
	v_mfma_f32_16x16x32_bf16 v[24:27], v[156:159], v[234:237], v[24:27]
	v_mfma_f32_16x16x32_bf16 v[12:15], v[142:145], v[242:245], v[12:15]
	v_mfma_f32_16x16x32_bf16 v[8:11], v[156:159], v[242:245], v[8:11]
	s_setprio 0
	s_setprio 1
	v_mfma_f32_16x16x32_bf16 v[60:63], v[152:155], v[184:187], v[60:63]
	v_mfma_f32_16x16x32_bf16 v[56:59], v[160:163], v[184:187], v[56:59]
	v_mfma_f32_16x16x32_bf16 v[44:47], v[152:155], v[230:233], v[44:47]
	v_mfma_f32_16x16x32_bf16 v[40:43], v[160:163], v[230:233], v[40:43]
	v_mfma_f32_16x16x32_bf16 v[28:31], v[152:155], v[238:241], v[28:31]
	v_mfma_f32_16x16x32_bf16 v[24:27], v[160:163], v[238:241], v[24:27]
	v_mfma_f32_16x16x32_bf16 v[12:15], v[152:155], v[246:249], v[12:15]
	v_mfma_f32_16x16x32_bf16 v[8:11], v[160:163], v[246:249], v[8:11]
	s_setprio 0
	s_setprio 1
	v_mfma_f32_16x16x32_bf16 v[52:55], v[164:167], v[180:183], v[52:55]
	v_mfma_f32_16x16x32_bf16 v[48:51], v[172:175], v[180:183], v[48:51]
	v_mfma_f32_16x16x32_bf16 v[36:39], v[164:167], v[208:211], v[36:39]
	v_mfma_f32_16x16x32_bf16 v[32:35], v[172:175], v[208:211], v[32:35]
	v_mfma_f32_16x16x32_bf16 v[20:23], v[164:167], v[234:237], v[20:23]
	v_mfma_f32_16x16x32_bf16 v[16:19], v[172:175], v[234:237], v[16:19]
	v_mfma_f32_16x16x32_bf16 v[4:7], v[164:167], v[242:245], v[4:7]
	v_mfma_f32_16x16x32_bf16 v[0:3], v[172:175], v[242:245], v[0:3]
	s_setprio 0
	s_setprio 1
	v_mfma_f32_16x16x32_bf16 v[52:55], v[168:171], v[184:187], v[52:55]
	v_mfma_f32_16x16x32_bf16 v[48:51], v[176:179], v[184:187], v[48:51]
	v_mfma_f32_16x16x32_bf16 v[36:39], v[168:171], v[230:233], v[36:39]
	v_mfma_f32_16x16x32_bf16 v[32:35], v[176:179], v[230:233], v[32:35]
	v_mfma_f32_16x16x32_bf16 v[20:23], v[168:171], v[238:241], v[20:23]
	v_mfma_f32_16x16x32_bf16 v[16:19], v[176:179], v[238:241], v[16:19]
	v_mfma_f32_16x16x32_bf16 v[4:7], v[168:171], v[246:249], v[4:7]
	v_mfma_f32_16x16x32_bf16 v[0:3], v[176:179], v[246:249], v[0:3]
	s_setprio 0
	s_barrier
	s_add_i32 s56, s56, 2
	s_add_u32 s54, s54, 0x100
	s_addc_u32 s55, s55, 0
	s_add_u32 s6, s6, 0x100
	s_addc_u32 s7, s7, 0
	s_cmp_gt_u32 s56, 13
	s_cbranch_scc0 .LBB0_2369
